# attention loop: the two 64-bit multiply-adds per iteration (K tile address) replaced by a scalar multiply and a 64-bit add
# speedup vs baseline: 1.0024x; 1.0024x over previous
.Lpeel_0:
	s_add_i32 s9, s3, -1
	s_min_u32 s9, s9, s2
	s_lshl_b32 s9, s9, 6
	s_waitcnt vmcnt(1)
	ds_write_b128 v142, v[112:115] offset:16384
	s_waitcnt vmcnt(0)
	ds_write_b128 v142, v[116:119] offset:24576
	s_mul_i32 s18, s9, 0x1200
	s_mov_b32 s19, 0
	v_lshl_add_u64 v[64:65], v[132:133], 0, s[18:19]
	global_load_dwordx4 v[120:123], v[64:65], off offset:2048
	global_load_dwordx4 v[124:127], v[136:137], off offset:-128
	ds_read_b128 v[64:67], v144 offset:8192
	ds_read_b128 v[68:71], v144 offset:12288
	ds_read_b128 v[72:75], v141 offset:8192
	ds_read_b128 v[76:79], v141 offset:12288
	v_exp_f32_e32 v151, v48
	v_exp_f32_e32 v152, v49
	s_waitcnt lgkmcnt(3)
	v_mfma_f32_32x32x16_bf16 v[16:31], v[64:67], v[80:83], v[16:31]
	v_exp_f32_e32 v153, v50
	v_exp_f32_e32 v154, v51
	ds_read_b128 v[48:51], v140 offset:8192
	ds_read_b128 v[64:67], v140 offset:12288
	v_exp_f32_e32 v155, v52
	s_waitcnt lgkmcnt(4)
	v_mfma_f32_32x32x16_bf16 v[0:15], v[68:71], v[80:83], v[0:15]
	v_exp_f32_e32 v156, v53
	v_exp_f32_e32 v159, v54
	v_exp_f32_e32 v160, v55
	v_exp_f32_e32 v162, v57
	s_waitcnt lgkmcnt(3)
	v_mfma_f32_32x32x16_bf16 v[16:31], v[72:75], v[84:87], v[16:31]
	ds_read_b128 v[68:71], v139 offset:8192
	ds_read_b128 v[80:83], v139 offset:12288
	v_add_f32_e32 v157, v155, v151
	v_add_f32_e32 v158, v156, v152
	ds_read_b128 v[52:55], v164
	ds_read_b128 v[72:75], v164 offset:4096
	v_add_f32_e32 v161, v159, v153
	s_waitcnt lgkmcnt(6)
	v_mfma_f32_32x32x16_bf16 v[0:15], v[76:79], v[84:87], v[0:15]
	v_exp_f32_e32 v77, v56
	v_add_f32_e32 v76, v160, v154
	v_exp_f32_e32 v62, v62
	ds_read_b128 v[112:115], v165
	ds_read_b128 v[116:119], v165 offset:4096
	v_cvt_pk_bf16_f32 v56, v151, v152
	s_waitcnt lgkmcnt(7)
	v_mfma_f32_32x32x16_bf16 v[16:31], v[48:51], v[88:91], v[16:31]
	v_exp_f32_e32 v49, v58
	v_exp_f32_e32 v50, v59
	v_add_f32_e32 v48, v77, v157
	v_add_f32_e32 v51, v162, v158
	v_add_f32_e32 v78, v49, v161
	v_add_f32_e32 v76, v50, v76
	s_waitcnt lgkmcnt(6)
	v_mfma_f32_32x32x16_bf16 v[0:15], v[64:67], v[88:91], v[0:15]
	v_exp_f32_e32 v60, v60
	v_add_f32_e32 v151, v62, v78
	v_exp_f32_e32 v61, v61
	v_exp_f32_e32 v63, v63
	v_cvt_pk_bf16_f32 v59, v159, v160
	v_exp_f32_e32 v160, v33
	s_waitcnt lgkmcnt(5)
	v_mfma_f32_32x32x16_bf16 v[16:31], v[68:71], v[92:95], v[16:31]
	v_cvt_pk_bf16_f32 v57, v153, v154
	v_cvt_pk_bf16_f32 v58, v155, v156
	v_add_f32_e32 v48, v60, v48
	v_add_f32_e32 v51, v61, v51
	v_cvt_pk_bf16_f32 v49, v49, v50
	s_waitcnt lgkmcnt(4)
	v_mfma_f32_32x32x16_bf16 v[0:15], v[80:83], v[92:95], v[0:15]
	v_readfirstlane_b32 s18, v171
	s_add_u32 m0, s18, 0x7600
	s_nop 0
	global_load_lds_dwordx4 v168, s[12:13] offset:2560
	v_exp_f32_e32 v95, v32
	v_add_f32_e32 v32, v63, v76
	v_add_f32_e32 v163, v160, v51
	v_add_f32_e32 v161, v95, v48
	v_cvt_pk_bf16_f32 v48, v77, v162
	v_cvt_pk_bf16_f32 v51, v62, v63
	s_waitcnt lgkmcnt(3)
	v_mfma_f32_32x32x16_bf16 v[78:93], v[52:55], v[96:99], 0
	v_cvt_pk_bf16_f32 v50, v60, v61
	v_exp_f32_e32 v60, v34
	v_exp_f32_e32 v61, v35
	v_exp_f32_e32 v36, v36
	v_exp_f32_e32 v37, v37
	v_exp_f32_e32 v38, v38
	v_exp_f32_e32 v39, v39
	s_waitcnt lgkmcnt(2)
	v_mfma_f32_32x32x16_bf16 v[62:77], v[72:75], v[96:99], 0
	ds_read_b128 v[52:55], v166
	ds_read_b128 v[152:155], v166 offset:4096
	v_add_f32_e32 v151, v60, v151
	v_add_f32_e32 v162, v61, v32
	s_waitcnt lgkmcnt(3)
	v_mfma_f32_32x32x16_bf16 v[78:93], v[112:115], v[100:103], v[78:93]
	v_add_f32_e32 v112, v36, v161
	v_add_f32_e32 v113, v37, v163
	v_add_f32_e32 v114, v38, v151
	v_exp_f32_e32 v115, v40
	v_add_f32_e32 v40, v39, v162
	ds_read_b128 v[32:35], v167
	ds_read_b128 v[156:159], v167 offset:4096
	s_waitcnt lgkmcnt(4)
	v_mfma_f32_32x32x16_bf16 v[62:77], v[116:119], v[100:103], v[62:77]
	v_exp_f32_e32 v116, v41
	v_add_f32_e32 v41, v115, v112
	s_min_u32 s9, s3, s2
	s_lshl_b32 s9, s9, 6
	v_add_f32_e32 v112, v116, v113
	s_waitcnt lgkmcnt(3)
	v_mfma_f32_32x32x16_bf16 v[78:93], v[52:55], v[104:107], v[78:93]
	v_cvt_pk_bf16_f32 v54, v36, v37
	v_exp_f32_e32 v37, v42
	v_cvt_pk_bf16_f32 v55, v38, v39
	v_exp_f32_e32 v38, v43
	v_exp_f32_e32 v39, v44
	v_exp_f32_e32 v44, v45
	v_exp_f32_e32 v45, v46
	v_exp_f32_e32 v46, v47
	v_cvt_pk_bf16_f32 v52, v95, v160
	v_cvt_pk_bf16_f32 v53, v60, v61
	v_add_f32_e32 v36, v37, v114
	v_add_f32_e32 v43, v38, v40
	v_add_f32_e32 v40, v39, v41
	v_add_f32_e32 v42, v44, v112
	v_add_f32_e32 v41, v45, v36
	v_add_f32_e32 v43, v46, v43
	v_cvt_pk_bf16_f32 v36, v115, v116
	v_cvt_pk_bf16_f32 v37, v37, v38
	v_cvt_pk_bf16_f32 v38, v39, v44
	v_cvt_pk_bf16_f32 v39, v45, v46
	s_waitcnt lgkmcnt(1)
	v_mfma_f32_32x32x16_bf16 v[78:93], v[32:35], v[108:111], v[78:93]
	s_waitcnt lgkmcnt(0)
	s_barrier
	s_mul_i32 s18, s9, 0x1200
	s_mov_b32 s19, 0
	v_lshl_add_u64 v[32:33], v[132:133], 0, s[18:19]
	global_load_dwordx4 v[112:115], v[32:33], off offset:2048
	global_load_dwordx4 v[116:119], v[136:137], off
	v_add_f32_e64 v32, v40, v42
	v_add_f32_e64 v33, v41, v43
	s_waitcnt vmcnt(4)
	ds_write_b128 v142, v[120:123]
	s_waitcnt vmcnt(3)
	ds_write_b128 v142, v[124:127] offset:8192
	v_mfma_f32_32x32x16_bf16 v[62:77], v[152:155], v[104:107], v[62:77]
	v_add_f32_e32 v32, v32, v33
	v_add_f32_e32 v150, v150, v32
	s_waitcnt lgkmcnt(2)
	v_mfma_f32_32x32x16_bf16 v[62:77], v[156:159], v[108:111], v[62:77]
	ds_read_b128 v[32:35], v144 offset:24576
	ds_read_b128 v[40:43], v144 offset:28672
	ds_read_b128 v[44:47], v141 offset:24576
	ds_read_b128 v[120:123], v141 offset:28672
	v_exp_f32_e32 v60, v78
	s_waitcnt lgkmcnt(3)
	v_mfma_f32_32x32x16_bf16 v[16:31], v[32:35], v[56:59], v[16:31]
	v_exp_f32_e32 v61, v79
	v_exp_f32_e32 v95, v80
	v_exp_f32_e32 v81, v81
	ds_read_b128 v[152:155], v140 offset:24576
	ds_read_b128 v[156:159], v140 offset:28672
	s_waitcnt lgkmcnt(4)
	v_mfma_f32_32x32x16_bf16 v[0:15], v[40:43], v[56:59], v[0:15]
	v_exp_f32_e32 v82, v82
	v_exp_f32_e32 v83, v83
	v_add_f32_e32 v78, v82, v60
	v_add_f32_e32 v79, v83, v61
	s_waitcnt lgkmcnt(2)
	v_mfma_f32_32x32x16_bf16 v[0:15], v[120:123], v[48:51], v[0:15]
	ds_read_b128 v[56:59], v139 offset:24576
	ds_read_b128 v[160:163], v139 offset:28672
	ds_read_b128 v[40:43], v164 offset:16384
	ds_read_b128 v[32:35], v164 offset:20480
	v_cvt_pk_bf16_f32 v82, v82, v83
	v_exp_f32_e32 v151, v62
	v_exp_f32_e32 v64, v64
	v_exp_f32_e32 v65, v65
	v_mfma_f32_32x32x16_bf16 v[16:31], v[44:47], v[48:51], v[16:31]
	v_exp_f32_e32 v44, v84
	v_exp_f32_e32 v45, v85
	v_exp_f32_e32 v84, v86
	v_exp_f32_e32 v85, v87
	v_add_f32_e32 v46, v44, v95
	v_add_f32_e32 v47, v45, v81
	v_add_f32_e32 v48, v84, v78
	s_waitcnt lgkmcnt(4)
	v_mfma_f32_32x32x16_bf16 v[0:15], v[156:159], v[52:55], v[0:15]
	v_add_f32_e32 v49, v85, v79
	v_exp_f32_e32 v78, v88
	v_exp_f32_e32 v79, v89
	v_exp_f32_e32 v87, v92
	v_cvt_pk_bf16_f32 v83, v44, v45
	v_exp_f32_e32 v44, v90
	v_mfma_f32_32x32x16_bf16 v[16:31], v[152:155], v[52:55], v[16:31]
	v_exp_f32_e32 v45, v91
	v_exp_f32_e32 v92, v93
	v_add_f32_e32 v46, v78, v46
	v_add_f32_e32 v47, v79, v47
	ds_read_b128 v[124:127], v165 offset:16384
	ds_read_b128 v[120:123], v165 offset:20480
	s_waitcnt lgkmcnt(4)
	v_mfma_f32_32x32x16_bf16 v[0:15], v[160:163], v[36:39], v[0:15]
	v_exp_f32_e32 v160, v63
	v_cvt_pk_bf16_f32 v80, v60, v61
	v_cvt_pk_bf16_f32 v81, v95, v81
	v_add_f32_e32 v48, v44, v48
	v_add_f32_e32 v49, v45, v49
	v_add_f32_e32 v46, v87, v46
	v_add_f32_e32 v47, v92, v47
	v_mfma_f32_32x32x16_bf16 v[16:31], v[56:59], v[36:39], v[16:31]
	v_add_f32_e32 v161, v151, v48
	v_add_f32_e32 v162, v160, v49
	v_cvt_pk_bf16_f32 v84, v84, v85
	v_cvt_pk_bf16_f32 v85, v78, v79
	v_cvt_pk_bf16_f32 v86, v44, v45
	v_add_f32_e32 v78, v64, v46
	v_add_f32_e32 v79, v65, v47
	s_waitcnt lgkmcnt(3)
	v_mfma_f32_32x32x16_bf16 v[48:63], v[40:43], v[96:99], 0
	ds_read_b128 v[88:91], v166 offset:16384
	ds_read_b128 v[152:155], v166 offset:20480
	v_exp_f32_e32 v66, v66
	v_exp_f32_e32 v67, v67
	v_exp_f32_e32 v68, v68
	v_exp_f32_e32 v69, v69
	v_cvt_pk_bf16_f32 v87, v87, v92
	s_waitcnt lgkmcnt(4)
	v_mfma_f32_32x32x16_bf16 v[32:47], v[32:35], v[96:99], 0
	ds_read_b128 v[156:159], v167 offset:16384
	ds_read_b128 v[92:95], v167 offset:20480
	v_add_f32_e32 v161, v66, v161
	v_add_f32_e32 v162, v67, v162
	v_add_f32_e32 v78, v68, v78
	v_add_f32_e32 v79, v69, v79
	s_waitcnt lgkmcnt(5)
	v_mfma_f32_32x32x16_bf16 v[48:63], v[124:127], v[100:103], v[48:63]
	v_exp_f32_e32 v70, v70
	v_exp_f32_e32 v71, v71
	s_add_i32 s9, s3, 2
	s_add_i32 s3, s3, -2
	v_lshl_add_u64 v[136:137], v[136:137], 0, s[22:23]
	s_waitcnt lgkmcnt(4)
	v_mfma_f32_32x32x16_bf16 v[32:47], v[120:123], v[100:103], v[32:47]
	v_add_f32_e32 v120, v70, v161
	v_add_f32_e32 v121, v71, v162
	s_cmp_lt_u32 s3, s2
	s_mov_b32 s3, s9
	s_waitcnt lgkmcnt(3)
	v_mfma_f32_32x32x16_bf16 v[48:63], v[88:91], v[104:107], v[48:63]
	v_cvt_pk_bf16_f32 v91, v68, v69
	v_exp_f32_e32 v68, v72
	v_exp_f32_e32 v69, v73
	v_exp_f32_e32 v72, v74
	v_exp_f32_e32 v73, v75
	v_exp_f32_e32 v74, v76
	v_exp_f32_e32 v75, v77
	s_waitcnt lgkmcnt(2)
	v_mfma_f32_32x32x16_bf16 v[32:47], v[152:155], v[104:107], v[32:47]
	v_cvt_pk_bf16_f32 v88, v151, v160
	v_cvt_pk_bf16_f32 v89, v64, v65
	v_cvt_pk_bf16_f32 v90, v66, v67
	v_add_f32_e32 v65, v68, v78
	v_add_f32_e32 v67, v69, v79
	s_waitcnt lgkmcnt(1)
	v_mfma_f32_32x32x16_bf16 v[48:63], v[156:159], v[108:111], v[48:63]
	v_add_f32_e32 v64, v72, v120
	v_add_f32_e32 v66, v73, v121
	v_add_f32_e32 v65, v74, v65
	v_add_f32_e32 v67, v75, v67
	s_waitcnt lgkmcnt(0)
	v_mfma_f32_32x32x16_bf16 v[32:47], v[92:95], v[108:111], v[32:47]
	v_cvt_pk_bf16_f32 v92, v70, v71
	v_cvt_pk_bf16_f32 v93, v68, v69
	v_cvt_pk_bf16_f32 v94, v72, v73
	v_cvt_pk_bf16_f32 v95, v74, v75
	v_add_f32_e64 v64, v64, v66
	v_add_f32_e64 v65, v65, v67
	s_waitcnt lgkmcnt(0)
	s_barrier
	v_add_f32_e32 v64, v64, v65
	v_add_f32_e32 v150, v150, v64
.Lpeel_1:
	s_add_i32 s9, s3, -1
	s_min_u32 s9, s9, s2
	s_lshl_b32 s9, s9, 6
	s_waitcnt vmcnt(1)
	ds_write_b128 v142, v[112:115] offset:16384
	s_waitcnt vmcnt(0)
	ds_write_b128 v142, v[116:119] offset:24576
	s_mul_i32 s18, s9, 0x1200
	s_mov_b32 s19, 0
	v_lshl_add_u64 v[64:65], v[132:133], 0, s[18:19]
	global_load_dwordx4 v[120:123], v[64:65], off offset:2048
	global_load_dwordx4 v[124:127], v[136:137], off offset:-128
	ds_read_b128 v[64:67], v144 offset:8192
	ds_read_b128 v[68:71], v144 offset:12288
	ds_read_b128 v[72:75], v141 offset:8192
	ds_read_b128 v[76:79], v141 offset:12288
	v_exp_f32_e32 v151, v48
	v_exp_f32_e32 v152, v49
	s_waitcnt lgkmcnt(3)
	v_mfma_f32_32x32x16_bf16 v[16:31], v[64:67], v[80:83], v[16:31]
	v_exp_f32_e32 v153, v50
	v_exp_f32_e32 v154, v51
	ds_read_b128 v[48:51], v140 offset:8192
	ds_read_b128 v[64:67], v140 offset:12288
	v_exp_f32_e32 v155, v52
	s_waitcnt lgkmcnt(4)
	v_mfma_f32_32x32x16_bf16 v[0:15], v[68:71], v[80:83], v[0:15]
	v_exp_f32_e32 v156, v53
	v_exp_f32_e32 v159, v54
	v_exp_f32_e32 v160, v55
	v_exp_f32_e32 v162, v57
	s_waitcnt lgkmcnt(3)
	v_mfma_f32_32x32x16_bf16 v[16:31], v[72:75], v[84:87], v[16:31]
	ds_read_b128 v[68:71], v139 offset:8192
	ds_read_b128 v[80:83], v139 offset:12288
	v_add_f32_e32 v157, v155, v151
	v_add_f32_e32 v158, v156, v152
	ds_read_b128 v[52:55], v164
	ds_read_b128 v[72:75], v164 offset:4096
	v_add_f32_e32 v161, v159, v153
	s_waitcnt lgkmcnt(6)
	v_mfma_f32_32x32x16_bf16 v[0:15], v[76:79], v[84:87], v[0:15]
	v_exp_f32_e32 v77, v56
	v_add_f32_e32 v76, v160, v154
	v_exp_f32_e32 v62, v62
	ds_read_b128 v[112:115], v165
	ds_read_b128 v[116:119], v165 offset:4096
	v_cvt_pk_bf16_f32 v56, v151, v152
	s_waitcnt lgkmcnt(7)
	v_mfma_f32_32x32x16_bf16 v[16:31], v[48:51], v[88:91], v[16:31]
	v_exp_f32_e32 v49, v58
	v_exp_f32_e32 v50, v59
	v_add_f32_e32 v48, v77, v157
	v_add_f32_e32 v51, v162, v158
	v_add_f32_e32 v78, v49, v161
	v_add_f32_e32 v76, v50, v76
	s_waitcnt lgkmcnt(6)
	v_mfma_f32_32x32x16_bf16 v[0:15], v[64:67], v[88:91], v[0:15]
	v_exp_f32_e32 v60, v60
	v_add_f32_e32 v151, v62, v78
	v_exp_f32_e32 v61, v61
	v_exp_f32_e32 v63, v63
	v_cvt_pk_bf16_f32 v59, v159, v160
	v_exp_f32_e32 v160, v33
	s_waitcnt lgkmcnt(5)
	v_mfma_f32_32x32x16_bf16 v[16:31], v[68:71], v[92:95], v[16:31]
	v_cvt_pk_bf16_f32 v57, v153, v154
	v_cvt_pk_bf16_f32 v58, v155, v156
	v_add_f32_e32 v48, v60, v48
	v_add_f32_e32 v51, v61, v51
	v_cvt_pk_bf16_f32 v49, v49, v50
	s_waitcnt lgkmcnt(4)
	v_mfma_f32_32x32x16_bf16 v[0:15], v[80:83], v[92:95], v[0:15]
	v_readfirstlane_b32 s18, v171
	s_add_u32 m0, s18, 0x95e0
	s_nop 0
	global_load_lds_dwordx4 v168, s[12:13] offset:2592
	v_exp_f32_e32 v95, v32
	v_add_f32_e32 v32, v63, v76
	v_add_f32_e32 v163, v160, v51
	v_add_f32_e32 v161, v95, v48
	v_cvt_pk_bf16_f32 v48, v77, v162
	v_cvt_pk_bf16_f32 v51, v62, v63
	s_waitcnt lgkmcnt(3)
	v_mfma_f32_32x32x16_bf16 v[78:93], v[52:55], v[96:99], 0
	v_cvt_pk_bf16_f32 v50, v60, v61
	v_exp_f32_e32 v60, v34
	v_exp_f32_e32 v61, v35
	v_exp_f32_e32 v36, v36
	v_exp_f32_e32 v37, v37
	v_exp_f32_e32 v38, v38
	v_exp_f32_e32 v39, v39
	s_waitcnt lgkmcnt(2)
	v_mfma_f32_32x32x16_bf16 v[62:77], v[72:75], v[96:99], 0
	ds_read_b128 v[52:55], v166
	ds_read_b128 v[152:155], v166 offset:4096
	v_add_f32_e32 v151, v60, v151
	v_add_f32_e32 v162, v61, v32
	s_waitcnt lgkmcnt(3)
	v_mfma_f32_32x32x16_bf16 v[78:93], v[112:115], v[100:103], v[78:93]
	v_add_f32_e32 v112, v36, v161
	v_add_f32_e32 v113, v37, v163
	v_add_f32_e32 v114, v38, v151
	v_exp_f32_e32 v115, v40
	v_add_f32_e32 v40, v39, v162
	ds_read_b128 v[32:35], v167
	ds_read_b128 v[156:159], v167 offset:4096
	s_waitcnt lgkmcnt(4)
	v_mfma_f32_32x32x16_bf16 v[62:77], v[116:119], v[100:103], v[62:77]
	v_exp_f32_e32 v116, v41
	v_add_f32_e32 v41, v115, v112
	s_min_u32 s9, s3, s2
	s_lshl_b32 s9, s9, 6
	v_add_f32_e32 v112, v116, v113
	s_waitcnt lgkmcnt(3)
	v_mfma_f32_32x32x16_bf16 v[78:93], v[52:55], v[104:107], v[78:93]
	v_cvt_pk_bf16_f32 v54, v36, v37
	v_exp_f32_e32 v37, v42
	v_cvt_pk_bf16_f32 v55, v38, v39
	v_exp_f32_e32 v38, v43
	v_exp_f32_e32 v39, v44
	v_exp_f32_e32 v44, v45
	v_exp_f32_e32 v45, v46
	v_exp_f32_e32 v46, v47
	v_cvt_pk_bf16_f32 v52, v95, v160
	v_cvt_pk_bf16_f32 v53, v60, v61
	v_add_f32_e32 v36, v37, v114
	v_add_f32_e32 v43, v38, v40
	v_add_f32_e32 v40, v39, v41
	v_add_f32_e32 v42, v44, v112
	v_add_f32_e32 v41, v45, v36
	v_add_f32_e32 v43, v46, v43
	v_cvt_pk_bf16_f32 v36, v115, v116
	v_cvt_pk_bf16_f32 v37, v37, v38
	v_cvt_pk_bf16_f32 v38, v39, v44
	v_cvt_pk_bf16_f32 v39, v45, v46
	s_waitcnt lgkmcnt(1)
	v_mfma_f32_32x32x16_bf16 v[78:93], v[32:35], v[108:111], v[78:93]
	s_waitcnt lgkmcnt(0)
	s_barrier
	s_mul_i32 s18, s9, 0x1200
	s_mov_b32 s19, 0
	v_lshl_add_u64 v[32:33], v[132:133], 0, s[18:19]
	global_load_dwordx4 v[112:115], v[32:33], off offset:2048
	global_load_dwordx4 v[116:119], v[136:137], off
	v_add_f32_e64 v32, v40, v42
	v_add_f32_e64 v33, v41, v43
	s_waitcnt vmcnt(4)
	ds_write_b128 v142, v[120:123]
	s_waitcnt vmcnt(3)
	ds_write_b128 v142, v[124:127] offset:8192
	v_mfma_f32_32x32x16_bf16 v[62:77], v[152:155], v[104:107], v[62:77]
	v_add_f32_e32 v32, v32, v33
	v_add_f32_e32 v150, v150, v32
	s_waitcnt lgkmcnt(2)
	v_mfma_f32_32x32x16_bf16 v[62:77], v[156:159], v[108:111], v[62:77]
	ds_read_b128 v[32:35], v144 offset:24576
	ds_read_b128 v[40:43], v144 offset:28672
	ds_read_b128 v[44:47], v141 offset:24576
	ds_read_b128 v[120:123], v141 offset:28672
	v_exp_f32_e32 v60, v78
	s_waitcnt lgkmcnt(3)
	v_mfma_f32_32x32x16_bf16 v[16:31], v[32:35], v[56:59], v[16:31]
	v_exp_f32_e32 v61, v79
	v_exp_f32_e32 v95, v80
	v_exp_f32_e32 v81, v81
	ds_read_b128 v[152:155], v140 offset:24576
	ds_read_b128 v[156:159], v140 offset:28672
	s_waitcnt lgkmcnt(4)
	v_mfma_f32_32x32x16_bf16 v[0:15], v[40:43], v[56:59], v[0:15]
	v_exp_f32_e32 v82, v82
	v_exp_f32_e32 v83, v83
	v_add_f32_e32 v78, v82, v60
	v_add_f32_e32 v79, v83, v61
	s_waitcnt lgkmcnt(2)
	v_mfma_f32_32x32x16_bf16 v[0:15], v[120:123], v[48:51], v[0:15]
	ds_read_b128 v[56:59], v139 offset:24576
	ds_read_b128 v[160:163], v139 offset:28672
	ds_read_b128 v[40:43], v164 offset:16384
	ds_read_b128 v[32:35], v164 offset:20480
	v_cvt_pk_bf16_f32 v82, v82, v83
	v_exp_f32_e32 v151, v62
	v_exp_f32_e32 v64, v64
	v_exp_f32_e32 v65, v65
	v_mfma_f32_32x32x16_bf16 v[16:31], v[44:47], v[48:51], v[16:31]
	v_exp_f32_e32 v44, v84
	v_exp_f32_e32 v45, v85
	v_exp_f32_e32 v84, v86
	v_exp_f32_e32 v85, v87
	v_add_f32_e32 v46, v44, v95
	v_add_f32_e32 v47, v45, v81
	v_add_f32_e32 v48, v84, v78
	s_waitcnt lgkmcnt(4)
	v_mfma_f32_32x32x16_bf16 v[0:15], v[156:159], v[52:55], v[0:15]
	v_add_f32_e32 v49, v85, v79
	v_exp_f32_e32 v78, v88
	v_exp_f32_e32 v79, v89
	v_exp_f32_e32 v87, v92
	v_cvt_pk_bf16_f32 v83, v44, v45
	v_exp_f32_e32 v44, v90
	v_mfma_f32_32x32x16_bf16 v[16:31], v[152:155], v[52:55], v[16:31]
	v_exp_f32_e32 v45, v91
	v_exp_f32_e32 v92, v93
	v_add_f32_e32 v46, v78, v46
	v_add_f32_e32 v47, v79, v47
	ds_read_b128 v[124:127], v165 offset:16384
	ds_read_b128 v[120:123], v165 offset:20480
	s_waitcnt lgkmcnt(4)
	v_mfma_f32_32x32x16_bf16 v[0:15], v[160:163], v[36:39], v[0:15]
	v_exp_f32_e32 v160, v63
	v_cvt_pk_bf16_f32 v80, v60, v61
	v_cvt_pk_bf16_f32 v81, v95, v81
	v_add_f32_e32 v48, v44, v48
	v_add_f32_e32 v49, v45, v49
	v_add_f32_e32 v46, v87, v46
	v_add_f32_e32 v47, v92, v47
	v_mfma_f32_32x32x16_bf16 v[16:31], v[56:59], v[36:39], v[16:31]
	v_add_f32_e32 v161, v151, v48
	v_add_f32_e32 v162, v160, v49
	v_cvt_pk_bf16_f32 v84, v84, v85
	v_cvt_pk_bf16_f32 v85, v78, v79
	v_cvt_pk_bf16_f32 v86, v44, v45
	v_add_f32_e32 v78, v64, v46
	v_add_f32_e32 v79, v65, v47
	s_waitcnt lgkmcnt(3)
	v_mfma_f32_32x32x16_bf16 v[48:63], v[40:43], v[96:99], 0
	ds_read_b128 v[88:91], v166 offset:16384
	ds_read_b128 v[152:155], v166 offset:20480
	v_exp_f32_e32 v66, v66
	v_exp_f32_e32 v67, v67
	v_exp_f32_e32 v68, v68
	v_exp_f32_e32 v69, v69
	v_cvt_pk_bf16_f32 v87, v87, v92
	s_waitcnt lgkmcnt(4)
	v_mfma_f32_32x32x16_bf16 v[32:47], v[32:35], v[96:99], 0
	ds_read_b128 v[156:159], v167 offset:16384
	ds_read_b128 v[92:95], v167 offset:20480
	v_add_f32_e32 v161, v66, v161
	v_add_f32_e32 v162, v67, v162
	v_add_f32_e32 v78, v68, v78
	v_add_f32_e32 v79, v69, v79
	s_waitcnt lgkmcnt(5)
	v_mfma_f32_32x32x16_bf16 v[48:63], v[124:127], v[100:103], v[48:63]
	v_exp_f32_e32 v70, v70
	v_exp_f32_e32 v71, v71
	s_add_i32 s9, s3, 2
	s_add_i32 s3, s3, -2
	v_lshl_add_u64 v[136:137], v[136:137], 0, s[22:23]
	s_waitcnt lgkmcnt(4)
	v_mfma_f32_32x32x16_bf16 v[32:47], v[120:123], v[100:103], v[32:47]
	v_add_f32_e32 v120, v70, v161
	v_add_f32_e32 v121, v71, v162
	s_cmp_lt_u32 s3, s2
	s_mov_b32 s3, s9
	s_waitcnt lgkmcnt(3)
	v_mfma_f32_32x32x16_bf16 v[48:63], v[88:91], v[104:107], v[48:63]
	v_cvt_pk_bf16_f32 v91, v68, v69
	v_exp_f32_e32 v68, v72
	v_exp_f32_e32 v69, v73
	v_exp_f32_e32 v72, v74
	v_exp_f32_e32 v73, v75
	v_exp_f32_e32 v74, v76
	v_exp_f32_e32 v75, v77
	s_waitcnt lgkmcnt(2)
	v_mfma_f32_32x32x16_bf16 v[32:47], v[152:155], v[104:107], v[32:47]
	v_cvt_pk_bf16_f32 v88, v151, v160
	v_cvt_pk_bf16_f32 v89, v64, v65
	v_cvt_pk_bf16_f32 v90, v66, v67
	v_add_f32_e32 v65, v68, v78
	v_add_f32_e32 v67, v69, v79
	s_waitcnt lgkmcnt(1)
	v_mfma_f32_32x32x16_bf16 v[48:63], v[156:159], v[108:111], v[48:63]
	v_add_f32_e32 v64, v72, v120
	v_add_f32_e32 v66, v73, v121
	v_add_f32_e32 v65, v74, v65
	v_add_f32_e32 v67, v75, v67
	s_waitcnt lgkmcnt(0)
	v_mfma_f32_32x32x16_bf16 v[32:47], v[92:95], v[108:111], v[32:47]
	v_cvt_pk_bf16_f32 v92, v70, v71
	v_cvt_pk_bf16_f32 v93, v68, v69
	v_cvt_pk_bf16_f32 v94, v72, v73
	v_cvt_pk_bf16_f32 v95, v74, v75
	v_add_f32_e64 v64, v64, v66
	v_add_f32_e64 v65, v65, v67
	s_waitcnt lgkmcnt(0)
	s_barrier
	v_add_f32_e32 v64, v64, v65
	v_add_f32_e32 v150, v150, v64
.Lpeel_2:
	s_add_i32 s9, s3, -1
	s_min_u32 s9, s9, s2
	s_lshl_b32 s9, s9, 6
	s_waitcnt vmcnt(1)
	ds_write_b128 v142, v[112:115] offset:16384
	s_waitcnt vmcnt(0)
	ds_write_b128 v142, v[116:119] offset:24576
	s_mul_i32 s18, s9, 0x1200
	s_mov_b32 s19, 0
	v_lshl_add_u64 v[64:65], v[132:133], 0, s[18:19]
	global_load_dwordx4 v[120:123], v[64:65], off offset:2048
	global_load_dwordx4 v[124:127], v[136:137], off offset:-128
	ds_read_b128 v[64:67], v144 offset:8192
	ds_read_b128 v[68:71], v144 offset:12288
	ds_read_b128 v[72:75], v141 offset:8192
	ds_read_b128 v[76:79], v141 offset:12288
	v_exp_f32_e32 v151, v48
	v_exp_f32_e32 v152, v49
	s_waitcnt lgkmcnt(3)
	v_mfma_f32_32x32x16_bf16 v[16:31], v[64:67], v[80:83], v[16:31]
	v_exp_f32_e32 v153, v50
	v_exp_f32_e32 v154, v51
	ds_read_b128 v[48:51], v140 offset:8192
	ds_read_b128 v[64:67], v140 offset:12288
	v_exp_f32_e32 v155, v52
	s_waitcnt lgkmcnt(4)
	v_mfma_f32_32x32x16_bf16 v[0:15], v[68:71], v[80:83], v[0:15]
	v_exp_f32_e32 v156, v53
	v_exp_f32_e32 v159, v54
	v_exp_f32_e32 v160, v55
	v_exp_f32_e32 v162, v57
	s_waitcnt lgkmcnt(3)
	v_mfma_f32_32x32x16_bf16 v[16:31], v[72:75], v[84:87], v[16:31]
	ds_read_b128 v[68:71], v139 offset:8192
	ds_read_b128 v[80:83], v139 offset:12288
	v_add_f32_e32 v157, v155, v151
	v_add_f32_e32 v158, v156, v152
	ds_read_b128 v[52:55], v164
	ds_read_b128 v[72:75], v164 offset:4096
	v_add_f32_e32 v161, v159, v153
	s_waitcnt lgkmcnt(6)
	v_mfma_f32_32x32x16_bf16 v[0:15], v[76:79], v[84:87], v[0:15]
	v_exp_f32_e32 v77, v56
	v_add_f32_e32 v76, v160, v154
	v_exp_f32_e32 v62, v62
	ds_read_b128 v[112:115], v165
	ds_read_b128 v[116:119], v165 offset:4096
	v_cvt_pk_bf16_f32 v56, v151, v152
	s_waitcnt lgkmcnt(7)
	v_mfma_f32_32x32x16_bf16 v[16:31], v[48:51], v[88:91], v[16:31]
	v_exp_f32_e32 v49, v58
	v_exp_f32_e32 v50, v59
	v_add_f32_e32 v48, v77, v157
	v_add_f32_e32 v51, v162, v158
	v_add_f32_e32 v78, v49, v161
	v_add_f32_e32 v76, v50, v76
	s_waitcnt lgkmcnt(6)
	v_mfma_f32_32x32x16_bf16 v[0:15], v[64:67], v[88:91], v[0:15]
	v_exp_f32_e32 v60, v60
	v_add_f32_e32 v151, v62, v78
	v_exp_f32_e32 v61, v61
	v_exp_f32_e32 v63, v63
	v_cvt_pk_bf16_f32 v59, v159, v160
	v_exp_f32_e32 v160, v33
	s_waitcnt lgkmcnt(5)
	v_mfma_f32_32x32x16_bf16 v[16:31], v[68:71], v[92:95], v[16:31]
	v_cvt_pk_bf16_f32 v57, v153, v154
	v_cvt_pk_bf16_f32 v58, v155, v156
	v_add_f32_e32 v48, v60, v48
	v_add_f32_e32 v51, v61, v51
	v_cvt_pk_bf16_f32 v49, v49, v50
	s_waitcnt lgkmcnt(4)
	v_mfma_f32_32x32x16_bf16 v[0:15], v[80:83], v[92:95], v[0:15]
	v_readfirstlane_b32 s18, v171
	s_add_u32 m0, s18, 0xb5c0
	s_nop 0
	global_load_lds_dwordx4 v168, s[12:13] offset:2624
	v_exp_f32_e32 v95, v32
	v_add_f32_e32 v32, v63, v76
	v_add_f32_e32 v163, v160, v51
	v_add_f32_e32 v161, v95, v48
	v_cvt_pk_bf16_f32 v48, v77, v162
	v_cvt_pk_bf16_f32 v51, v62, v63
	s_waitcnt lgkmcnt(3)
	v_mfma_f32_32x32x16_bf16 v[78:93], v[52:55], v[96:99], 0
	v_cvt_pk_bf16_f32 v50, v60, v61
	v_exp_f32_e32 v60, v34
	v_exp_f32_e32 v61, v35
	v_exp_f32_e32 v36, v36
	v_exp_f32_e32 v37, v37
	v_exp_f32_e32 v38, v38
	v_exp_f32_e32 v39, v39
	s_waitcnt lgkmcnt(2)
	v_mfma_f32_32x32x16_bf16 v[62:77], v[72:75], v[96:99], 0
	ds_read_b128 v[52:55], v166
	ds_read_b128 v[152:155], v166 offset:4096
	v_add_f32_e32 v151, v60, v151
	v_add_f32_e32 v162, v61, v32
	s_waitcnt lgkmcnt(3)
	v_mfma_f32_32x32x16_bf16 v[78:93], v[112:115], v[100:103], v[78:93]
	v_add_f32_e32 v112, v36, v161
	v_add_f32_e32 v113, v37, v163
	v_add_f32_e32 v114, v38, v151
	v_exp_f32_e32 v115, v40
	v_add_f32_e32 v40, v39, v162
	ds_read_b128 v[32:35], v167
	ds_read_b128 v[156:159], v167 offset:4096
	s_waitcnt lgkmcnt(4)
	v_mfma_f32_32x32x16_bf16 v[62:77], v[116:119], v[100:103], v[62:77]
	v_exp_f32_e32 v116, v41
	v_add_f32_e32 v41, v115, v112
	s_min_u32 s9, s3, s2
	s_lshl_b32 s9, s9, 6
	v_add_f32_e32 v112, v116, v113
	s_waitcnt lgkmcnt(3)
	v_mfma_f32_32x32x16_bf16 v[78:93], v[52:55], v[104:107], v[78:93]
	v_cvt_pk_bf16_f32 v54, v36, v37
	v_exp_f32_e32 v37, v42
	v_cvt_pk_bf16_f32 v55, v38, v39
	v_exp_f32_e32 v38, v43
	v_exp_f32_e32 v39, v44
	v_exp_f32_e32 v44, v45
	v_exp_f32_e32 v45, v46
	v_exp_f32_e32 v46, v47
	v_cvt_pk_bf16_f32 v52, v95, v160
	v_cvt_pk_bf16_f32 v53, v60, v61
	v_add_f32_e32 v36, v37, v114
	v_add_f32_e32 v43, v38, v40
	v_add_f32_e32 v40, v39, v41
	v_add_f32_e32 v42, v44, v112
	v_add_f32_e32 v41, v45, v36
	v_add_f32_e32 v43, v46, v43
	v_cvt_pk_bf16_f32 v36, v115, v116
	v_cvt_pk_bf16_f32 v37, v37, v38
	v_cvt_pk_bf16_f32 v38, v39, v44
	v_cvt_pk_bf16_f32 v39, v45, v46
	s_waitcnt lgkmcnt(1)
	v_mfma_f32_32x32x16_bf16 v[78:93], v[32:35], v[108:111], v[78:93]
	s_waitcnt lgkmcnt(0)
	s_barrier
	s_mul_i32 s18, s9, 0x1200
	s_mov_b32 s19, 0
	v_lshl_add_u64 v[32:33], v[132:133], 0, s[18:19]
	global_load_dwordx4 v[112:115], v[32:33], off offset:2048
	global_load_dwordx4 v[116:119], v[136:137], off
	v_add_f32_e64 v32, v40, v42
	v_add_f32_e64 v33, v41, v43
	s_waitcnt vmcnt(4)
	ds_write_b128 v142, v[120:123]
	s_waitcnt vmcnt(3)
	ds_write_b128 v142, v[124:127] offset:8192
	v_mfma_f32_32x32x16_bf16 v[62:77], v[152:155], v[104:107], v[62:77]
	v_add_f32_e32 v32, v32, v33
	v_add_f32_e32 v150, v150, v32
	s_waitcnt lgkmcnt(2)
	v_mfma_f32_32x32x16_bf16 v[62:77], v[156:159], v[108:111], v[62:77]
	ds_read_b128 v[32:35], v144 offset:24576
	ds_read_b128 v[40:43], v144 offset:28672
	ds_read_b128 v[44:47], v141 offset:24576
	ds_read_b128 v[120:123], v141 offset:28672
	v_exp_f32_e32 v60, v78
	s_waitcnt lgkmcnt(3)
	v_mfma_f32_32x32x16_bf16 v[16:31], v[32:35], v[56:59], v[16:31]
	v_exp_f32_e32 v61, v79
	v_exp_f32_e32 v95, v80
	v_exp_f32_e32 v81, v81
	ds_read_b128 v[152:155], v140 offset:24576
	ds_read_b128 v[156:159], v140 offset:28672
	s_waitcnt lgkmcnt(4)
	v_mfma_f32_32x32x16_bf16 v[0:15], v[40:43], v[56:59], v[0:15]
	v_exp_f32_e32 v82, v82
	v_exp_f32_e32 v83, v83
	v_add_f32_e32 v78, v82, v60
	v_add_f32_e32 v79, v83, v61
	s_waitcnt lgkmcnt(2)
	v_mfma_f32_32x32x16_bf16 v[0:15], v[120:123], v[48:51], v[0:15]
	ds_read_b128 v[56:59], v139 offset:24576
	ds_read_b128 v[160:163], v139 offset:28672
	ds_read_b128 v[40:43], v164 offset:16384
	ds_read_b128 v[32:35], v164 offset:20480
	v_cvt_pk_bf16_f32 v82, v82, v83
	v_exp_f32_e32 v151, v62
	v_exp_f32_e32 v64, v64
	v_exp_f32_e32 v65, v65
	v_mfma_f32_32x32x16_bf16 v[16:31], v[44:47], v[48:51], v[16:31]
	v_exp_f32_e32 v44, v84
	v_exp_f32_e32 v45, v85
	v_exp_f32_e32 v84, v86
	v_exp_f32_e32 v85, v87
	v_add_f32_e32 v46, v44, v95
	v_add_f32_e32 v47, v45, v81
	v_add_f32_e32 v48, v84, v78
	s_waitcnt lgkmcnt(4)
	v_mfma_f32_32x32x16_bf16 v[0:15], v[156:159], v[52:55], v[0:15]
	v_add_f32_e32 v49, v85, v79
	v_exp_f32_e32 v78, v88
	v_exp_f32_e32 v79, v89
	v_exp_f32_e32 v87, v92
	v_cvt_pk_bf16_f32 v83, v44, v45
	v_exp_f32_e32 v44, v90
	v_mfma_f32_32x32x16_bf16 v[16:31], v[152:155], v[52:55], v[16:31]
	v_exp_f32_e32 v45, v91
	v_exp_f32_e32 v92, v93
	v_add_f32_e32 v46, v78, v46
	v_add_f32_e32 v47, v79, v47
	ds_read_b128 v[124:127], v165 offset:16384
	ds_read_b128 v[120:123], v165 offset:20480
	s_waitcnt lgkmcnt(4)
	v_mfma_f32_32x32x16_bf16 v[0:15], v[160:163], v[36:39], v[0:15]
	v_exp_f32_e32 v160, v63
	v_cvt_pk_bf16_f32 v80, v60, v61
	v_cvt_pk_bf16_f32 v81, v95, v81
	v_add_f32_e32 v48, v44, v48
	v_add_f32_e32 v49, v45, v49
	v_add_f32_e32 v46, v87, v46
	v_add_f32_e32 v47, v92, v47
	v_mfma_f32_32x32x16_bf16 v[16:31], v[56:59], v[36:39], v[16:31]
	v_add_f32_e32 v161, v151, v48
	v_add_f32_e32 v162, v160, v49
	v_cvt_pk_bf16_f32 v84, v84, v85
	v_cvt_pk_bf16_f32 v85, v78, v79
	v_cvt_pk_bf16_f32 v86, v44, v45
	v_add_f32_e32 v78, v64, v46
	v_add_f32_e32 v79, v65, v47
	s_waitcnt lgkmcnt(3)
	v_mfma_f32_32x32x16_bf16 v[48:63], v[40:43], v[96:99], 0
	ds_read_b128 v[88:91], v166 offset:16384
	ds_read_b128 v[152:155], v166 offset:20480
	v_exp_f32_e32 v66, v66
	v_exp_f32_e32 v67, v67
	v_exp_f32_e32 v68, v68
	v_exp_f32_e32 v69, v69
	v_cvt_pk_bf16_f32 v87, v87, v92
	s_waitcnt lgkmcnt(4)
	v_mfma_f32_32x32x16_bf16 v[32:47], v[32:35], v[96:99], 0
	ds_read_b128 v[156:159], v167 offset:16384
	ds_read_b128 v[92:95], v167 offset:20480
	v_add_f32_e32 v161, v66, v161
	v_add_f32_e32 v162, v67, v162
	v_add_f32_e32 v78, v68, v78
	v_add_f32_e32 v79, v69, v79
	s_waitcnt lgkmcnt(5)
	v_mfma_f32_32x32x16_bf16 v[48:63], v[124:127], v[100:103], v[48:63]
	v_exp_f32_e32 v70, v70
	v_exp_f32_e32 v71, v71
	s_add_i32 s9, s3, 2
	s_add_i32 s3, s3, -2
	v_lshl_add_u64 v[136:137], v[136:137], 0, s[22:23]
	s_waitcnt lgkmcnt(4)
	v_mfma_f32_32x32x16_bf16 v[32:47], v[120:123], v[100:103], v[32:47]
	v_add_f32_e32 v120, v70, v161
	v_add_f32_e32 v121, v71, v162
	s_cmp_lt_u32 s3, s2
	s_mov_b32 s3, s9
	s_waitcnt lgkmcnt(3)
	v_mfma_f32_32x32x16_bf16 v[48:63], v[88:91], v[104:107], v[48:63]
	v_cvt_pk_bf16_f32 v91, v68, v69
	v_exp_f32_e32 v68, v72
	v_exp_f32_e32 v69, v73
	v_exp_f32_e32 v72, v74
	v_exp_f32_e32 v73, v75
	v_exp_f32_e32 v74, v76
	v_exp_f32_e32 v75, v77
	s_waitcnt lgkmcnt(2)
	v_mfma_f32_32x32x16_bf16 v[32:47], v[152:155], v[104:107], v[32:47]
	v_cvt_pk_bf16_f32 v88, v151, v160
	v_cvt_pk_bf16_f32 v89, v64, v65
	v_cvt_pk_bf16_f32 v90, v66, v67
	v_add_f32_e32 v65, v68, v78
	v_add_f32_e32 v67, v69, v79
	s_waitcnt lgkmcnt(1)
	v_mfma_f32_32x32x16_bf16 v[48:63], v[156:159], v[108:111], v[48:63]
	v_add_f32_e32 v64, v72, v120
	v_add_f32_e32 v66, v73, v121
	v_add_f32_e32 v65, v74, v65
	v_add_f32_e32 v67, v75, v67
	s_waitcnt lgkmcnt(0)
	v_mfma_f32_32x32x16_bf16 v[32:47], v[92:95], v[108:111], v[32:47]
	v_cvt_pk_bf16_f32 v92, v70, v71
	v_cvt_pk_bf16_f32 v93, v68, v69
	v_cvt_pk_bf16_f32 v94, v72, v73
	v_cvt_pk_bf16_f32 v95, v74, v75
	v_add_f32_e64 v64, v64, v66
	v_add_f32_e64 v65, v65, v67
	s_waitcnt lgkmcnt(0)
	s_barrier
	v_add_f32_e32 v64, v64, v65
	v_add_f32_e32 v150, v150, v64
.Lpeel_3:
	s_add_i32 s9, s3, -1
	s_min_u32 s9, s9, s2
	s_lshl_b32 s9, s9, 6
	s_waitcnt vmcnt(1)
	ds_write_b128 v142, v[112:115] offset:16384
	s_waitcnt vmcnt(0)
	ds_write_b128 v142, v[116:119] offset:24576
	s_mul_i32 s18, s9, 0x1200
	s_mov_b32 s19, 0
	v_lshl_add_u64 v[64:65], v[132:133], 0, s[18:19]
	global_load_dwordx4 v[120:123], v[64:65], off offset:2048
	global_load_dwordx4 v[124:127], v[136:137], off offset:-128
	ds_read_b128 v[64:67], v144 offset:8192
	ds_read_b128 v[68:71], v144 offset:12288
	ds_read_b128 v[72:75], v141 offset:8192
	ds_read_b128 v[76:79], v141 offset:12288
	v_exp_f32_e32 v151, v48
	v_exp_f32_e32 v152, v49
	s_waitcnt lgkmcnt(3)
	v_mfma_f32_32x32x16_bf16 v[16:31], v[64:67], v[80:83], v[16:31]
	v_exp_f32_e32 v153, v50
	v_exp_f32_e32 v154, v51
	ds_read_b128 v[48:51], v140 offset:8192
	ds_read_b128 v[64:67], v140 offset:12288
	v_exp_f32_e32 v155, v52
	s_waitcnt lgkmcnt(4)
	v_mfma_f32_32x32x16_bf16 v[0:15], v[68:71], v[80:83], v[0:15]
	v_exp_f32_e32 v156, v53
	v_exp_f32_e32 v159, v54
	v_exp_f32_e32 v160, v55
	v_exp_f32_e32 v162, v57
	s_waitcnt lgkmcnt(3)
	v_mfma_f32_32x32x16_bf16 v[16:31], v[72:75], v[84:87], v[16:31]
	ds_read_b128 v[68:71], v139 offset:8192
	ds_read_b128 v[80:83], v139 offset:12288
	v_add_f32_e32 v157, v155, v151
	v_add_f32_e32 v158, v156, v152
	ds_read_b128 v[52:55], v164
	ds_read_b128 v[72:75], v164 offset:4096
	v_add_f32_e32 v161, v159, v153
	s_waitcnt lgkmcnt(6)
	v_mfma_f32_32x32x16_bf16 v[0:15], v[76:79], v[84:87], v[0:15]
	v_exp_f32_e32 v77, v56
	v_add_f32_e32 v76, v160, v154
	v_exp_f32_e32 v62, v62
	ds_read_b128 v[112:115], v165
	ds_read_b128 v[116:119], v165 offset:4096
	v_cvt_pk_bf16_f32 v56, v151, v152
	s_waitcnt lgkmcnt(7)
	v_mfma_f32_32x32x16_bf16 v[16:31], v[48:51], v[88:91], v[16:31]
	v_exp_f32_e32 v49, v58
	v_exp_f32_e32 v50, v59
	v_add_f32_e32 v48, v77, v157
	v_add_f32_e32 v51, v162, v158
	v_add_f32_e32 v78, v49, v161
	v_add_f32_e32 v76, v50, v76
	s_waitcnt lgkmcnt(6)
	v_mfma_f32_32x32x16_bf16 v[0:15], v[64:67], v[88:91], v[0:15]
	v_exp_f32_e32 v60, v60
	v_add_f32_e32 v151, v62, v78
	v_exp_f32_e32 v61, v61
	v_exp_f32_e32 v63, v63
	v_cvt_pk_bf16_f32 v59, v159, v160
	v_exp_f32_e32 v160, v33
	s_waitcnt lgkmcnt(5)
	v_mfma_f32_32x32x16_bf16 v[16:31], v[68:71], v[92:95], v[16:31]
	v_cvt_pk_bf16_f32 v57, v153, v154
	v_cvt_pk_bf16_f32 v58, v155, v156
	v_add_f32_e32 v48, v60, v48
	v_add_f32_e32 v51, v61, v51
	v_cvt_pk_bf16_f32 v49, v49, v50
	s_waitcnt lgkmcnt(4)
	v_mfma_f32_32x32x16_bf16 v[0:15], v[80:83], v[92:95], v[0:15]
	v_readfirstlane_b32 s18, v171
	s_add_u32 m0, s18, 0xd5a0
	s_nop 0
	global_load_lds_dwordx4 v168, s[12:13] offset:2656
	v_exp_f32_e32 v95, v32
	v_add_f32_e32 v32, v63, v76
	v_add_f32_e32 v163, v160, v51
	v_add_f32_e32 v161, v95, v48
	v_cvt_pk_bf16_f32 v48, v77, v162
	v_cvt_pk_bf16_f32 v51, v62, v63
	s_waitcnt lgkmcnt(3)
	v_mfma_f32_32x32x16_bf16 v[78:93], v[52:55], v[96:99], 0
	v_cvt_pk_bf16_f32 v50, v60, v61
	v_exp_f32_e32 v60, v34
	v_exp_f32_e32 v61, v35
	v_exp_f32_e32 v36, v36
	v_exp_f32_e32 v37, v37
	v_exp_f32_e32 v38, v38
	v_exp_f32_e32 v39, v39
	s_waitcnt lgkmcnt(2)
	v_mfma_f32_32x32x16_bf16 v[62:77], v[72:75], v[96:99], 0
	ds_read_b128 v[52:55], v166
	ds_read_b128 v[152:155], v166 offset:4096
	v_add_f32_e32 v151, v60, v151
	v_add_f32_e32 v162, v61, v32
	s_waitcnt lgkmcnt(3)
	v_mfma_f32_32x32x16_bf16 v[78:93], v[112:115], v[100:103], v[78:93]
	v_add_f32_e32 v112, v36, v161
	v_add_f32_e32 v113, v37, v163
	v_add_f32_e32 v114, v38, v151
	v_exp_f32_e32 v115, v40
	v_add_f32_e32 v40, v39, v162
	ds_read_b128 v[32:35], v167
	ds_read_b128 v[156:159], v167 offset:4096
	s_waitcnt lgkmcnt(4)
	v_mfma_f32_32x32x16_bf16 v[62:77], v[116:119], v[100:103], v[62:77]
	v_exp_f32_e32 v116, v41
	v_add_f32_e32 v41, v115, v112
	s_min_u32 s9, s3, s2
	s_lshl_b32 s9, s9, 6
	v_add_f32_e32 v112, v116, v113
	s_waitcnt lgkmcnt(3)
	v_mfma_f32_32x32x16_bf16 v[78:93], v[52:55], v[104:107], v[78:93]
	v_cvt_pk_bf16_f32 v54, v36, v37
	v_exp_f32_e32 v37, v42
	v_cvt_pk_bf16_f32 v55, v38, v39
	v_exp_f32_e32 v38, v43
	v_exp_f32_e32 v39, v44
	v_exp_f32_e32 v44, v45
	v_exp_f32_e32 v45, v46
	v_exp_f32_e32 v46, v47
	v_cvt_pk_bf16_f32 v52, v95, v160
	v_cvt_pk_bf16_f32 v53, v60, v61
	v_add_f32_e32 v36, v37, v114
	v_add_f32_e32 v43, v38, v40
	v_add_f32_e32 v40, v39, v41
	v_add_f32_e32 v42, v44, v112
	v_add_f32_e32 v41, v45, v36
	v_add_f32_e32 v43, v46, v43
	v_cvt_pk_bf16_f32 v36, v115, v116
	v_cvt_pk_bf16_f32 v37, v37, v38
	v_cvt_pk_bf16_f32 v38, v39, v44
	v_cvt_pk_bf16_f32 v39, v45, v46
	s_waitcnt lgkmcnt(1)
	v_mfma_f32_32x32x16_bf16 v[78:93], v[32:35], v[108:111], v[78:93]
	s_waitcnt lgkmcnt(0)
	s_barrier
	s_mul_i32 s18, s9, 0x1200
	s_mov_b32 s19, 0
	v_lshl_add_u64 v[32:33], v[132:133], 0, s[18:19]
	global_load_dwordx4 v[112:115], v[32:33], off offset:2048
	global_load_dwordx4 v[116:119], v[136:137], off
	v_add_f32_e64 v32, v40, v42
	v_add_f32_e64 v33, v41, v43
	s_waitcnt vmcnt(4)
	ds_write_b128 v142, v[120:123]
	s_waitcnt vmcnt(3)
	ds_write_b128 v142, v[124:127] offset:8192
	v_mfma_f32_32x32x16_bf16 v[62:77], v[152:155], v[104:107], v[62:77]
	v_add_f32_e32 v32, v32, v33
	v_add_f32_e32 v150, v150, v32
	s_waitcnt lgkmcnt(2)
	v_mfma_f32_32x32x16_bf16 v[62:77], v[156:159], v[108:111], v[62:77]
	ds_read_b128 v[32:35], v144 offset:24576
	ds_read_b128 v[40:43], v144 offset:28672
	ds_read_b128 v[44:47], v141 offset:24576
	ds_read_b128 v[120:123], v141 offset:28672
	v_exp_f32_e32 v60, v78
	s_waitcnt lgkmcnt(3)
	v_mfma_f32_32x32x16_bf16 v[16:31], v[32:35], v[56:59], v[16:31]
	v_exp_f32_e32 v61, v79
	v_exp_f32_e32 v95, v80
	v_exp_f32_e32 v81, v81
	ds_read_b128 v[152:155], v140 offset:24576
	ds_read_b128 v[156:159], v140 offset:28672
	s_waitcnt lgkmcnt(4)
	v_mfma_f32_32x32x16_bf16 v[0:15], v[40:43], v[56:59], v[0:15]
	v_exp_f32_e32 v82, v82
	v_exp_f32_e32 v83, v83
	v_add_f32_e32 v78, v82, v60
	v_add_f32_e32 v79, v83, v61
	s_waitcnt lgkmcnt(2)
	v_mfma_f32_32x32x16_bf16 v[0:15], v[120:123], v[48:51], v[0:15]
	ds_read_b128 v[56:59], v139 offset:24576
	ds_read_b128 v[160:163], v139 offset:28672
	ds_read_b128 v[40:43], v164 offset:16384
	ds_read_b128 v[32:35], v164 offset:20480
	v_cvt_pk_bf16_f32 v82, v82, v83
	v_exp_f32_e32 v151, v62
	v_exp_f32_e32 v64, v64
	v_exp_f32_e32 v65, v65
	v_mfma_f32_32x32x16_bf16 v[16:31], v[44:47], v[48:51], v[16:31]
	v_exp_f32_e32 v44, v84
	v_exp_f32_e32 v45, v85
	v_exp_f32_e32 v84, v86
	v_exp_f32_e32 v85, v87
	v_add_f32_e32 v46, v44, v95
	v_add_f32_e32 v47, v45, v81
	v_add_f32_e32 v48, v84, v78
	s_waitcnt lgkmcnt(4)
	v_mfma_f32_32x32x16_bf16 v[0:15], v[156:159], v[52:55], v[0:15]
	v_add_f32_e32 v49, v85, v79
	v_exp_f32_e32 v78, v88
	v_exp_f32_e32 v79, v89
	v_exp_f32_e32 v87, v92
	v_cvt_pk_bf16_f32 v83, v44, v45
	v_exp_f32_e32 v44, v90
	v_mfma_f32_32x32x16_bf16 v[16:31], v[152:155], v[52:55], v[16:31]
	v_exp_f32_e32 v45, v91
	v_exp_f32_e32 v92, v93
	v_add_f32_e32 v46, v78, v46
	v_add_f32_e32 v47, v79, v47
	ds_read_b128 v[124:127], v165 offset:16384
	ds_read_b128 v[120:123], v165 offset:20480
	s_waitcnt lgkmcnt(4)
	v_mfma_f32_32x32x16_bf16 v[0:15], v[160:163], v[36:39], v[0:15]
	v_exp_f32_e32 v160, v63
	v_cvt_pk_bf16_f32 v80, v60, v61
	v_cvt_pk_bf16_f32 v81, v95, v81
	v_add_f32_e32 v48, v44, v48
	v_add_f32_e32 v49, v45, v49
	v_add_f32_e32 v46, v87, v46
	v_add_f32_e32 v47, v92, v47
	v_mfma_f32_32x32x16_bf16 v[16:31], v[56:59], v[36:39], v[16:31]
	v_add_f32_e32 v161, v151, v48
	v_add_f32_e32 v162, v160, v49
	v_cvt_pk_bf16_f32 v84, v84, v85
	v_cvt_pk_bf16_f32 v85, v78, v79
	v_cvt_pk_bf16_f32 v86, v44, v45
	v_add_f32_e32 v78, v64, v46
	v_add_f32_e32 v79, v65, v47
	s_waitcnt lgkmcnt(3)
	v_mfma_f32_32x32x16_bf16 v[48:63], v[40:43], v[96:99], 0
	ds_read_b128 v[88:91], v166 offset:16384
	ds_read_b128 v[152:155], v166 offset:20480
	v_exp_f32_e32 v66, v66
	v_exp_f32_e32 v67, v67
	v_exp_f32_e32 v68, v68
	v_exp_f32_e32 v69, v69
	v_cvt_pk_bf16_f32 v87, v87, v92
	s_waitcnt lgkmcnt(4)
	v_mfma_f32_32x32x16_bf16 v[32:47], v[32:35], v[96:99], 0
	ds_read_b128 v[156:159], v167 offset:16384
	ds_read_b128 v[92:95], v167 offset:20480
	v_add_f32_e32 v161, v66, v161
	v_add_f32_e32 v162, v67, v162
	v_add_f32_e32 v78, v68, v78
	v_add_f32_e32 v79, v69, v79
	s_waitcnt lgkmcnt(5)
	v_mfma_f32_32x32x16_bf16 v[48:63], v[124:127], v[100:103], v[48:63]
	v_exp_f32_e32 v70, v70
	v_exp_f32_e32 v71, v71
	s_add_i32 s9, s3, 2
	s_add_i32 s3, s3, -2
	v_lshl_add_u64 v[136:137], v[136:137], 0, s[22:23]
	s_waitcnt lgkmcnt(4)
	v_mfma_f32_32x32x16_bf16 v[32:47], v[120:123], v[100:103], v[32:47]
	v_add_f32_e32 v120, v70, v161
	v_add_f32_e32 v121, v71, v162
	s_cmp_lt_u32 s3, s2
	s_mov_b32 s3, s9
	s_waitcnt lgkmcnt(3)
	v_mfma_f32_32x32x16_bf16 v[48:63], v[88:91], v[104:107], v[48:63]
	v_cvt_pk_bf16_f32 v91, v68, v69
	v_exp_f32_e32 v68, v72
	v_exp_f32_e32 v69, v73
	v_exp_f32_e32 v72, v74
	v_exp_f32_e32 v73, v75
	v_exp_f32_e32 v74, v76
	v_exp_f32_e32 v75, v77
	s_waitcnt lgkmcnt(2)
	v_mfma_f32_32x32x16_bf16 v[32:47], v[152:155], v[104:107], v[32:47]
	v_cvt_pk_bf16_f32 v88, v151, v160
	v_cvt_pk_bf16_f32 v89, v64, v65
	v_cvt_pk_bf16_f32 v90, v66, v67
	v_add_f32_e32 v65, v68, v78
	v_add_f32_e32 v67, v69, v79
	s_waitcnt lgkmcnt(1)
	v_mfma_f32_32x32x16_bf16 v[48:63], v[156:159], v[108:111], v[48:63]
	v_add_f32_e32 v64, v72, v120
	v_add_f32_e32 v66, v73, v121
	v_add_f32_e32 v65, v74, v65
	v_add_f32_e32 v67, v75, v67
	s_waitcnt lgkmcnt(0)
	v_mfma_f32_32x32x16_bf16 v[32:47], v[92:95], v[108:111], v[32:47]
	v_cvt_pk_bf16_f32 v92, v70, v71
	v_cvt_pk_bf16_f32 v93, v68, v69
	v_cvt_pk_bf16_f32 v94, v72, v73
	v_cvt_pk_bf16_f32 v95, v74, v75
	v_add_f32_e64 v64, v64, v66
	v_add_f32_e64 v65, v65, v67
	s_waitcnt lgkmcnt(0)
	s_barrier
	v_add_f32_e32 v64, v64, v65
	v_add_f32_e32 v150, v150, v64
.Lpeel_4:
	s_add_i32 s9, s3, -1
	s_min_u32 s9, s9, s2
	s_lshl_b32 s9, s9, 6
	s_waitcnt vmcnt(1)
	ds_write_b128 v142, v[112:115] offset:16384
	s_waitcnt vmcnt(0)
	ds_write_b128 v142, v[116:119] offset:24576
	s_mul_i32 s18, s9, 0x1200
	s_mov_b32 s19, 0
	v_lshl_add_u64 v[64:65], v[132:133], 0, s[18:19]
	global_load_dwordx4 v[120:123], v[64:65], off offset:2048
	global_load_dwordx4 v[124:127], v[136:137], off offset:-128
	ds_read_b128 v[64:67], v144 offset:8192
	ds_read_b128 v[68:71], v144 offset:12288
	ds_read_b128 v[72:75], v141 offset:8192
	ds_read_b128 v[76:79], v141 offset:12288
	v_exp_f32_e32 v151, v48
	v_exp_f32_e32 v152, v49
	s_waitcnt lgkmcnt(3)
	v_mfma_f32_32x32x16_bf16 v[16:31], v[64:67], v[80:83], v[16:31]
	v_exp_f32_e32 v153, v50
	v_exp_f32_e32 v154, v51
	ds_read_b128 v[48:51], v140 offset:8192
	ds_read_b128 v[64:67], v140 offset:12288
	v_exp_f32_e32 v155, v52
	s_waitcnt lgkmcnt(4)
	v_mfma_f32_32x32x16_bf16 v[0:15], v[68:71], v[80:83], v[0:15]
	v_exp_f32_e32 v156, v53
	v_exp_f32_e32 v159, v54
	v_exp_f32_e32 v160, v55
	v_exp_f32_e32 v162, v57
	s_waitcnt lgkmcnt(3)
	v_mfma_f32_32x32x16_bf16 v[16:31], v[72:75], v[84:87], v[16:31]
	ds_read_b128 v[68:71], v139 offset:8192
	ds_read_b128 v[80:83], v139 offset:12288
	v_add_f32_e32 v157, v155, v151
	v_add_f32_e32 v158, v156, v152
	ds_read_b128 v[52:55], v164
	ds_read_b128 v[72:75], v164 offset:4096
	v_add_f32_e32 v161, v159, v153
	s_waitcnt lgkmcnt(6)
	v_mfma_f32_32x32x16_bf16 v[0:15], v[76:79], v[84:87], v[0:15]
	v_exp_f32_e32 v77, v56
	v_add_f32_e32 v76, v160, v154
	v_exp_f32_e32 v62, v62
	ds_read_b128 v[112:115], v165
	ds_read_b128 v[116:119], v165 offset:4096
	v_cvt_pk_bf16_f32 v56, v151, v152
	s_waitcnt lgkmcnt(7)
	v_mfma_f32_32x32x16_bf16 v[16:31], v[48:51], v[88:91], v[16:31]
	v_exp_f32_e32 v49, v58
	v_exp_f32_e32 v50, v59
	v_add_f32_e32 v48, v77, v157
	v_add_f32_e32 v51, v162, v158
	v_add_f32_e32 v78, v49, v161
	v_add_f32_e32 v76, v50, v76
	s_waitcnt lgkmcnt(6)
	v_mfma_f32_32x32x16_bf16 v[0:15], v[64:67], v[88:91], v[0:15]
	v_exp_f32_e32 v60, v60
	v_add_f32_e32 v151, v62, v78
	v_exp_f32_e32 v61, v61
	v_exp_f32_e32 v63, v63
	v_cvt_pk_bf16_f32 v59, v159, v160
	v_exp_f32_e32 v160, v33
	s_waitcnt lgkmcnt(5)
	v_mfma_f32_32x32x16_bf16 v[16:31], v[68:71], v[92:95], v[16:31]
	v_cvt_pk_bf16_f32 v57, v153, v154
	v_cvt_pk_bf16_f32 v58, v155, v156
	v_add_f32_e32 v48, v60, v48
	v_add_f32_e32 v51, v61, v51
	v_cvt_pk_bf16_f32 v49, v49, v50
	s_waitcnt lgkmcnt(4)
	v_mfma_f32_32x32x16_bf16 v[0:15], v[80:83], v[92:95], v[0:15]
	v_readfirstlane_b32 s18, v171
	s_add_u32 m0, s18, 0xfc00
	s_nop 0
	global_load_lds_dwordx4 v168, s[14:15] offset:1024
	v_exp_f32_e32 v95, v32
	v_add_f32_e32 v32, v63, v76
	v_add_f32_e32 v163, v160, v51
	v_add_f32_e32 v161, v95, v48
	v_cvt_pk_bf16_f32 v48, v77, v162
	v_cvt_pk_bf16_f32 v51, v62, v63
	s_waitcnt lgkmcnt(3)
	v_mfma_f32_32x32x16_bf16 v[78:93], v[52:55], v[96:99], 0
	v_cvt_pk_bf16_f32 v50, v60, v61
	v_exp_f32_e32 v60, v34
	v_exp_f32_e32 v61, v35
	v_exp_f32_e32 v36, v36
	v_exp_f32_e32 v37, v37
	v_exp_f32_e32 v38, v38
	v_exp_f32_e32 v39, v39
	s_waitcnt lgkmcnt(2)
	v_mfma_f32_32x32x16_bf16 v[62:77], v[72:75], v[96:99], 0
	ds_read_b128 v[52:55], v166
	ds_read_b128 v[152:155], v166 offset:4096
	v_add_f32_e32 v151, v60, v151
	v_add_f32_e32 v162, v61, v32
	s_waitcnt lgkmcnt(3)
	v_mfma_f32_32x32x16_bf16 v[78:93], v[112:115], v[100:103], v[78:93]
	v_add_f32_e32 v112, v36, v161
	v_add_f32_e32 v113, v37, v163
	v_add_f32_e32 v114, v38, v151
	v_exp_f32_e32 v115, v40
	v_add_f32_e32 v40, v39, v162
	ds_read_b128 v[32:35], v167
	ds_read_b128 v[156:159], v167 offset:4096
	s_waitcnt lgkmcnt(4)
	v_mfma_f32_32x32x16_bf16 v[62:77], v[116:119], v[100:103], v[62:77]
	v_exp_f32_e32 v116, v41
	v_add_f32_e32 v41, v115, v112
	s_min_u32 s9, s3, s2
	s_lshl_b32 s9, s9, 6
	v_add_f32_e32 v112, v116, v113
	s_waitcnt lgkmcnt(3)
	v_mfma_f32_32x32x16_bf16 v[78:93], v[52:55], v[104:107], v[78:93]
	v_cvt_pk_bf16_f32 v54, v36, v37
	v_exp_f32_e32 v37, v42
	v_cvt_pk_bf16_f32 v55, v38, v39
	v_exp_f32_e32 v38, v43
	v_exp_f32_e32 v39, v44
	v_exp_f32_e32 v44, v45
	v_exp_f32_e32 v45, v46
	v_exp_f32_e32 v46, v47
	v_cvt_pk_bf16_f32 v52, v95, v160
	v_cvt_pk_bf16_f32 v53, v60, v61
	v_add_f32_e32 v36, v37, v114
	v_add_f32_e32 v43, v38, v40
	v_add_f32_e32 v40, v39, v41
	v_add_f32_e32 v42, v44, v112
	v_add_f32_e32 v41, v45, v36
	v_add_f32_e32 v43, v46, v43
	v_cvt_pk_bf16_f32 v36, v115, v116
	v_cvt_pk_bf16_f32 v37, v37, v38
	v_cvt_pk_bf16_f32 v38, v39, v44
	v_cvt_pk_bf16_f32 v39, v45, v46
	s_waitcnt lgkmcnt(1)
	v_mfma_f32_32x32x16_bf16 v[78:93], v[32:35], v[108:111], v[78:93]
	s_waitcnt lgkmcnt(0)
	s_barrier
	s_mul_i32 s18, s9, 0x1200
	s_mov_b32 s19, 0
	v_lshl_add_u64 v[32:33], v[132:133], 0, s[18:19]
	global_load_dwordx4 v[112:115], v[32:33], off offset:2048
	global_load_dwordx4 v[116:119], v[136:137], off
	v_add_f32_e64 v32, v40, v42
	v_add_f32_e64 v33, v41, v43
	s_waitcnt vmcnt(4)
	ds_write_b128 v142, v[120:123]
	s_waitcnt vmcnt(3)
	ds_write_b128 v142, v[124:127] offset:8192
	v_mfma_f32_32x32x16_bf16 v[62:77], v[152:155], v[104:107], v[62:77]
	v_add_f32_e32 v32, v32, v33
	v_add_f32_e32 v150, v150, v32
	s_waitcnt lgkmcnt(2)
	v_mfma_f32_32x32x16_bf16 v[62:77], v[156:159], v[108:111], v[62:77]
	ds_read_b128 v[32:35], v144 offset:24576
	ds_read_b128 v[40:43], v144 offset:28672
	ds_read_b128 v[44:47], v141 offset:24576
	ds_read_b128 v[120:123], v141 offset:28672
	v_exp_f32_e32 v60, v78
	s_waitcnt lgkmcnt(3)
	v_mfma_f32_32x32x16_bf16 v[16:31], v[32:35], v[56:59], v[16:31]
	v_exp_f32_e32 v61, v79
	v_exp_f32_e32 v95, v80
	v_exp_f32_e32 v81, v81
	ds_read_b128 v[152:155], v140 offset:24576
	ds_read_b128 v[156:159], v140 offset:28672
	s_waitcnt lgkmcnt(4)
	v_mfma_f32_32x32x16_bf16 v[0:15], v[40:43], v[56:59], v[0:15]
	v_exp_f32_e32 v82, v82
	v_exp_f32_e32 v83, v83
	v_add_f32_e32 v78, v82, v60
	v_add_f32_e32 v79, v83, v61
	s_waitcnt lgkmcnt(2)
	v_mfma_f32_32x32x16_bf16 v[0:15], v[120:123], v[48:51], v[0:15]
	ds_read_b128 v[56:59], v139 offset:24576
	ds_read_b128 v[160:163], v139 offset:28672
	ds_read_b128 v[40:43], v164 offset:16384
	ds_read_b128 v[32:35], v164 offset:20480
	v_cvt_pk_bf16_f32 v82, v82, v83
	v_exp_f32_e32 v151, v62
	v_exp_f32_e32 v64, v64
	v_exp_f32_e32 v65, v65
	v_mfma_f32_32x32x16_bf16 v[16:31], v[44:47], v[48:51], v[16:31]
	v_exp_f32_e32 v44, v84
	v_exp_f32_e32 v45, v85
	v_exp_f32_e32 v84, v86
	v_exp_f32_e32 v85, v87
	v_add_f32_e32 v46, v44, v95
	v_add_f32_e32 v47, v45, v81
	v_add_f32_e32 v48, v84, v78
	s_waitcnt lgkmcnt(4)
	v_mfma_f32_32x32x16_bf16 v[0:15], v[156:159], v[52:55], v[0:15]
	v_add_f32_e32 v49, v85, v79
	v_exp_f32_e32 v78, v88
	v_exp_f32_e32 v79, v89
	v_exp_f32_e32 v87, v92
	v_cvt_pk_bf16_f32 v83, v44, v45
	v_exp_f32_e32 v44, v90
	v_mfma_f32_32x32x16_bf16 v[16:31], v[152:155], v[52:55], v[16:31]
	v_exp_f32_e32 v45, v91
	v_exp_f32_e32 v92, v93
	v_add_f32_e32 v46, v78, v46
	v_add_f32_e32 v47, v79, v47
	ds_read_b128 v[124:127], v165 offset:16384
	ds_read_b128 v[120:123], v165 offset:20480
	s_waitcnt lgkmcnt(4)
	v_mfma_f32_32x32x16_bf16 v[0:15], v[160:163], v[36:39], v[0:15]
	v_exp_f32_e32 v160, v63
	v_cvt_pk_bf16_f32 v80, v60, v61
	v_cvt_pk_bf16_f32 v81, v95, v81
	v_add_f32_e32 v48, v44, v48
	v_add_f32_e32 v49, v45, v49
	v_add_f32_e32 v46, v87, v46
	v_add_f32_e32 v47, v92, v47
	v_mfma_f32_32x32x16_bf16 v[16:31], v[56:59], v[36:39], v[16:31]
	v_add_f32_e32 v161, v151, v48
	v_add_f32_e32 v162, v160, v49
	v_cvt_pk_bf16_f32 v84, v84, v85
	v_cvt_pk_bf16_f32 v85, v78, v79
	v_cvt_pk_bf16_f32 v86, v44, v45
	v_add_f32_e32 v78, v64, v46
	v_add_f32_e32 v79, v65, v47
	s_waitcnt lgkmcnt(3)
	v_mfma_f32_32x32x16_bf16 v[48:63], v[40:43], v[96:99], 0
	ds_read_b128 v[88:91], v166 offset:16384
	ds_read_b128 v[152:155], v166 offset:20480
	v_exp_f32_e32 v66, v66
	v_exp_f32_e32 v67, v67
	v_exp_f32_e32 v68, v68
	v_exp_f32_e32 v69, v69
	v_cvt_pk_bf16_f32 v87, v87, v92
	s_waitcnt lgkmcnt(4)
	v_mfma_f32_32x32x16_bf16 v[32:47], v[32:35], v[96:99], 0
	ds_read_b128 v[156:159], v167 offset:16384
	ds_read_b128 v[92:95], v167 offset:20480
	v_add_f32_e32 v161, v66, v161
	v_add_f32_e32 v162, v67, v162
	v_add_f32_e32 v78, v68, v78
	v_add_f32_e32 v79, v69, v79
	s_waitcnt lgkmcnt(5)
	v_mfma_f32_32x32x16_bf16 v[48:63], v[124:127], v[100:103], v[48:63]
	v_exp_f32_e32 v70, v70
	v_exp_f32_e32 v71, v71
	s_add_i32 s9, s3, 2
	s_add_i32 s3, s3, -2
	v_lshl_add_u64 v[136:137], v[136:137], 0, s[22:23]
	s_waitcnt lgkmcnt(4)
	v_mfma_f32_32x32x16_bf16 v[32:47], v[120:123], v[100:103], v[32:47]
	v_add_f32_e32 v120, v70, v161
	v_add_f32_e32 v121, v71, v162
	s_cmp_lt_u32 s3, s2
	s_mov_b32 s3, s9
	s_waitcnt lgkmcnt(3)
	v_mfma_f32_32x32x16_bf16 v[48:63], v[88:91], v[104:107], v[48:63]
	v_cvt_pk_bf16_f32 v91, v68, v69
	v_exp_f32_e32 v68, v72
	v_exp_f32_e32 v69, v73
	v_exp_f32_e32 v72, v74
	v_exp_f32_e32 v73, v75
	v_exp_f32_e32 v74, v76
	v_exp_f32_e32 v75, v77
	s_waitcnt lgkmcnt(2)
	v_mfma_f32_32x32x16_bf16 v[32:47], v[152:155], v[104:107], v[32:47]
	v_cvt_pk_bf16_f32 v88, v151, v160
	v_cvt_pk_bf16_f32 v89, v64, v65
	v_cvt_pk_bf16_f32 v90, v66, v67
	v_add_f32_e32 v65, v68, v78
	v_add_f32_e32 v67, v69, v79
	s_waitcnt lgkmcnt(1)
	v_mfma_f32_32x32x16_bf16 v[48:63], v[156:159], v[108:111], v[48:63]
	v_add_f32_e32 v64, v72, v120
	v_add_f32_e32 v66, v73, v121
	v_add_f32_e32 v65, v74, v65
	v_add_f32_e32 v67, v75, v67
	s_waitcnt lgkmcnt(0)
	v_mfma_f32_32x32x16_bf16 v[32:47], v[92:95], v[108:111], v[32:47]
	v_cvt_pk_bf16_f32 v92, v70, v71
	v_cvt_pk_bf16_f32 v93, v68, v69
	v_cvt_pk_bf16_f32 v94, v72, v73
	v_cvt_pk_bf16_f32 v95, v74, v75
	v_add_f32_e64 v64, v64, v66
	v_add_f32_e64 v65, v65, v67
	s_waitcnt lgkmcnt(0)
	s_barrier
	v_add_f32_e32 v64, v64, v65
	v_add_f32_e32 v150, v150, v64
.Lpeel_5:
	s_add_i32 s9, s3, -1
	s_min_u32 s9, s9, s2
	s_lshl_b32 s9, s9, 6
	s_waitcnt vmcnt(1)
	ds_write_b128 v142, v[112:115] offset:16384
	s_waitcnt vmcnt(0)
	ds_write_b128 v142, v[116:119] offset:24576
	s_mul_i32 s18, s9, 0x1200
	s_mov_b32 s19, 0
	v_lshl_add_u64 v[64:65], v[132:133], 0, s[18:19]
	global_load_dwordx4 v[120:123], v[64:65], off offset:2048
	global_load_dwordx4 v[124:127], v[136:137], off offset:-128
	ds_read_b128 v[64:67], v144 offset:8192
	ds_read_b128 v[68:71], v144 offset:12288
	ds_read_b128 v[72:75], v141 offset:8192
	ds_read_b128 v[76:79], v141 offset:12288
	v_exp_f32_e32 v151, v48
	v_exp_f32_e32 v152, v49
	s_waitcnt lgkmcnt(3)
	v_mfma_f32_32x32x16_bf16 v[16:31], v[64:67], v[80:83], v[16:31]
	v_exp_f32_e32 v153, v50
	v_exp_f32_e32 v154, v51
	ds_read_b128 v[48:51], v140 offset:8192
	ds_read_b128 v[64:67], v140 offset:12288
	v_exp_f32_e32 v155, v52
	s_waitcnt lgkmcnt(4)
	v_mfma_f32_32x32x16_bf16 v[0:15], v[68:71], v[80:83], v[0:15]
	v_exp_f32_e32 v156, v53
	v_exp_f32_e32 v159, v54
	v_exp_f32_e32 v160, v55
	v_exp_f32_e32 v162, v57
	s_waitcnt lgkmcnt(3)
	v_mfma_f32_32x32x16_bf16 v[16:31], v[72:75], v[84:87], v[16:31]
	ds_read_b128 v[68:71], v139 offset:8192
	ds_read_b128 v[80:83], v139 offset:12288
	v_add_f32_e32 v157, v155, v151
	v_add_f32_e32 v158, v156, v152
	ds_read_b128 v[52:55], v164
	ds_read_b128 v[72:75], v164 offset:4096
	v_add_f32_e32 v161, v159, v153
	s_waitcnt lgkmcnt(6)
	v_mfma_f32_32x32x16_bf16 v[0:15], v[76:79], v[84:87], v[0:15]
	v_exp_f32_e32 v77, v56
	v_add_f32_e32 v76, v160, v154
	v_exp_f32_e32 v62, v62
	ds_read_b128 v[112:115], v165
	ds_read_b128 v[116:119], v165 offset:4096
	v_cvt_pk_bf16_f32 v56, v151, v152
	s_waitcnt lgkmcnt(7)
	v_mfma_f32_32x32x16_bf16 v[16:31], v[48:51], v[88:91], v[16:31]
	v_exp_f32_e32 v49, v58
	v_exp_f32_e32 v50, v59
	v_add_f32_e32 v48, v77, v157
	v_add_f32_e32 v51, v162, v158
	v_add_f32_e32 v78, v49, v161
	v_add_f32_e32 v76, v50, v76
	s_waitcnt lgkmcnt(6)
	v_mfma_f32_32x32x16_bf16 v[0:15], v[64:67], v[88:91], v[0:15]
	v_exp_f32_e32 v60, v60
	v_add_f32_e32 v151, v62, v78
	v_exp_f32_e32 v61, v61
	v_exp_f32_e32 v63, v63
	v_cvt_pk_bf16_f32 v59, v159, v160
	v_exp_f32_e32 v160, v33
	s_waitcnt lgkmcnt(5)
	v_mfma_f32_32x32x16_bf16 v[16:31], v[68:71], v[92:95], v[16:31]
	v_cvt_pk_bf16_f32 v57, v153, v154
	v_cvt_pk_bf16_f32 v58, v155, v156
	v_add_f32_e32 v48, v60, v48
	v_add_f32_e32 v51, v61, v51
	v_cvt_pk_bf16_f32 v49, v49, v50
	s_waitcnt lgkmcnt(4)
	v_mfma_f32_32x32x16_bf16 v[0:15], v[80:83], v[92:95], v[0:15]
	v_readfirstlane_b32 s18, v171
	s_add_u32 m0, s18, 0x11be0
	s_nop 0
	global_load_lds_dwordx4 v168, s[14:15] offset:1056
	v_exp_f32_e32 v95, v32
	v_add_f32_e32 v32, v63, v76
	v_add_f32_e32 v163, v160, v51
	v_add_f32_e32 v161, v95, v48
	v_cvt_pk_bf16_f32 v48, v77, v162
	v_cvt_pk_bf16_f32 v51, v62, v63
	s_waitcnt lgkmcnt(3)
	v_mfma_f32_32x32x16_bf16 v[78:93], v[52:55], v[96:99], 0
	v_cvt_pk_bf16_f32 v50, v60, v61
	v_exp_f32_e32 v60, v34
	v_exp_f32_e32 v61, v35
	v_exp_f32_e32 v36, v36
	v_exp_f32_e32 v37, v37
	v_exp_f32_e32 v38, v38
	v_exp_f32_e32 v39, v39
	s_waitcnt lgkmcnt(2)
	v_mfma_f32_32x32x16_bf16 v[62:77], v[72:75], v[96:99], 0
	ds_read_b128 v[52:55], v166
	ds_read_b128 v[152:155], v166 offset:4096
	v_add_f32_e32 v151, v60, v151
	v_add_f32_e32 v162, v61, v32
	s_waitcnt lgkmcnt(3)
	v_mfma_f32_32x32x16_bf16 v[78:93], v[112:115], v[100:103], v[78:93]
	v_add_f32_e32 v112, v36, v161
	v_add_f32_e32 v113, v37, v163
	v_add_f32_e32 v114, v38, v151
	v_exp_f32_e32 v115, v40
	v_add_f32_e32 v40, v39, v162
	ds_read_b128 v[32:35], v167
	ds_read_b128 v[156:159], v167 offset:4096
	s_waitcnt lgkmcnt(4)
	v_mfma_f32_32x32x16_bf16 v[62:77], v[116:119], v[100:103], v[62:77]
	v_exp_f32_e32 v116, v41
	v_add_f32_e32 v41, v115, v112
	s_min_u32 s9, s3, s2
	s_lshl_b32 s9, s9, 6
	v_add_f32_e32 v112, v116, v113
	s_waitcnt lgkmcnt(3)
	v_mfma_f32_32x32x16_bf16 v[78:93], v[52:55], v[104:107], v[78:93]
	v_cvt_pk_bf16_f32 v54, v36, v37
	v_exp_f32_e32 v37, v42
	v_cvt_pk_bf16_f32 v55, v38, v39
	v_exp_f32_e32 v38, v43
	v_exp_f32_e32 v39, v44
	v_exp_f32_e32 v44, v45
	v_exp_f32_e32 v45, v46
	v_exp_f32_e32 v46, v47
	v_cvt_pk_bf16_f32 v52, v95, v160
	v_cvt_pk_bf16_f32 v53, v60, v61
	v_add_f32_e32 v36, v37, v114
	v_add_f32_e32 v43, v38, v40
	v_add_f32_e32 v40, v39, v41
	v_add_f32_e32 v42, v44, v112
	v_add_f32_e32 v41, v45, v36
	v_add_f32_e32 v43, v46, v43
	v_cvt_pk_bf16_f32 v36, v115, v116
	v_cvt_pk_bf16_f32 v37, v37, v38
	v_cvt_pk_bf16_f32 v38, v39, v44
	v_cvt_pk_bf16_f32 v39, v45, v46
	s_waitcnt lgkmcnt(1)
	v_mfma_f32_32x32x16_bf16 v[78:93], v[32:35], v[108:111], v[78:93]
	s_waitcnt lgkmcnt(0)
	s_barrier
	s_mul_i32 s18, s9, 0x1200
	s_mov_b32 s19, 0
	v_lshl_add_u64 v[32:33], v[132:133], 0, s[18:19]
	global_load_dwordx4 v[112:115], v[32:33], off offset:2048
	global_load_dwordx4 v[116:119], v[136:137], off
	v_add_f32_e64 v32, v40, v42
	v_add_f32_e64 v33, v41, v43
	s_waitcnt vmcnt(4)
	ds_write_b128 v142, v[120:123]
	s_waitcnt vmcnt(3)
	ds_write_b128 v142, v[124:127] offset:8192
	v_mfma_f32_32x32x16_bf16 v[62:77], v[152:155], v[104:107], v[62:77]
	v_add_f32_e32 v32, v32, v33
	v_add_f32_e32 v150, v150, v32
	s_waitcnt lgkmcnt(2)
	v_mfma_f32_32x32x16_bf16 v[62:77], v[156:159], v[108:111], v[62:77]
	ds_read_b128 v[32:35], v144 offset:24576
	ds_read_b128 v[40:43], v144 offset:28672
	ds_read_b128 v[44:47], v141 offset:24576
	ds_read_b128 v[120:123], v141 offset:28672
	v_exp_f32_e32 v60, v78
	s_waitcnt lgkmcnt(3)
	v_mfma_f32_32x32x16_bf16 v[16:31], v[32:35], v[56:59], v[16:31]
	v_exp_f32_e32 v61, v79
	v_exp_f32_e32 v95, v80
	v_exp_f32_e32 v81, v81
	ds_read_b128 v[152:155], v140 offset:24576
	ds_read_b128 v[156:159], v140 offset:28672
	s_waitcnt lgkmcnt(4)
	v_mfma_f32_32x32x16_bf16 v[0:15], v[40:43], v[56:59], v[0:15]
	v_exp_f32_e32 v82, v82
	v_exp_f32_e32 v83, v83
	v_add_f32_e32 v78, v82, v60
	v_add_f32_e32 v79, v83, v61
	s_waitcnt lgkmcnt(2)
	v_mfma_f32_32x32x16_bf16 v[0:15], v[120:123], v[48:51], v[0:15]
	ds_read_b128 v[56:59], v139 offset:24576
	ds_read_b128 v[160:163], v139 offset:28672
	ds_read_b128 v[40:43], v164 offset:16384
	ds_read_b128 v[32:35], v164 offset:20480
	v_cvt_pk_bf16_f32 v82, v82, v83
	v_exp_f32_e32 v151, v62
	v_exp_f32_e32 v64, v64
	v_exp_f32_e32 v65, v65
	v_mfma_f32_32x32x16_bf16 v[16:31], v[44:47], v[48:51], v[16:31]
	v_exp_f32_e32 v44, v84
	v_exp_f32_e32 v45, v85
	v_exp_f32_e32 v84, v86
	v_exp_f32_e32 v85, v87
	v_add_f32_e32 v46, v44, v95
	v_add_f32_e32 v47, v45, v81
	v_add_f32_e32 v48, v84, v78
	s_waitcnt lgkmcnt(4)
	v_mfma_f32_32x32x16_bf16 v[0:15], v[156:159], v[52:55], v[0:15]
	v_add_f32_e32 v49, v85, v79
	v_exp_f32_e32 v78, v88
	v_exp_f32_e32 v79, v89
	v_exp_f32_e32 v87, v92
	v_cvt_pk_bf16_f32 v83, v44, v45
	v_exp_f32_e32 v44, v90
	v_mfma_f32_32x32x16_bf16 v[16:31], v[152:155], v[52:55], v[16:31]
	v_exp_f32_e32 v45, v91
	v_exp_f32_e32 v92, v93
	v_add_f32_e32 v46, v78, v46
	v_add_f32_e32 v47, v79, v47
	ds_read_b128 v[124:127], v165 offset:16384
	ds_read_b128 v[120:123], v165 offset:20480
	s_waitcnt lgkmcnt(4)
	v_mfma_f32_32x32x16_bf16 v[0:15], v[160:163], v[36:39], v[0:15]
	v_exp_f32_e32 v160, v63
	v_cvt_pk_bf16_f32 v80, v60, v61
	v_cvt_pk_bf16_f32 v81, v95, v81
	v_add_f32_e32 v48, v44, v48
	v_add_f32_e32 v49, v45, v49
	v_add_f32_e32 v46, v87, v46
	v_add_f32_e32 v47, v92, v47
	v_mfma_f32_32x32x16_bf16 v[16:31], v[56:59], v[36:39], v[16:31]
	v_add_f32_e32 v161, v151, v48
	v_add_f32_e32 v162, v160, v49
	v_cvt_pk_bf16_f32 v84, v84, v85
	v_cvt_pk_bf16_f32 v85, v78, v79
	v_cvt_pk_bf16_f32 v86, v44, v45
	v_add_f32_e32 v78, v64, v46
	v_add_f32_e32 v79, v65, v47
	s_waitcnt lgkmcnt(3)
	v_mfma_f32_32x32x16_bf16 v[48:63], v[40:43], v[96:99], 0
	ds_read_b128 v[88:91], v166 offset:16384
	ds_read_b128 v[152:155], v166 offset:20480
	v_exp_f32_e32 v66, v66
	v_exp_f32_e32 v67, v67
	v_exp_f32_e32 v68, v68
	v_exp_f32_e32 v69, v69
	v_cvt_pk_bf16_f32 v87, v87, v92
	s_waitcnt lgkmcnt(4)
	v_mfma_f32_32x32x16_bf16 v[32:47], v[32:35], v[96:99], 0
	ds_read_b128 v[156:159], v167 offset:16384
	ds_read_b128 v[92:95], v167 offset:20480
	v_add_f32_e32 v161, v66, v161
	v_add_f32_e32 v162, v67, v162
	v_add_f32_e32 v78, v68, v78
	v_add_f32_e32 v79, v69, v79
	s_waitcnt lgkmcnt(5)
	v_mfma_f32_32x32x16_bf16 v[48:63], v[124:127], v[100:103], v[48:63]
	v_exp_f32_e32 v70, v70
	v_exp_f32_e32 v71, v71
	s_add_i32 s9, s3, 2
	s_add_i32 s3, s3, -2
	v_lshl_add_u64 v[136:137], v[136:137], 0, s[22:23]
	s_waitcnt lgkmcnt(4)
	v_mfma_f32_32x32x16_bf16 v[32:47], v[120:123], v[100:103], v[32:47]
	v_add_f32_e32 v120, v70, v161
	v_add_f32_e32 v121, v71, v162
	s_cmp_lt_u32 s3, s2
	s_mov_b32 s3, s9
	s_waitcnt lgkmcnt(3)
	v_mfma_f32_32x32x16_bf16 v[48:63], v[88:91], v[104:107], v[48:63]
	v_cvt_pk_bf16_f32 v91, v68, v69
	v_exp_f32_e32 v68, v72
	v_exp_f32_e32 v69, v73
	v_exp_f32_e32 v72, v74
	v_exp_f32_e32 v73, v75
	v_exp_f32_e32 v74, v76
	v_exp_f32_e32 v75, v77
	s_waitcnt lgkmcnt(2)
	v_mfma_f32_32x32x16_bf16 v[32:47], v[152:155], v[104:107], v[32:47]
	v_cvt_pk_bf16_f32 v88, v151, v160
	v_cvt_pk_bf16_f32 v89, v64, v65
	v_cvt_pk_bf16_f32 v90, v66, v67
	v_add_f32_e32 v65, v68, v78
	v_add_f32_e32 v67, v69, v79
	s_waitcnt lgkmcnt(1)
	v_mfma_f32_32x32x16_bf16 v[48:63], v[156:159], v[108:111], v[48:63]
	v_add_f32_e32 v64, v72, v120
	v_add_f32_e32 v66, v73, v121
	v_add_f32_e32 v65, v74, v65
	v_add_f32_e32 v67, v75, v67
	s_waitcnt lgkmcnt(0)
	v_mfma_f32_32x32x16_bf16 v[32:47], v[92:95], v[108:111], v[32:47]
	v_cvt_pk_bf16_f32 v92, v70, v71
	v_cvt_pk_bf16_f32 v93, v68, v69
	v_cvt_pk_bf16_f32 v94, v72, v73
	v_cvt_pk_bf16_f32 v95, v74, v75
	v_add_f32_e64 v64, v64, v66
	v_add_f32_e64 v65, v65, v67
	s_waitcnt lgkmcnt(0)
	s_barrier
	v_add_f32_e32 v64, v64, v65
	v_add_f32_e32 v150, v150, v64
.Lpeel_6:
	s_add_i32 s9, s3, -1
	s_min_u32 s9, s9, s2
	s_lshl_b32 s9, s9, 6
	s_waitcnt vmcnt(1)
	ds_write_b128 v142, v[112:115] offset:16384
	s_waitcnt vmcnt(0)
	ds_write_b128 v142, v[116:119] offset:24576
	s_mul_i32 s18, s9, 0x1200
	s_mov_b32 s19, 0
	v_lshl_add_u64 v[64:65], v[132:133], 0, s[18:19]
	global_load_dwordx4 v[120:123], v[64:65], off offset:2048
	global_load_dwordx4 v[124:127], v[136:137], off offset:-128
	ds_read_b128 v[64:67], v144 offset:8192
	ds_read_b128 v[68:71], v144 offset:12288
	ds_read_b128 v[72:75], v141 offset:8192
	ds_read_b128 v[76:79], v141 offset:12288
	v_exp_f32_e32 v151, v48
	v_exp_f32_e32 v152, v49
	s_waitcnt lgkmcnt(3)
	v_mfma_f32_32x32x16_bf16 v[16:31], v[64:67], v[80:83], v[16:31]
	v_exp_f32_e32 v153, v50
	v_exp_f32_e32 v154, v51
	ds_read_b128 v[48:51], v140 offset:8192
	ds_read_b128 v[64:67], v140 offset:12288
	v_exp_f32_e32 v155, v52
	s_waitcnt lgkmcnt(4)
	v_mfma_f32_32x32x16_bf16 v[0:15], v[68:71], v[80:83], v[0:15]
	v_exp_f32_e32 v156, v53
	v_exp_f32_e32 v159, v54
	v_exp_f32_e32 v160, v55
	v_exp_f32_e32 v162, v57
	s_waitcnt lgkmcnt(3)
	v_mfma_f32_32x32x16_bf16 v[16:31], v[72:75], v[84:87], v[16:31]
	ds_read_b128 v[68:71], v139 offset:8192
	ds_read_b128 v[80:83], v139 offset:12288
	v_add_f32_e32 v157, v155, v151
	v_add_f32_e32 v158, v156, v152
	ds_read_b128 v[52:55], v164
	ds_read_b128 v[72:75], v164 offset:4096
	v_add_f32_e32 v161, v159, v153
	s_waitcnt lgkmcnt(6)
	v_mfma_f32_32x32x16_bf16 v[0:15], v[76:79], v[84:87], v[0:15]
	v_exp_f32_e32 v77, v56
	v_add_f32_e32 v76, v160, v154
	v_exp_f32_e32 v62, v62
	ds_read_b128 v[112:115], v165
	ds_read_b128 v[116:119], v165 offset:4096
	v_cvt_pk_bf16_f32 v56, v151, v152
	s_waitcnt lgkmcnt(7)
	v_mfma_f32_32x32x16_bf16 v[16:31], v[48:51], v[88:91], v[16:31]
	v_exp_f32_e32 v49, v58
	v_exp_f32_e32 v50, v59
	v_add_f32_e32 v48, v77, v157
	v_add_f32_e32 v51, v162, v158
	v_add_f32_e32 v78, v49, v161
	v_add_f32_e32 v76, v50, v76
	s_waitcnt lgkmcnt(6)
	v_mfma_f32_32x32x16_bf16 v[0:15], v[64:67], v[88:91], v[0:15]
	v_exp_f32_e32 v60, v60
	v_add_f32_e32 v151, v62, v78
	v_exp_f32_e32 v61, v61
	v_exp_f32_e32 v63, v63
	v_cvt_pk_bf16_f32 v59, v159, v160
	v_exp_f32_e32 v160, v33
	s_waitcnt lgkmcnt(5)
	v_mfma_f32_32x32x16_bf16 v[16:31], v[68:71], v[92:95], v[16:31]
	v_cvt_pk_bf16_f32 v57, v153, v154
	v_cvt_pk_bf16_f32 v58, v155, v156
	v_add_f32_e32 v48, v60, v48
	v_add_f32_e32 v51, v61, v51
	v_cvt_pk_bf16_f32 v49, v49, v50
	s_waitcnt lgkmcnt(4)
	v_mfma_f32_32x32x16_bf16 v[0:15], v[80:83], v[92:95], v[0:15]
	v_readfirstlane_b32 s18, v171
	s_add_u32 m0, s18, 0x13bc0
	s_nop 0
	global_load_lds_dwordx4 v168, s[14:15] offset:1088
	v_exp_f32_e32 v95, v32
	v_add_f32_e32 v32, v63, v76
	v_add_f32_e32 v163, v160, v51
	v_add_f32_e32 v161, v95, v48
	v_cvt_pk_bf16_f32 v48, v77, v162
	v_cvt_pk_bf16_f32 v51, v62, v63
	s_waitcnt lgkmcnt(3)
	v_mfma_f32_32x32x16_bf16 v[78:93], v[52:55], v[96:99], 0
	v_cvt_pk_bf16_f32 v50, v60, v61
	v_exp_f32_e32 v60, v34
	v_exp_f32_e32 v61, v35
	v_exp_f32_e32 v36, v36
	v_exp_f32_e32 v37, v37
	v_exp_f32_e32 v38, v38
	v_exp_f32_e32 v39, v39
	s_waitcnt lgkmcnt(2)
	v_mfma_f32_32x32x16_bf16 v[62:77], v[72:75], v[96:99], 0
	ds_read_b128 v[52:55], v166
	ds_read_b128 v[152:155], v166 offset:4096
	v_add_f32_e32 v151, v60, v151
	v_add_f32_e32 v162, v61, v32
	s_waitcnt lgkmcnt(3)
	v_mfma_f32_32x32x16_bf16 v[78:93], v[112:115], v[100:103], v[78:93]
	v_add_f32_e32 v112, v36, v161
	v_add_f32_e32 v113, v37, v163
	v_add_f32_e32 v114, v38, v151
	v_exp_f32_e32 v115, v40
	v_add_f32_e32 v40, v39, v162
	ds_read_b128 v[32:35], v167
	ds_read_b128 v[156:159], v167 offset:4096
	s_waitcnt lgkmcnt(4)
	v_mfma_f32_32x32x16_bf16 v[62:77], v[116:119], v[100:103], v[62:77]
	v_exp_f32_e32 v116, v41
	v_add_f32_e32 v41, v115, v112
	s_min_u32 s9, s3, s2
	s_lshl_b32 s9, s9, 6
	v_add_f32_e32 v112, v116, v113
	s_waitcnt lgkmcnt(3)
	v_mfma_f32_32x32x16_bf16 v[78:93], v[52:55], v[104:107], v[78:93]
	v_cvt_pk_bf16_f32 v54, v36, v37
	v_exp_f32_e32 v37, v42
	v_cvt_pk_bf16_f32 v55, v38, v39
	v_exp_f32_e32 v38, v43
	v_exp_f32_e32 v39, v44
	v_exp_f32_e32 v44, v45
	v_exp_f32_e32 v45, v46
	v_exp_f32_e32 v46, v47
	v_cvt_pk_bf16_f32 v52, v95, v160
	v_cvt_pk_bf16_f32 v53, v60, v61
	v_add_f32_e32 v36, v37, v114
	v_add_f32_e32 v43, v38, v40
	v_add_f32_e32 v40, v39, v41
	v_add_f32_e32 v42, v44, v112
	v_add_f32_e32 v41, v45, v36
	v_add_f32_e32 v43, v46, v43
	v_cvt_pk_bf16_f32 v36, v115, v116
	v_cvt_pk_bf16_f32 v37, v37, v38
	v_cvt_pk_bf16_f32 v38, v39, v44
	v_cvt_pk_bf16_f32 v39, v45, v46
	s_waitcnt lgkmcnt(1)
	v_mfma_f32_32x32x16_bf16 v[78:93], v[32:35], v[108:111], v[78:93]
	s_waitcnt lgkmcnt(0)
	s_barrier
	s_mul_i32 s18, s9, 0x1200
	s_mov_b32 s19, 0
	v_lshl_add_u64 v[32:33], v[132:133], 0, s[18:19]
	global_load_dwordx4 v[112:115], v[32:33], off offset:2048
	global_load_dwordx4 v[116:119], v[136:137], off
	v_add_f32_e64 v32, v40, v42
	v_add_f32_e64 v33, v41, v43
	s_waitcnt vmcnt(4)
	ds_write_b128 v142, v[120:123]
	s_waitcnt vmcnt(3)
	ds_write_b128 v142, v[124:127] offset:8192
	v_mfma_f32_32x32x16_bf16 v[62:77], v[152:155], v[104:107], v[62:77]
	v_add_f32_e32 v32, v32, v33
	v_add_f32_e32 v150, v150, v32
	s_waitcnt lgkmcnt(2)
	v_mfma_f32_32x32x16_bf16 v[62:77], v[156:159], v[108:111], v[62:77]
	ds_read_b128 v[32:35], v144 offset:24576
	ds_read_b128 v[40:43], v144 offset:28672
	ds_read_b128 v[44:47], v141 offset:24576
	ds_read_b128 v[120:123], v141 offset:28672
	v_exp_f32_e32 v60, v78
	s_waitcnt lgkmcnt(3)
	v_mfma_f32_32x32x16_bf16 v[16:31], v[32:35], v[56:59], v[16:31]
	v_exp_f32_e32 v61, v79
	v_exp_f32_e32 v95, v80
	v_exp_f32_e32 v81, v81
	ds_read_b128 v[152:155], v140 offset:24576
	ds_read_b128 v[156:159], v140 offset:28672
	s_waitcnt lgkmcnt(4)
	v_mfma_f32_32x32x16_bf16 v[0:15], v[40:43], v[56:59], v[0:15]
	v_exp_f32_e32 v82, v82
	v_exp_f32_e32 v83, v83
	v_add_f32_e32 v78, v82, v60
	v_add_f32_e32 v79, v83, v61
	s_waitcnt lgkmcnt(2)
	v_mfma_f32_32x32x16_bf16 v[0:15], v[120:123], v[48:51], v[0:15]
	ds_read_b128 v[56:59], v139 offset:24576
	ds_read_b128 v[160:163], v139 offset:28672
	ds_read_b128 v[40:43], v164 offset:16384
	ds_read_b128 v[32:35], v164 offset:20480
	v_cvt_pk_bf16_f32 v82, v82, v83
	v_exp_f32_e32 v151, v62
	v_exp_f32_e32 v64, v64
	v_exp_f32_e32 v65, v65
	v_mfma_f32_32x32x16_bf16 v[16:31], v[44:47], v[48:51], v[16:31]
	v_exp_f32_e32 v44, v84
	v_exp_f32_e32 v45, v85
	v_exp_f32_e32 v84, v86
	v_exp_f32_e32 v85, v87
	v_add_f32_e32 v46, v44, v95
	v_add_f32_e32 v47, v45, v81
	v_add_f32_e32 v48, v84, v78
	s_waitcnt lgkmcnt(4)
	v_mfma_f32_32x32x16_bf16 v[0:15], v[156:159], v[52:55], v[0:15]
	v_add_f32_e32 v49, v85, v79
	v_exp_f32_e32 v78, v88
	v_exp_f32_e32 v79, v89
	v_exp_f32_e32 v87, v92
	v_cvt_pk_bf16_f32 v83, v44, v45
	v_exp_f32_e32 v44, v90
	v_mfma_f32_32x32x16_bf16 v[16:31], v[152:155], v[52:55], v[16:31]
	v_exp_f32_e32 v45, v91
	v_exp_f32_e32 v92, v93
	v_add_f32_e32 v46, v78, v46
	v_add_f32_e32 v47, v79, v47
	ds_read_b128 v[124:127], v165 offset:16384
	ds_read_b128 v[120:123], v165 offset:20480
	s_waitcnt lgkmcnt(4)
	v_mfma_f32_32x32x16_bf16 v[0:15], v[160:163], v[36:39], v[0:15]
	v_exp_f32_e32 v160, v63
	v_cvt_pk_bf16_f32 v80, v60, v61
	v_cvt_pk_bf16_f32 v81, v95, v81
	v_add_f32_e32 v48, v44, v48
	v_add_f32_e32 v49, v45, v49
	v_add_f32_e32 v46, v87, v46
	v_add_f32_e32 v47, v92, v47
	v_mfma_f32_32x32x16_bf16 v[16:31], v[56:59], v[36:39], v[16:31]
	v_add_f32_e32 v161, v151, v48
	v_add_f32_e32 v162, v160, v49
	v_cvt_pk_bf16_f32 v84, v84, v85
	v_cvt_pk_bf16_f32 v85, v78, v79
	v_cvt_pk_bf16_f32 v86, v44, v45
	v_add_f32_e32 v78, v64, v46
	v_add_f32_e32 v79, v65, v47
	s_waitcnt lgkmcnt(3)
	v_mfma_f32_32x32x16_bf16 v[48:63], v[40:43], v[96:99], 0
	ds_read_b128 v[88:91], v166 offset:16384
	ds_read_b128 v[152:155], v166 offset:20480
	v_exp_f32_e32 v66, v66
	v_exp_f32_e32 v67, v67
	v_exp_f32_e32 v68, v68
	v_exp_f32_e32 v69, v69
	v_cvt_pk_bf16_f32 v87, v87, v92
	s_waitcnt lgkmcnt(4)
	v_mfma_f32_32x32x16_bf16 v[32:47], v[32:35], v[96:99], 0
	ds_read_b128 v[156:159], v167 offset:16384
	ds_read_b128 v[92:95], v167 offset:20480
	v_add_f32_e32 v161, v66, v161
	v_add_f32_e32 v162, v67, v162
	v_add_f32_e32 v78, v68, v78
	v_add_f32_e32 v79, v69, v79
	s_waitcnt lgkmcnt(5)
	v_mfma_f32_32x32x16_bf16 v[48:63], v[124:127], v[100:103], v[48:63]
	v_exp_f32_e32 v70, v70
	v_exp_f32_e32 v71, v71
	s_add_i32 s9, s3, 2
	s_add_i32 s3, s3, -2
	v_lshl_add_u64 v[136:137], v[136:137], 0, s[22:23]
	s_waitcnt lgkmcnt(4)
	v_mfma_f32_32x32x16_bf16 v[32:47], v[120:123], v[100:103], v[32:47]
	v_add_f32_e32 v120, v70, v161
	v_add_f32_e32 v121, v71, v162
	s_cmp_lt_u32 s3, s2
	s_mov_b32 s3, s9
	s_waitcnt lgkmcnt(3)
	v_mfma_f32_32x32x16_bf16 v[48:63], v[88:91], v[104:107], v[48:63]
	v_cvt_pk_bf16_f32 v91, v68, v69
	v_exp_f32_e32 v68, v72
	v_exp_f32_e32 v69, v73
	v_exp_f32_e32 v72, v74
	v_exp_f32_e32 v73, v75
	v_exp_f32_e32 v74, v76
	v_exp_f32_e32 v75, v77
	s_waitcnt lgkmcnt(2)
	v_mfma_f32_32x32x16_bf16 v[32:47], v[152:155], v[104:107], v[32:47]
	v_cvt_pk_bf16_f32 v88, v151, v160
	v_cvt_pk_bf16_f32 v89, v64, v65
	v_cvt_pk_bf16_f32 v90, v66, v67
	v_add_f32_e32 v65, v68, v78
	v_add_f32_e32 v67, v69, v79
	s_waitcnt lgkmcnt(1)
	v_mfma_f32_32x32x16_bf16 v[48:63], v[156:159], v[108:111], v[48:63]
	v_add_f32_e32 v64, v72, v120
	v_add_f32_e32 v66, v73, v121
	v_add_f32_e32 v65, v74, v65
	v_add_f32_e32 v67, v75, v67
	s_waitcnt lgkmcnt(0)
	v_mfma_f32_32x32x16_bf16 v[32:47], v[92:95], v[108:111], v[32:47]
	v_cvt_pk_bf16_f32 v92, v70, v71
	v_cvt_pk_bf16_f32 v93, v68, v69
	v_cvt_pk_bf16_f32 v94, v72, v73
	v_cvt_pk_bf16_f32 v95, v74, v75
	v_add_f32_e64 v64, v64, v66
	v_add_f32_e64 v65, v65, v67
	s_waitcnt lgkmcnt(0)
	s_barrier
	v_add_f32_e32 v64, v64, v65
	v_add_f32_e32 v150, v150, v64
.Lpeel_7:
	s_add_i32 s9, s3, -1
	s_min_u32 s9, s9, s2
	s_lshl_b32 s9, s9, 6
	s_waitcnt vmcnt(1)
	ds_write_b128 v142, v[112:115] offset:16384
	s_waitcnt vmcnt(0)
	ds_write_b128 v142, v[116:119] offset:24576
	s_mul_i32 s18, s9, 0x1200
	s_mov_b32 s19, 0
	v_lshl_add_u64 v[64:65], v[132:133], 0, s[18:19]
	global_load_dwordx4 v[120:123], v[64:65], off offset:2048
	global_load_dwordx4 v[124:127], v[136:137], off offset:-128
	ds_read_b128 v[64:67], v144 offset:8192
	ds_read_b128 v[68:71], v144 offset:12288
	ds_read_b128 v[72:75], v141 offset:8192
	ds_read_b128 v[76:79], v141 offset:12288
	v_exp_f32_e32 v151, v48
	v_exp_f32_e32 v152, v49
	s_waitcnt lgkmcnt(3)
	v_mfma_f32_32x32x16_bf16 v[16:31], v[64:67], v[80:83], v[16:31]
	v_exp_f32_e32 v153, v50
	v_exp_f32_e32 v154, v51
	ds_read_b128 v[48:51], v140 offset:8192
	ds_read_b128 v[64:67], v140 offset:12288
	v_exp_f32_e32 v155, v52
	s_waitcnt lgkmcnt(4)
	v_mfma_f32_32x32x16_bf16 v[0:15], v[68:71], v[80:83], v[0:15]
	v_exp_f32_e32 v156, v53
	v_exp_f32_e32 v159, v54
	v_exp_f32_e32 v160, v55
	v_exp_f32_e32 v162, v57
	s_waitcnt lgkmcnt(3)
	v_mfma_f32_32x32x16_bf16 v[16:31], v[72:75], v[84:87], v[16:31]
	ds_read_b128 v[68:71], v139 offset:8192
	ds_read_b128 v[80:83], v139 offset:12288
	v_add_f32_e32 v157, v155, v151
	v_add_f32_e32 v158, v156, v152
	ds_read_b128 v[52:55], v164
	ds_read_b128 v[72:75], v164 offset:4096
	v_add_f32_e32 v161, v159, v153
	s_waitcnt lgkmcnt(6)
	v_mfma_f32_32x32x16_bf16 v[0:15], v[76:79], v[84:87], v[0:15]
	v_exp_f32_e32 v77, v56
	v_add_f32_e32 v76, v160, v154
	v_exp_f32_e32 v62, v62
	ds_read_b128 v[112:115], v165
	ds_read_b128 v[116:119], v165 offset:4096
	v_cvt_pk_bf16_f32 v56, v151, v152
	s_waitcnt lgkmcnt(7)
	v_mfma_f32_32x32x16_bf16 v[16:31], v[48:51], v[88:91], v[16:31]
	v_exp_f32_e32 v49, v58
	v_exp_f32_e32 v50, v59
	v_add_f32_e32 v48, v77, v157
	v_add_f32_e32 v51, v162, v158
	v_add_f32_e32 v78, v49, v161
	v_add_f32_e32 v76, v50, v76
	s_waitcnt lgkmcnt(6)
	v_mfma_f32_32x32x16_bf16 v[0:15], v[64:67], v[88:91], v[0:15]
	v_exp_f32_e32 v60, v60
	v_add_f32_e32 v151, v62, v78
	v_exp_f32_e32 v61, v61
	v_exp_f32_e32 v63, v63
	v_cvt_pk_bf16_f32 v59, v159, v160
	v_exp_f32_e32 v160, v33
	s_waitcnt lgkmcnt(5)
	v_mfma_f32_32x32x16_bf16 v[16:31], v[68:71], v[92:95], v[16:31]
	v_cvt_pk_bf16_f32 v57, v153, v154
	v_cvt_pk_bf16_f32 v58, v155, v156
	v_add_f32_e32 v48, v60, v48
	v_add_f32_e32 v51, v61, v51
	v_cvt_pk_bf16_f32 v49, v49, v50
	s_waitcnt lgkmcnt(4)
	v_mfma_f32_32x32x16_bf16 v[0:15], v[80:83], v[92:95], v[0:15]
	v_readfirstlane_b32 s18, v171
	s_add_u32 m0, s18, 0x15ba0
	s_nop 0
	global_load_lds_dwordx4 v168, s[14:15] offset:1120
	v_exp_f32_e32 v95, v32
	v_add_f32_e32 v32, v63, v76
	v_add_f32_e32 v163, v160, v51
	v_add_f32_e32 v161, v95, v48
	v_cvt_pk_bf16_f32 v48, v77, v162
	v_cvt_pk_bf16_f32 v51, v62, v63
	s_waitcnt lgkmcnt(3)
	v_mfma_f32_32x32x16_bf16 v[78:93], v[52:55], v[96:99], 0
	v_cvt_pk_bf16_f32 v50, v60, v61
	v_exp_f32_e32 v60, v34
	v_exp_f32_e32 v61, v35
	v_exp_f32_e32 v36, v36
	v_exp_f32_e32 v37, v37
	v_exp_f32_e32 v38, v38
	v_exp_f32_e32 v39, v39
	s_waitcnt lgkmcnt(2)
	v_mfma_f32_32x32x16_bf16 v[62:77], v[72:75], v[96:99], 0
	ds_read_b128 v[52:55], v166
	ds_read_b128 v[152:155], v166 offset:4096
	v_add_f32_e32 v151, v60, v151
	v_add_f32_e32 v162, v61, v32
	s_waitcnt lgkmcnt(3)
	v_mfma_f32_32x32x16_bf16 v[78:93], v[112:115], v[100:103], v[78:93]
	v_add_f32_e32 v112, v36, v161
	v_add_f32_e32 v113, v37, v163
	v_add_f32_e32 v114, v38, v151
	v_exp_f32_e32 v115, v40
	v_add_f32_e32 v40, v39, v162
	ds_read_b128 v[32:35], v167
	ds_read_b128 v[156:159], v167 offset:4096
	s_waitcnt lgkmcnt(4)
	v_mfma_f32_32x32x16_bf16 v[62:77], v[116:119], v[100:103], v[62:77]
	v_exp_f32_e32 v116, v41
	v_add_f32_e32 v41, v115, v112
	s_min_u32 s9, s3, s2
	s_lshl_b32 s9, s9, 6
	v_add_f32_e32 v112, v116, v113
	s_waitcnt lgkmcnt(3)
	v_mfma_f32_32x32x16_bf16 v[78:93], v[52:55], v[104:107], v[78:93]
	v_cvt_pk_bf16_f32 v54, v36, v37
	v_exp_f32_e32 v37, v42
	v_cvt_pk_bf16_f32 v55, v38, v39
	v_exp_f32_e32 v38, v43
	v_exp_f32_e32 v39, v44
	v_exp_f32_e32 v44, v45
	v_exp_f32_e32 v45, v46
	v_exp_f32_e32 v46, v47
	v_cvt_pk_bf16_f32 v52, v95, v160
	v_cvt_pk_bf16_f32 v53, v60, v61
	v_add_f32_e32 v36, v37, v114
	v_add_f32_e32 v43, v38, v40
	v_add_f32_e32 v40, v39, v41
	v_add_f32_e32 v42, v44, v112
	v_add_f32_e32 v41, v45, v36
	v_add_f32_e32 v43, v46, v43
	v_cvt_pk_bf16_f32 v36, v115, v116
	v_cvt_pk_bf16_f32 v37, v37, v38
	v_cvt_pk_bf16_f32 v38, v39, v44
	v_cvt_pk_bf16_f32 v39, v45, v46
	s_waitcnt lgkmcnt(1)
	v_mfma_f32_32x32x16_bf16 v[78:93], v[32:35], v[108:111], v[78:93]
	s_waitcnt lgkmcnt(0)
	s_barrier
	s_mul_i32 s18, s9, 0x1200
	s_mov_b32 s19, 0
	v_lshl_add_u64 v[32:33], v[132:133], 0, s[18:19]
	global_load_dwordx4 v[112:115], v[32:33], off offset:2048
	global_load_dwordx4 v[116:119], v[136:137], off
	v_add_f32_e64 v32, v40, v42
	v_add_f32_e64 v33, v41, v43
	s_waitcnt vmcnt(4)
	ds_write_b128 v142, v[120:123]
	s_waitcnt vmcnt(3)
	ds_write_b128 v142, v[124:127] offset:8192
	v_mfma_f32_32x32x16_bf16 v[62:77], v[152:155], v[104:107], v[62:77]
	v_add_f32_e32 v32, v32, v33
	v_add_f32_e32 v150, v150, v32
	s_waitcnt lgkmcnt(2)
	v_mfma_f32_32x32x16_bf16 v[62:77], v[156:159], v[108:111], v[62:77]
	ds_read_b128 v[32:35], v144 offset:24576
	ds_read_b128 v[40:43], v144 offset:28672
	ds_read_b128 v[44:47], v141 offset:24576
	ds_read_b128 v[120:123], v141 offset:28672
	v_exp_f32_e32 v60, v78
	s_waitcnt lgkmcnt(3)
	v_mfma_f32_32x32x16_bf16 v[16:31], v[32:35], v[56:59], v[16:31]
	v_exp_f32_e32 v61, v79
	v_exp_f32_e32 v95, v80
	v_exp_f32_e32 v81, v81
	ds_read_b128 v[152:155], v140 offset:24576
	ds_read_b128 v[156:159], v140 offset:28672
	s_waitcnt lgkmcnt(4)
	v_mfma_f32_32x32x16_bf16 v[0:15], v[40:43], v[56:59], v[0:15]
	v_exp_f32_e32 v82, v82
	v_exp_f32_e32 v83, v83
	v_add_f32_e32 v78, v82, v60
	v_add_f32_e32 v79, v83, v61
	s_waitcnt lgkmcnt(2)
	v_mfma_f32_32x32x16_bf16 v[0:15], v[120:123], v[48:51], v[0:15]
	ds_read_b128 v[56:59], v139 offset:24576
	ds_read_b128 v[160:163], v139 offset:28672
	ds_read_b128 v[40:43], v164 offset:16384
	ds_read_b128 v[32:35], v164 offset:20480
	v_cvt_pk_bf16_f32 v82, v82, v83
	v_exp_f32_e32 v151, v62
	v_exp_f32_e32 v64, v64
	v_exp_f32_e32 v65, v65
	v_mfma_f32_32x32x16_bf16 v[16:31], v[44:47], v[48:51], v[16:31]
	v_exp_f32_e32 v44, v84
	v_exp_f32_e32 v45, v85
	v_exp_f32_e32 v84, v86
	v_exp_f32_e32 v85, v87
	v_add_f32_e32 v46, v44, v95
	v_add_f32_e32 v47, v45, v81
	v_add_f32_e32 v48, v84, v78
	s_waitcnt lgkmcnt(4)
	v_mfma_f32_32x32x16_bf16 v[0:15], v[156:159], v[52:55], v[0:15]
	v_add_f32_e32 v49, v85, v79
	v_exp_f32_e32 v78, v88
	v_exp_f32_e32 v79, v89
	v_exp_f32_e32 v87, v92
	v_cvt_pk_bf16_f32 v83, v44, v45
	v_exp_f32_e32 v44, v90
	v_mfma_f32_32x32x16_bf16 v[16:31], v[152:155], v[52:55], v[16:31]
	v_exp_f32_e32 v45, v91
	v_exp_f32_e32 v92, v93
	v_add_f32_e32 v46, v78, v46
	v_add_f32_e32 v47, v79, v47
	ds_read_b128 v[124:127], v165 offset:16384
	ds_read_b128 v[120:123], v165 offset:20480
	s_waitcnt lgkmcnt(4)
	v_mfma_f32_32x32x16_bf16 v[0:15], v[160:163], v[36:39], v[0:15]
	v_exp_f32_e32 v160, v63
	v_cvt_pk_bf16_f32 v80, v60, v61
	v_cvt_pk_bf16_f32 v81, v95, v81
	v_add_f32_e32 v48, v44, v48
	v_add_f32_e32 v49, v45, v49
	v_add_f32_e32 v46, v87, v46
	v_add_f32_e32 v47, v92, v47
	v_mfma_f32_32x32x16_bf16 v[16:31], v[56:59], v[36:39], v[16:31]
	v_add_f32_e32 v161, v151, v48
	v_add_f32_e32 v162, v160, v49
	v_cvt_pk_bf16_f32 v84, v84, v85
	v_cvt_pk_bf16_f32 v85, v78, v79
	v_cvt_pk_bf16_f32 v86, v44, v45
	v_add_f32_e32 v78, v64, v46
	v_add_f32_e32 v79, v65, v47
	s_waitcnt lgkmcnt(3)
	v_mfma_f32_32x32x16_bf16 v[48:63], v[40:43], v[96:99], 0
	ds_read_b128 v[88:91], v166 offset:16384
	ds_read_b128 v[152:155], v166 offset:20480
	v_exp_f32_e32 v66, v66
	v_exp_f32_e32 v67, v67
	v_exp_f32_e32 v68, v68
	v_exp_f32_e32 v69, v69
	v_cvt_pk_bf16_f32 v87, v87, v92
	s_waitcnt lgkmcnt(4)
	v_mfma_f32_32x32x16_bf16 v[32:47], v[32:35], v[96:99], 0
	ds_read_b128 v[156:159], v167 offset:16384
	ds_read_b128 v[92:95], v167 offset:20480
	v_add_f32_e32 v161, v66, v161
	v_add_f32_e32 v162, v67, v162
	v_add_f32_e32 v78, v68, v78
	v_add_f32_e32 v79, v69, v79
	s_waitcnt lgkmcnt(5)
	v_mfma_f32_32x32x16_bf16 v[48:63], v[124:127], v[100:103], v[48:63]
	v_exp_f32_e32 v70, v70
	v_exp_f32_e32 v71, v71
	s_add_i32 s9, s3, 2
	s_add_i32 s3, s3, -2
	v_lshl_add_u64 v[136:137], v[136:137], 0, s[22:23]
	s_waitcnt lgkmcnt(4)
	v_mfma_f32_32x32x16_bf16 v[32:47], v[120:123], v[100:103], v[32:47]
	v_add_f32_e32 v120, v70, v161
	v_add_f32_e32 v121, v71, v162
	s_cmp_lt_u32 s3, s2
	s_mov_b32 s3, s9
	s_waitcnt lgkmcnt(3)
	v_mfma_f32_32x32x16_bf16 v[48:63], v[88:91], v[104:107], v[48:63]
	v_cvt_pk_bf16_f32 v91, v68, v69
	v_exp_f32_e32 v68, v72
	v_exp_f32_e32 v69, v73
	v_exp_f32_e32 v72, v74
	v_exp_f32_e32 v73, v75
	v_exp_f32_e32 v74, v76
	v_exp_f32_e32 v75, v77
	s_waitcnt lgkmcnt(2)
	v_mfma_f32_32x32x16_bf16 v[32:47], v[152:155], v[104:107], v[32:47]
	v_cvt_pk_bf16_f32 v88, v151, v160
	v_cvt_pk_bf16_f32 v89, v64, v65
	v_cvt_pk_bf16_f32 v90, v66, v67
	v_add_f32_e32 v65, v68, v78
	v_add_f32_e32 v67, v69, v79
	s_waitcnt lgkmcnt(1)
	v_mfma_f32_32x32x16_bf16 v[48:63], v[156:159], v[108:111], v[48:63]
	v_add_f32_e32 v64, v72, v120
	v_add_f32_e32 v66, v73, v121
	v_add_f32_e32 v65, v74, v65
	v_add_f32_e32 v67, v75, v67
	s_waitcnt lgkmcnt(0)
	v_mfma_f32_32x32x16_bf16 v[32:47], v[92:95], v[108:111], v[32:47]
	v_cvt_pk_bf16_f32 v92, v70, v71
	v_cvt_pk_bf16_f32 v93, v68, v69
	v_cvt_pk_bf16_f32 v94, v72, v73
	v_cvt_pk_bf16_f32 v95, v74, v75
	v_add_f32_e64 v64, v64, v66
	v_add_f32_e64 v65, v65, v67
	s_waitcnt lgkmcnt(0)
	s_barrier
	v_add_f32_e32 v64, v64, v65
	v_add_f32_e32 v150, v150, v64
.Lpeel_8:
	s_add_i32 s9, s3, -1
	s_min_u32 s9, s9, s2
	s_lshl_b32 s9, s9, 6
	s_waitcnt vmcnt(1)
	ds_write_b128 v142, v[112:115] offset:16384
	s_waitcnt vmcnt(0)
	ds_write_b128 v142, v[116:119] offset:24576
	s_mul_i32 s18, s9, 0x1200
	s_mov_b32 s19, 0
	v_lshl_add_u64 v[64:65], v[132:133], 0, s[18:19]
	global_load_dwordx4 v[120:123], v[64:65], off offset:2048
	global_load_dwordx4 v[124:127], v[136:137], off offset:-128
	ds_read_b128 v[64:67], v144 offset:8192
	ds_read_b128 v[68:71], v144 offset:12288
	ds_read_b128 v[72:75], v141 offset:8192
	ds_read_b128 v[76:79], v141 offset:12288
	v_exp_f32_e32 v151, v48
	v_exp_f32_e32 v152, v49
	s_waitcnt lgkmcnt(3)
	v_mfma_f32_32x32x16_bf16 v[16:31], v[64:67], v[80:83], v[16:31]
	v_exp_f32_e32 v153, v50
	v_exp_f32_e32 v154, v51
	ds_read_b128 v[48:51], v140 offset:8192
	ds_read_b128 v[64:67], v140 offset:12288
	v_exp_f32_e32 v155, v52
	s_waitcnt lgkmcnt(4)
	v_mfma_f32_32x32x16_bf16 v[0:15], v[68:71], v[80:83], v[0:15]
	v_exp_f32_e32 v156, v53
	v_exp_f32_e32 v159, v54
	v_exp_f32_e32 v160, v55
	v_exp_f32_e32 v162, v57
	s_waitcnt lgkmcnt(3)
	v_mfma_f32_32x32x16_bf16 v[16:31], v[72:75], v[84:87], v[16:31]
	ds_read_b128 v[68:71], v139 offset:8192
	ds_read_b128 v[80:83], v139 offset:12288
	v_add_f32_e32 v157, v155, v151
	v_add_f32_e32 v158, v156, v152
	ds_read_b128 v[52:55], v164
	ds_read_b128 v[72:75], v164 offset:4096
	v_add_f32_e32 v161, v159, v153
	s_waitcnt lgkmcnt(6)
	v_mfma_f32_32x32x16_bf16 v[0:15], v[76:79], v[84:87], v[0:15]
	v_exp_f32_e32 v77, v56
	v_add_f32_e32 v76, v160, v154
	v_exp_f32_e32 v62, v62
	ds_read_b128 v[112:115], v165
	ds_read_b128 v[116:119], v165 offset:4096
	v_cvt_pk_bf16_f32 v56, v151, v152
	s_waitcnt lgkmcnt(7)
	v_mfma_f32_32x32x16_bf16 v[16:31], v[48:51], v[88:91], v[16:31]
	v_exp_f32_e32 v49, v58
	v_exp_f32_e32 v50, v59
	v_add_f32_e32 v48, v77, v157
	v_add_f32_e32 v51, v162, v158
	v_add_f32_e32 v78, v49, v161
	v_add_f32_e32 v76, v50, v76
	s_waitcnt lgkmcnt(6)
	v_mfma_f32_32x32x16_bf16 v[0:15], v[64:67], v[88:91], v[0:15]
	v_exp_f32_e32 v60, v60
	v_add_f32_e32 v151, v62, v78
	v_exp_f32_e32 v61, v61
	v_exp_f32_e32 v63, v63
	v_cvt_pk_bf16_f32 v59, v159, v160
	v_exp_f32_e32 v160, v33
	s_waitcnt lgkmcnt(5)
	v_mfma_f32_32x32x16_bf16 v[16:31], v[68:71], v[92:95], v[16:31]
	v_cvt_pk_bf16_f32 v57, v153, v154
	v_cvt_pk_bf16_f32 v58, v155, v156
	v_add_f32_e32 v48, v60, v48
	v_add_f32_e32 v51, v61, v51
	v_cvt_pk_bf16_f32 v49, v49, v50
	s_waitcnt lgkmcnt(4)
	v_mfma_f32_32x32x16_bf16 v[0:15], v[80:83], v[92:95], v[0:15]
	v_readfirstlane_b32 s18, v171
	s_mov_b64 vcc, s[34:35]
	s_add_u32 m0, s18, 0x17800
	s_nop 0
	global_load_lds_dwordx4 v170, vcc offset:2048
	v_exp_f32_e32 v95, v32
	v_add_f32_e32 v32, v63, v76
	v_add_f32_e32 v163, v160, v51
	v_add_f32_e32 v161, v95, v48
	v_cvt_pk_bf16_f32 v48, v77, v162
	v_cvt_pk_bf16_f32 v51, v62, v63
	s_waitcnt lgkmcnt(3)
	v_mfma_f32_32x32x16_bf16 v[78:93], v[52:55], v[96:99], 0
	v_cvt_pk_bf16_f32 v50, v60, v61
	v_exp_f32_e32 v60, v34
	v_exp_f32_e32 v61, v35
	v_exp_f32_e32 v36, v36
	v_exp_f32_e32 v37, v37
	v_exp_f32_e32 v38, v38
	v_exp_f32_e32 v39, v39
	s_waitcnt lgkmcnt(2)
	v_mfma_f32_32x32x16_bf16 v[62:77], v[72:75], v[96:99], 0
	ds_read_b128 v[52:55], v166
	ds_read_b128 v[152:155], v166 offset:4096
	v_add_f32_e32 v151, v60, v151
	v_add_f32_e32 v162, v61, v32
	s_waitcnt lgkmcnt(3)
	v_mfma_f32_32x32x16_bf16 v[78:93], v[112:115], v[100:103], v[78:93]
	v_add_f32_e32 v112, v36, v161
	v_add_f32_e32 v113, v37, v163
	v_add_f32_e32 v114, v38, v151
	v_exp_f32_e32 v115, v40
	v_add_f32_e32 v40, v39, v162
	ds_read_b128 v[32:35], v167
	ds_read_b128 v[156:159], v167 offset:4096
	s_waitcnt lgkmcnt(4)
	v_mfma_f32_32x32x16_bf16 v[62:77], v[116:119], v[100:103], v[62:77]
	v_exp_f32_e32 v116, v41
	v_add_f32_e32 v41, v115, v112
	s_min_u32 s9, s3, s2
	s_lshl_b32 s9, s9, 6
	v_add_f32_e32 v112, v116, v113
	s_waitcnt lgkmcnt(3)
	v_mfma_f32_32x32x16_bf16 v[78:93], v[52:55], v[104:107], v[78:93]
	v_cvt_pk_bf16_f32 v54, v36, v37
	v_exp_f32_e32 v37, v42
	v_cvt_pk_bf16_f32 v55, v38, v39
	v_exp_f32_e32 v38, v43
	v_exp_f32_e32 v39, v44
	v_exp_f32_e32 v44, v45
	v_exp_f32_e32 v45, v46
	v_exp_f32_e32 v46, v47
	v_cvt_pk_bf16_f32 v52, v95, v160
	v_cvt_pk_bf16_f32 v53, v60, v61
	v_add_f32_e32 v36, v37, v114
	v_add_f32_e32 v43, v38, v40
	v_add_f32_e32 v40, v39, v41
	v_add_f32_e32 v42, v44, v112
	v_add_f32_e32 v41, v45, v36
	v_add_f32_e32 v43, v46, v43
	v_cvt_pk_bf16_f32 v36, v115, v116
	v_cvt_pk_bf16_f32 v37, v37, v38
	v_cvt_pk_bf16_f32 v38, v39, v44
	v_cvt_pk_bf16_f32 v39, v45, v46
	s_waitcnt lgkmcnt(1)
	v_mfma_f32_32x32x16_bf16 v[78:93], v[32:35], v[108:111], v[78:93]
	s_waitcnt lgkmcnt(0)
	s_barrier
	s_mul_i32 s18, s9, 0x1200
	s_mov_b32 s19, 0
	v_lshl_add_u64 v[32:33], v[132:133], 0, s[18:19]
	global_load_dwordx4 v[112:115], v[32:33], off offset:2048
	global_load_dwordx4 v[116:119], v[136:137], off
	v_add_f32_e64 v32, v40, v42
	v_add_f32_e64 v33, v41, v43
	s_waitcnt vmcnt(4)
	ds_write_b128 v142, v[120:123]
	s_waitcnt vmcnt(3)
	ds_write_b128 v142, v[124:127] offset:8192
	v_mfma_f32_32x32x16_bf16 v[62:77], v[152:155], v[104:107], v[62:77]
	v_add_f32_e32 v32, v32, v33
	v_add_f32_e32 v150, v150, v32
	s_waitcnt lgkmcnt(2)
	v_mfma_f32_32x32x16_bf16 v[62:77], v[156:159], v[108:111], v[62:77]
	ds_read_b128 v[32:35], v144 offset:24576
	ds_read_b128 v[40:43], v144 offset:28672
	ds_read_b128 v[44:47], v141 offset:24576
	ds_read_b128 v[120:123], v141 offset:28672
	v_exp_f32_e32 v60, v78
	s_waitcnt lgkmcnt(3)
	v_mfma_f32_32x32x16_bf16 v[16:31], v[32:35], v[56:59], v[16:31]
	v_exp_f32_e32 v61, v79
	v_exp_f32_e32 v95, v80
	v_exp_f32_e32 v81, v81
	ds_read_b128 v[152:155], v140 offset:24576
	ds_read_b128 v[156:159], v140 offset:28672
	s_waitcnt lgkmcnt(4)
	v_mfma_f32_32x32x16_bf16 v[0:15], v[40:43], v[56:59], v[0:15]
	v_exp_f32_e32 v82, v82
	v_exp_f32_e32 v83, v83
	v_add_f32_e32 v78, v82, v60
	v_add_f32_e32 v79, v83, v61
	s_waitcnt lgkmcnt(2)
	v_mfma_f32_32x32x16_bf16 v[0:15], v[120:123], v[48:51], v[0:15]
	ds_read_b128 v[56:59], v139 offset:24576
	ds_read_b128 v[160:163], v139 offset:28672
	ds_read_b128 v[40:43], v164 offset:16384
	ds_read_b128 v[32:35], v164 offset:20480
	v_cvt_pk_bf16_f32 v82, v82, v83
	v_exp_f32_e32 v151, v62
	v_exp_f32_e32 v64, v64
	v_exp_f32_e32 v65, v65
	v_mfma_f32_32x32x16_bf16 v[16:31], v[44:47], v[48:51], v[16:31]
	v_exp_f32_e32 v44, v84
	v_exp_f32_e32 v45, v85
	v_exp_f32_e32 v84, v86
	v_exp_f32_e32 v85, v87
	v_add_f32_e32 v46, v44, v95
	v_add_f32_e32 v47, v45, v81
	v_add_f32_e32 v48, v84, v78
	s_waitcnt lgkmcnt(4)
	v_mfma_f32_32x32x16_bf16 v[0:15], v[156:159], v[52:55], v[0:15]
	v_add_f32_e32 v49, v85, v79
	v_exp_f32_e32 v78, v88
	v_exp_f32_e32 v79, v89
	v_exp_f32_e32 v87, v92
	v_cvt_pk_bf16_f32 v83, v44, v45
	v_exp_f32_e32 v44, v90
	v_mfma_f32_32x32x16_bf16 v[16:31], v[152:155], v[52:55], v[16:31]
	v_exp_f32_e32 v45, v91
	v_exp_f32_e32 v92, v93
	v_add_f32_e32 v46, v78, v46
	v_add_f32_e32 v47, v79, v47
	ds_read_b128 v[124:127], v165 offset:16384
	ds_read_b128 v[120:123], v165 offset:20480
	s_waitcnt lgkmcnt(4)
	v_mfma_f32_32x32x16_bf16 v[0:15], v[160:163], v[36:39], v[0:15]
	v_exp_f32_e32 v160, v63
	v_cvt_pk_bf16_f32 v80, v60, v61
	v_cvt_pk_bf16_f32 v81, v95, v81
	v_add_f32_e32 v48, v44, v48
	v_add_f32_e32 v49, v45, v49
	v_add_f32_e32 v46, v87, v46
	v_add_f32_e32 v47, v92, v47
	v_mfma_f32_32x32x16_bf16 v[16:31], v[56:59], v[36:39], v[16:31]
	v_add_f32_e32 v161, v151, v48
	v_add_f32_e32 v162, v160, v49
	v_cvt_pk_bf16_f32 v84, v84, v85
	v_cvt_pk_bf16_f32 v85, v78, v79
	v_cvt_pk_bf16_f32 v86, v44, v45
	v_add_f32_e32 v78, v64, v46
	v_add_f32_e32 v79, v65, v47
	s_waitcnt lgkmcnt(3)
	v_mfma_f32_32x32x16_bf16 v[48:63], v[40:43], v[96:99], 0
	ds_read_b128 v[88:91], v166 offset:16384
	ds_read_b128 v[152:155], v166 offset:20480
	v_exp_f32_e32 v66, v66
	v_exp_f32_e32 v67, v67
	v_exp_f32_e32 v68, v68
	v_exp_f32_e32 v69, v69
	v_cvt_pk_bf16_f32 v87, v87, v92
	s_waitcnt lgkmcnt(4)
	v_mfma_f32_32x32x16_bf16 v[32:47], v[32:35], v[96:99], 0
	ds_read_b128 v[156:159], v167 offset:16384
	ds_read_b128 v[92:95], v167 offset:20480
	v_add_f32_e32 v161, v66, v161
	v_add_f32_e32 v162, v67, v162
	v_add_f32_e32 v78, v68, v78
	v_add_f32_e32 v79, v69, v79
	s_waitcnt lgkmcnt(5)
	v_mfma_f32_32x32x16_bf16 v[48:63], v[124:127], v[100:103], v[48:63]
	v_exp_f32_e32 v70, v70
	v_exp_f32_e32 v71, v71
	s_add_i32 s9, s3, 2
	s_add_i32 s3, s3, -2
	v_lshl_add_u64 v[136:137], v[136:137], 0, s[22:23]
	s_waitcnt lgkmcnt(4)
	v_mfma_f32_32x32x16_bf16 v[32:47], v[120:123], v[100:103], v[32:47]
	v_add_f32_e32 v120, v70, v161
	v_add_f32_e32 v121, v71, v162
	s_cmp_lt_u32 s3, s2
	s_mov_b32 s3, s9
	s_waitcnt lgkmcnt(3)
	v_mfma_f32_32x32x16_bf16 v[48:63], v[88:91], v[104:107], v[48:63]
	v_cvt_pk_bf16_f32 v91, v68, v69
	v_exp_f32_e32 v68, v72
	v_exp_f32_e32 v69, v73
	v_exp_f32_e32 v72, v74
	v_exp_f32_e32 v73, v75
	v_exp_f32_e32 v74, v76
	v_exp_f32_e32 v75, v77
	s_waitcnt lgkmcnt(2)
	v_mfma_f32_32x32x16_bf16 v[32:47], v[152:155], v[104:107], v[32:47]
	v_cvt_pk_bf16_f32 v88, v151, v160
	v_cvt_pk_bf16_f32 v89, v64, v65
	v_cvt_pk_bf16_f32 v90, v66, v67
	v_add_f32_e32 v65, v68, v78
	v_add_f32_e32 v67, v69, v79
	s_waitcnt lgkmcnt(1)
	v_mfma_f32_32x32x16_bf16 v[48:63], v[156:159], v[108:111], v[48:63]
	v_add_f32_e32 v64, v72, v120
	v_add_f32_e32 v66, v73, v121
	v_add_f32_e32 v65, v74, v65
	v_add_f32_e32 v67, v75, v67
	s_waitcnt lgkmcnt(0)
	v_mfma_f32_32x32x16_bf16 v[32:47], v[92:95], v[108:111], v[32:47]
	v_cvt_pk_bf16_f32 v92, v70, v71
	v_cvt_pk_bf16_f32 v93, v68, v69
	v_cvt_pk_bf16_f32 v94, v72, v73
	v_cvt_pk_bf16_f32 v95, v74, v75
	v_add_f32_e64 v64, v64, v66
	v_add_f32_e64 v65, v65, v67
	s_waitcnt lgkmcnt(0)
	s_barrier
	v_add_f32_e32 v64, v64, v65
	v_add_f32_e32 v150, v150, v64
.Lpeel_9:
	s_add_i32 s9, s3, -1
	s_min_u32 s9, s9, s2
	s_lshl_b32 s9, s9, 6
	s_waitcnt vmcnt(1)
	ds_write_b128 v142, v[112:115] offset:16384
	s_waitcnt vmcnt(0)
	ds_write_b128 v142, v[116:119] offset:24576
	s_mul_i32 s18, s9, 0x1200
	s_mov_b32 s19, 0
	v_lshl_add_u64 v[64:65], v[132:133], 0, s[18:19]
	global_load_dwordx4 v[120:123], v[64:65], off offset:2048
	global_load_dwordx4 v[124:127], v[136:137], off offset:-128
	ds_read_b128 v[64:67], v144 offset:8192
	ds_read_b128 v[68:71], v144 offset:12288
	ds_read_b128 v[72:75], v141 offset:8192
	ds_read_b128 v[76:79], v141 offset:12288
	v_exp_f32_e32 v151, v48
	v_exp_f32_e32 v152, v49
	s_waitcnt lgkmcnt(3)
	v_mfma_f32_32x32x16_bf16 v[16:31], v[64:67], v[80:83], v[16:31]
	v_exp_f32_e32 v153, v50
	v_exp_f32_e32 v154, v51
	ds_read_b128 v[48:51], v140 offset:8192
	ds_read_b128 v[64:67], v140 offset:12288
	v_exp_f32_e32 v155, v52
	s_waitcnt lgkmcnt(4)
	v_mfma_f32_32x32x16_bf16 v[0:15], v[68:71], v[80:83], v[0:15]
	v_exp_f32_e32 v156, v53
	v_exp_f32_e32 v159, v54
	v_exp_f32_e32 v160, v55
	v_exp_f32_e32 v162, v57
	s_waitcnt lgkmcnt(3)
	v_mfma_f32_32x32x16_bf16 v[16:31], v[72:75], v[84:87], v[16:31]
	ds_read_b128 v[68:71], v139 offset:8192
	ds_read_b128 v[80:83], v139 offset:12288
	v_add_f32_e32 v157, v155, v151
	v_add_f32_e32 v158, v156, v152
	ds_read_b128 v[52:55], v164
	ds_read_b128 v[72:75], v164 offset:4096
	v_add_f32_e32 v161, v159, v153
	s_waitcnt lgkmcnt(6)
	v_mfma_f32_32x32x16_bf16 v[0:15], v[76:79], v[84:87], v[0:15]
	v_exp_f32_e32 v77, v56
	v_add_f32_e32 v76, v160, v154
	v_exp_f32_e32 v62, v62
	ds_read_b128 v[112:115], v165
	ds_read_b128 v[116:119], v165 offset:4096
	v_cvt_pk_bf16_f32 v56, v151, v152
	s_waitcnt lgkmcnt(7)
	v_mfma_f32_32x32x16_bf16 v[16:31], v[48:51], v[88:91], v[16:31]
	v_exp_f32_e32 v49, v58
	v_exp_f32_e32 v50, v59
	v_add_f32_e32 v48, v77, v157
	v_add_f32_e32 v51, v162, v158
	v_add_f32_e32 v78, v49, v161
	v_add_f32_e32 v76, v50, v76
	s_waitcnt lgkmcnt(6)
	v_mfma_f32_32x32x16_bf16 v[0:15], v[64:67], v[88:91], v[0:15]
	v_exp_f32_e32 v60, v60
	v_add_f32_e32 v151, v62, v78
	v_exp_f32_e32 v61, v61
	v_exp_f32_e32 v63, v63
	v_cvt_pk_bf16_f32 v59, v159, v160
	v_exp_f32_e32 v160, v33
	s_waitcnt lgkmcnt(5)
	v_mfma_f32_32x32x16_bf16 v[16:31], v[68:71], v[92:95], v[16:31]
	v_cvt_pk_bf16_f32 v57, v153, v154
	v_cvt_pk_bf16_f32 v58, v155, v156
	v_add_f32_e32 v48, v60, v48
	v_add_f32_e32 v51, v61, v51
	v_cvt_pk_bf16_f32 v49, v49, v50
	s_waitcnt lgkmcnt(4)
	v_mfma_f32_32x32x16_bf16 v[0:15], v[80:83], v[92:95], v[0:15]
	v_readfirstlane_b32 s18, v171
	s_add_u32 vcc_lo, s34, 0x48000
	s_addc_u32 vcc_hi, s35, 0
	s_add_u32 m0, s18, 0x19800
	s_nop 0
	global_load_lds_dwordx4 v170, vcc offset:2048
	v_exp_f32_e32 v95, v32
	v_add_f32_e32 v32, v63, v76
	v_add_f32_e32 v163, v160, v51
	v_add_f32_e32 v161, v95, v48
	v_cvt_pk_bf16_f32 v48, v77, v162
	v_cvt_pk_bf16_f32 v51, v62, v63
	s_waitcnt lgkmcnt(3)
	v_mfma_f32_32x32x16_bf16 v[78:93], v[52:55], v[96:99], 0
	v_cvt_pk_bf16_f32 v50, v60, v61
	v_exp_f32_e32 v60, v34
	v_exp_f32_e32 v61, v35
	v_exp_f32_e32 v36, v36
	v_exp_f32_e32 v37, v37
	v_exp_f32_e32 v38, v38
	v_exp_f32_e32 v39, v39
	s_waitcnt lgkmcnt(2)
	v_mfma_f32_32x32x16_bf16 v[62:77], v[72:75], v[96:99], 0
	ds_read_b128 v[52:55], v166
	ds_read_b128 v[152:155], v166 offset:4096
	v_add_f32_e32 v151, v60, v151
	v_add_f32_e32 v162, v61, v32
	s_waitcnt lgkmcnt(3)
	v_mfma_f32_32x32x16_bf16 v[78:93], v[112:115], v[100:103], v[78:93]
	v_add_f32_e32 v112, v36, v161
	v_add_f32_e32 v113, v37, v163
	v_add_f32_e32 v114, v38, v151
	v_exp_f32_e32 v115, v40
	v_add_f32_e32 v40, v39, v162
	ds_read_b128 v[32:35], v167
	ds_read_b128 v[156:159], v167 offset:4096
	s_waitcnt lgkmcnt(4)
	v_mfma_f32_32x32x16_bf16 v[62:77], v[116:119], v[100:103], v[62:77]
	v_exp_f32_e32 v116, v41
	v_add_f32_e32 v41, v115, v112
	s_min_u32 s9, s3, s2
	s_lshl_b32 s9, s9, 6
	v_add_f32_e32 v112, v116, v113
	s_waitcnt lgkmcnt(3)
	v_mfma_f32_32x32x16_bf16 v[78:93], v[52:55], v[104:107], v[78:93]
	v_cvt_pk_bf16_f32 v54, v36, v37
	v_exp_f32_e32 v37, v42
	v_cvt_pk_bf16_f32 v55, v38, v39
	v_exp_f32_e32 v38, v43
	v_exp_f32_e32 v39, v44
	v_exp_f32_e32 v44, v45
	v_exp_f32_e32 v45, v46
	v_exp_f32_e32 v46, v47
	v_cvt_pk_bf16_f32 v52, v95, v160
	v_cvt_pk_bf16_f32 v53, v60, v61
	v_add_f32_e32 v36, v37, v114
	v_add_f32_e32 v43, v38, v40
	v_add_f32_e32 v40, v39, v41
	v_add_f32_e32 v42, v44, v112
	v_add_f32_e32 v41, v45, v36
	v_add_f32_e32 v43, v46, v43
	v_cvt_pk_bf16_f32 v36, v115, v116
	v_cvt_pk_bf16_f32 v37, v37, v38
	v_cvt_pk_bf16_f32 v38, v39, v44
	v_cvt_pk_bf16_f32 v39, v45, v46
	s_waitcnt lgkmcnt(1)
	v_mfma_f32_32x32x16_bf16 v[78:93], v[32:35], v[108:111], v[78:93]
	s_waitcnt lgkmcnt(0)
	s_barrier
	s_mul_i32 s18, s9, 0x1200
	s_mov_b32 s19, 0
	v_lshl_add_u64 v[32:33], v[132:133], 0, s[18:19]
	global_load_dwordx4 v[112:115], v[32:33], off offset:2048
	global_load_dwordx4 v[116:119], v[136:137], off
	v_add_f32_e64 v32, v40, v42
	v_add_f32_e64 v33, v41, v43
	s_waitcnt vmcnt(4)
	ds_write_b128 v142, v[120:123]
	s_waitcnt vmcnt(3)
	ds_write_b128 v142, v[124:127] offset:8192
	v_mfma_f32_32x32x16_bf16 v[62:77], v[152:155], v[104:107], v[62:77]
	v_add_f32_e32 v32, v32, v33
	v_add_f32_e32 v150, v150, v32
	s_waitcnt lgkmcnt(2)
	v_mfma_f32_32x32x16_bf16 v[62:77], v[156:159], v[108:111], v[62:77]
	ds_read_b128 v[32:35], v144 offset:24576
	ds_read_b128 v[40:43], v144 offset:28672
	ds_read_b128 v[44:47], v141 offset:24576
	ds_read_b128 v[120:123], v141 offset:28672
	v_exp_f32_e32 v60, v78
	s_waitcnt lgkmcnt(3)
	v_mfma_f32_32x32x16_bf16 v[16:31], v[32:35], v[56:59], v[16:31]
	v_exp_f32_e32 v61, v79
	v_exp_f32_e32 v95, v80
	v_exp_f32_e32 v81, v81
	ds_read_b128 v[152:155], v140 offset:24576
	ds_read_b128 v[156:159], v140 offset:28672
	s_waitcnt lgkmcnt(4)
	v_mfma_f32_32x32x16_bf16 v[0:15], v[40:43], v[56:59], v[0:15]
	v_exp_f32_e32 v82, v82
	v_exp_f32_e32 v83, v83
	v_add_f32_e32 v78, v82, v60
	v_add_f32_e32 v79, v83, v61
	s_waitcnt lgkmcnt(2)
	v_mfma_f32_32x32x16_bf16 v[0:15], v[120:123], v[48:51], v[0:15]
	ds_read_b128 v[56:59], v139 offset:24576
	ds_read_b128 v[160:163], v139 offset:28672
	ds_read_b128 v[40:43], v164 offset:16384
	ds_read_b128 v[32:35], v164 offset:20480
	v_cvt_pk_bf16_f32 v82, v82, v83
	v_exp_f32_e32 v151, v62
	v_exp_f32_e32 v64, v64
	v_exp_f32_e32 v65, v65
	v_mfma_f32_32x32x16_bf16 v[16:31], v[44:47], v[48:51], v[16:31]
	v_exp_f32_e32 v44, v84
	v_exp_f32_e32 v45, v85
	v_exp_f32_e32 v84, v86
	v_exp_f32_e32 v85, v87
	v_add_f32_e32 v46, v44, v95
	v_add_f32_e32 v47, v45, v81
	v_add_f32_e32 v48, v84, v78
	s_waitcnt lgkmcnt(4)
	v_mfma_f32_32x32x16_bf16 v[0:15], v[156:159], v[52:55], v[0:15]
	v_add_f32_e32 v49, v85, v79
	v_exp_f32_e32 v78, v88
	v_exp_f32_e32 v79, v89
	v_exp_f32_e32 v87, v92
	v_cvt_pk_bf16_f32 v83, v44, v45
	v_exp_f32_e32 v44, v90
	v_mfma_f32_32x32x16_bf16 v[16:31], v[152:155], v[52:55], v[16:31]
	v_exp_f32_e32 v45, v91
	v_exp_f32_e32 v92, v93
	v_add_f32_e32 v46, v78, v46
	v_add_f32_e32 v47, v79, v47
	ds_read_b128 v[124:127], v165 offset:16384
	ds_read_b128 v[120:123], v165 offset:20480
	s_waitcnt lgkmcnt(4)
	v_mfma_f32_32x32x16_bf16 v[0:15], v[160:163], v[36:39], v[0:15]
	v_exp_f32_e32 v160, v63
	v_cvt_pk_bf16_f32 v80, v60, v61
	v_cvt_pk_bf16_f32 v81, v95, v81
	v_add_f32_e32 v48, v44, v48
	v_add_f32_e32 v49, v45, v49
	v_add_f32_e32 v46, v87, v46
	v_add_f32_e32 v47, v92, v47
	v_mfma_f32_32x32x16_bf16 v[16:31], v[56:59], v[36:39], v[16:31]
	v_add_f32_e32 v161, v151, v48
	v_add_f32_e32 v162, v160, v49
	v_cvt_pk_bf16_f32 v84, v84, v85
	v_cvt_pk_bf16_f32 v85, v78, v79
	v_cvt_pk_bf16_f32 v86, v44, v45
	v_add_f32_e32 v78, v64, v46
	v_add_f32_e32 v79, v65, v47
	s_waitcnt lgkmcnt(3)
	v_mfma_f32_32x32x16_bf16 v[48:63], v[40:43], v[96:99], 0
	ds_read_b128 v[88:91], v166 offset:16384
	ds_read_b128 v[152:155], v166 offset:20480
	v_exp_f32_e32 v66, v66
	v_exp_f32_e32 v67, v67
	v_exp_f32_e32 v68, v68
	v_exp_f32_e32 v69, v69
	v_cvt_pk_bf16_f32 v87, v87, v92
	s_waitcnt lgkmcnt(4)
	v_mfma_f32_32x32x16_bf16 v[32:47], v[32:35], v[96:99], 0
	ds_read_b128 v[156:159], v167 offset:16384
	ds_read_b128 v[92:95], v167 offset:20480
	v_add_f32_e32 v161, v66, v161
	v_add_f32_e32 v162, v67, v162
	v_add_f32_e32 v78, v68, v78
	v_add_f32_e32 v79, v69, v79
	s_waitcnt lgkmcnt(5)
	v_mfma_f32_32x32x16_bf16 v[48:63], v[124:127], v[100:103], v[48:63]
	v_exp_f32_e32 v70, v70
	v_exp_f32_e32 v71, v71
	s_add_i32 s9, s3, 2
	s_add_i32 s3, s3, -2
	v_lshl_add_u64 v[136:137], v[136:137], 0, s[22:23]
	s_waitcnt lgkmcnt(4)
	v_mfma_f32_32x32x16_bf16 v[32:47], v[120:123], v[100:103], v[32:47]
	v_add_f32_e32 v120, v70, v161
	v_add_f32_e32 v121, v71, v162
	s_cmp_lt_u32 s3, s2
	s_mov_b32 s3, s9
	s_waitcnt lgkmcnt(3)
	v_mfma_f32_32x32x16_bf16 v[48:63], v[88:91], v[104:107], v[48:63]
	v_cvt_pk_bf16_f32 v91, v68, v69
	v_exp_f32_e32 v68, v72
	v_exp_f32_e32 v69, v73
	v_exp_f32_e32 v72, v74
	v_exp_f32_e32 v73, v75
	v_exp_f32_e32 v74, v76
	v_exp_f32_e32 v75, v77
	s_waitcnt lgkmcnt(2)
	v_mfma_f32_32x32x16_bf16 v[32:47], v[152:155], v[104:107], v[32:47]
	v_cvt_pk_bf16_f32 v88, v151, v160
	v_cvt_pk_bf16_f32 v89, v64, v65
	v_cvt_pk_bf16_f32 v90, v66, v67
	v_add_f32_e32 v65, v68, v78
	v_add_f32_e32 v67, v69, v79
	s_waitcnt lgkmcnt(1)
	v_mfma_f32_32x32x16_bf16 v[48:63], v[156:159], v[108:111], v[48:63]
	v_add_f32_e32 v64, v72, v120
	v_add_f32_e32 v66, v73, v121
	v_add_f32_e32 v65, v74, v65
	v_add_f32_e32 v67, v75, v67
	s_waitcnt lgkmcnt(0)
	v_mfma_f32_32x32x16_bf16 v[32:47], v[92:95], v[108:111], v[32:47]
	v_cvt_pk_bf16_f32 v92, v70, v71
	v_cvt_pk_bf16_f32 v93, v68, v69
	v_cvt_pk_bf16_f32 v94, v72, v73
	v_cvt_pk_bf16_f32 v95, v74, v75
	v_add_f32_e64 v64, v64, v66
	v_add_f32_e64 v65, v65, v67
	s_waitcnt lgkmcnt(0)
	s_barrier
	v_add_f32_e32 v64, v64, v65
	v_add_f32_e32 v150, v150, v64
.Lpeel_10:
	s_add_i32 s9, s3, -1
	s_min_u32 s9, s9, s2
	s_lshl_b32 s9, s9, 6
	s_waitcnt vmcnt(1)
	ds_write_b128 v142, v[112:115] offset:16384
	s_waitcnt vmcnt(0)
	ds_write_b128 v142, v[116:119] offset:24576
	s_mul_i32 s18, s9, 0x1200
	s_mov_b32 s19, 0
	v_lshl_add_u64 v[64:65], v[132:133], 0, s[18:19]
	global_load_dwordx4 v[120:123], v[64:65], off offset:2048
	global_load_dwordx4 v[124:127], v[136:137], off offset:-128
	ds_read_b128 v[64:67], v144 offset:8192
	ds_read_b128 v[68:71], v144 offset:12288
	ds_read_b128 v[72:75], v141 offset:8192
	ds_read_b128 v[76:79], v141 offset:12288
	v_exp_f32_e32 v151, v48
	v_exp_f32_e32 v152, v49
	s_waitcnt lgkmcnt(3)
	v_mfma_f32_32x32x16_bf16 v[16:31], v[64:67], v[80:83], v[16:31]
	v_exp_f32_e32 v153, v50
	v_exp_f32_e32 v154, v51
	ds_read_b128 v[48:51], v140 offset:8192
	ds_read_b128 v[64:67], v140 offset:12288
	v_exp_f32_e32 v155, v52
	s_waitcnt lgkmcnt(4)
	v_mfma_f32_32x32x16_bf16 v[0:15], v[68:71], v[80:83], v[0:15]
	v_exp_f32_e32 v156, v53
	v_exp_f32_e32 v159, v54
	v_exp_f32_e32 v160, v55
	v_exp_f32_e32 v162, v57
	s_waitcnt lgkmcnt(3)
	v_mfma_f32_32x32x16_bf16 v[16:31], v[72:75], v[84:87], v[16:31]
	ds_read_b128 v[68:71], v139 offset:8192
	ds_read_b128 v[80:83], v139 offset:12288
	v_add_f32_e32 v157, v155, v151
	v_add_f32_e32 v158, v156, v152
	ds_read_b128 v[52:55], v164
	ds_read_b128 v[72:75], v164 offset:4096
	v_add_f32_e32 v161, v159, v153
	s_waitcnt lgkmcnt(6)
	v_mfma_f32_32x32x16_bf16 v[0:15], v[76:79], v[84:87], v[0:15]
	v_exp_f32_e32 v77, v56
	v_add_f32_e32 v76, v160, v154
	v_exp_f32_e32 v62, v62
	ds_read_b128 v[112:115], v165
	ds_read_b128 v[116:119], v165 offset:4096
	v_cvt_pk_bf16_f32 v56, v151, v152
	s_waitcnt lgkmcnt(7)
	v_mfma_f32_32x32x16_bf16 v[16:31], v[48:51], v[88:91], v[16:31]
	v_exp_f32_e32 v49, v58
	v_exp_f32_e32 v50, v59
	v_add_f32_e32 v48, v77, v157
	v_add_f32_e32 v51, v162, v158
	v_add_f32_e32 v78, v49, v161
	v_add_f32_e32 v76, v50, v76
	s_waitcnt lgkmcnt(6)
	v_mfma_f32_32x32x16_bf16 v[0:15], v[64:67], v[88:91], v[0:15]
	v_exp_f32_e32 v60, v60
	v_add_f32_e32 v151, v62, v78
	v_exp_f32_e32 v61, v61
	v_exp_f32_e32 v63, v63
	v_cvt_pk_bf16_f32 v59, v159, v160
	v_exp_f32_e32 v160, v33
	s_waitcnt lgkmcnt(5)
	v_mfma_f32_32x32x16_bf16 v[16:31], v[68:71], v[92:95], v[16:31]
	v_cvt_pk_bf16_f32 v57, v153, v154
	v_cvt_pk_bf16_f32 v58, v155, v156
	v_add_f32_e32 v48, v60, v48
	v_add_f32_e32 v51, v61, v51
	v_cvt_pk_bf16_f32 v49, v49, v50
	s_waitcnt lgkmcnt(4)
	v_mfma_f32_32x32x16_bf16 v[0:15], v[80:83], v[92:95], v[0:15]
	v_readfirstlane_b32 s18, v171
	s_add_u32 vcc_lo, s34, 0x90000
	s_addc_u32 vcc_hi, s35, 0
	s_add_u32 m0, s18, 0x1b800
	s_nop 0
	global_load_lds_dwordx4 v170, vcc offset:2048
	v_exp_f32_e32 v95, v32
	v_add_f32_e32 v32, v63, v76
	v_add_f32_e32 v163, v160, v51
	v_add_f32_e32 v161, v95, v48
	v_cvt_pk_bf16_f32 v48, v77, v162
	v_cvt_pk_bf16_f32 v51, v62, v63
	s_waitcnt lgkmcnt(3)
	v_mfma_f32_32x32x16_bf16 v[78:93], v[52:55], v[96:99], 0
	v_cvt_pk_bf16_f32 v50, v60, v61
	v_exp_f32_e32 v60, v34
	v_exp_f32_e32 v61, v35
	v_exp_f32_e32 v36, v36
	v_exp_f32_e32 v37, v37
	v_exp_f32_e32 v38, v38
	v_exp_f32_e32 v39, v39
	s_waitcnt lgkmcnt(2)
	v_mfma_f32_32x32x16_bf16 v[62:77], v[72:75], v[96:99], 0
	ds_read_b128 v[52:55], v166
	ds_read_b128 v[152:155], v166 offset:4096
	v_add_f32_e32 v151, v60, v151
	v_add_f32_e32 v162, v61, v32
	s_waitcnt lgkmcnt(3)
	v_mfma_f32_32x32x16_bf16 v[78:93], v[112:115], v[100:103], v[78:93]
	v_add_f32_e32 v112, v36, v161
	v_add_f32_e32 v113, v37, v163
	v_add_f32_e32 v114, v38, v151
	v_exp_f32_e32 v115, v40
	v_add_f32_e32 v40, v39, v162
	ds_read_b128 v[32:35], v167
	ds_read_b128 v[156:159], v167 offset:4096
	s_waitcnt lgkmcnt(4)
	v_mfma_f32_32x32x16_bf16 v[62:77], v[116:119], v[100:103], v[62:77]
	v_exp_f32_e32 v116, v41
	v_add_f32_e32 v41, v115, v112
	s_min_u32 s9, s3, s2
	s_lshl_b32 s9, s9, 6
	v_add_f32_e32 v112, v116, v113
	s_waitcnt lgkmcnt(3)
	v_mfma_f32_32x32x16_bf16 v[78:93], v[52:55], v[104:107], v[78:93]
	v_cvt_pk_bf16_f32 v54, v36, v37
	v_exp_f32_e32 v37, v42
	v_cvt_pk_bf16_f32 v55, v38, v39
	v_exp_f32_e32 v38, v43
	v_exp_f32_e32 v39, v44
	v_exp_f32_e32 v44, v45
	v_exp_f32_e32 v45, v46
	v_exp_f32_e32 v46, v47
	v_cvt_pk_bf16_f32 v52, v95, v160
	v_cvt_pk_bf16_f32 v53, v60, v61
	v_add_f32_e32 v36, v37, v114
	v_add_f32_e32 v43, v38, v40
	v_add_f32_e32 v40, v39, v41
	v_add_f32_e32 v42, v44, v112
	v_add_f32_e32 v41, v45, v36
	v_add_f32_e32 v43, v46, v43
	v_cvt_pk_bf16_f32 v36, v115, v116
	v_cvt_pk_bf16_f32 v37, v37, v38
	v_cvt_pk_bf16_f32 v38, v39, v44
	v_cvt_pk_bf16_f32 v39, v45, v46
	s_waitcnt lgkmcnt(1)
	v_mfma_f32_32x32x16_bf16 v[78:93], v[32:35], v[108:111], v[78:93]
	s_waitcnt lgkmcnt(0)
	s_barrier
	s_mul_i32 s18, s9, 0x1200
	s_mov_b32 s19, 0
	v_lshl_add_u64 v[32:33], v[132:133], 0, s[18:19]
	global_load_dwordx4 v[112:115], v[32:33], off offset:2048
	global_load_dwordx4 v[116:119], v[136:137], off
	v_add_f32_e64 v32, v40, v42
	v_add_f32_e64 v33, v41, v43
	s_waitcnt vmcnt(4)
	ds_write_b128 v142, v[120:123]
	s_waitcnt vmcnt(3)
	ds_write_b128 v142, v[124:127] offset:8192
	v_mfma_f32_32x32x16_bf16 v[62:77], v[152:155], v[104:107], v[62:77]
	v_add_f32_e32 v32, v32, v33
	v_add_f32_e32 v150, v150, v32
	s_waitcnt lgkmcnt(2)
	v_mfma_f32_32x32x16_bf16 v[62:77], v[156:159], v[108:111], v[62:77]
	ds_read_b128 v[32:35], v144 offset:24576
	ds_read_b128 v[40:43], v144 offset:28672
	ds_read_b128 v[44:47], v141 offset:24576
	ds_read_b128 v[120:123], v141 offset:28672
	v_exp_f32_e32 v60, v78
	s_waitcnt lgkmcnt(3)
	v_mfma_f32_32x32x16_bf16 v[16:31], v[32:35], v[56:59], v[16:31]
	v_exp_f32_e32 v61, v79
	v_exp_f32_e32 v95, v80
	v_exp_f32_e32 v81, v81
	ds_read_b128 v[152:155], v140 offset:24576
	ds_read_b128 v[156:159], v140 offset:28672
	s_waitcnt lgkmcnt(4)
	v_mfma_f32_32x32x16_bf16 v[0:15], v[40:43], v[56:59], v[0:15]
	v_exp_f32_e32 v82, v82
	v_exp_f32_e32 v83, v83
	v_add_f32_e32 v78, v82, v60
	v_add_f32_e32 v79, v83, v61
	s_waitcnt lgkmcnt(2)
	v_mfma_f32_32x32x16_bf16 v[0:15], v[120:123], v[48:51], v[0:15]
	ds_read_b128 v[56:59], v139 offset:24576
	ds_read_b128 v[160:163], v139 offset:28672
	ds_read_b128 v[40:43], v164 offset:16384
	ds_read_b128 v[32:35], v164 offset:20480
	v_cvt_pk_bf16_f32 v82, v82, v83
	v_exp_f32_e32 v151, v62
	v_exp_f32_e32 v64, v64
	v_exp_f32_e32 v65, v65
	v_mfma_f32_32x32x16_bf16 v[16:31], v[44:47], v[48:51], v[16:31]
	v_exp_f32_e32 v44, v84
	v_exp_f32_e32 v45, v85
	v_exp_f32_e32 v84, v86
	v_exp_f32_e32 v85, v87
	v_add_f32_e32 v46, v44, v95
	v_add_f32_e32 v47, v45, v81
	v_add_f32_e32 v48, v84, v78
	s_waitcnt lgkmcnt(4)
	v_mfma_f32_32x32x16_bf16 v[0:15], v[156:159], v[52:55], v[0:15]
	v_add_f32_e32 v49, v85, v79
	v_exp_f32_e32 v78, v88
	v_exp_f32_e32 v79, v89
	v_exp_f32_e32 v87, v92
	v_cvt_pk_bf16_f32 v83, v44, v45
	v_exp_f32_e32 v44, v90
	v_mfma_f32_32x32x16_bf16 v[16:31], v[152:155], v[52:55], v[16:31]
	v_exp_f32_e32 v45, v91
	v_exp_f32_e32 v92, v93
	v_add_f32_e32 v46, v78, v46
	v_add_f32_e32 v47, v79, v47
	ds_read_b128 v[124:127], v165 offset:16384
	ds_read_b128 v[120:123], v165 offset:20480
	s_waitcnt lgkmcnt(4)
	v_mfma_f32_32x32x16_bf16 v[0:15], v[160:163], v[36:39], v[0:15]
	v_exp_f32_e32 v160, v63
	v_cvt_pk_bf16_f32 v80, v60, v61
	v_cvt_pk_bf16_f32 v81, v95, v81
	v_add_f32_e32 v48, v44, v48
	v_add_f32_e32 v49, v45, v49
	v_add_f32_e32 v46, v87, v46
	v_add_f32_e32 v47, v92, v47
	v_mfma_f32_32x32x16_bf16 v[16:31], v[56:59], v[36:39], v[16:31]
	v_add_f32_e32 v161, v151, v48
	v_add_f32_e32 v162, v160, v49
	v_cvt_pk_bf16_f32 v84, v84, v85
	v_cvt_pk_bf16_f32 v85, v78, v79
	v_cvt_pk_bf16_f32 v86, v44, v45
	v_add_f32_e32 v78, v64, v46
	v_add_f32_e32 v79, v65, v47
	s_waitcnt lgkmcnt(3)
	v_mfma_f32_32x32x16_bf16 v[48:63], v[40:43], v[96:99], 0
	ds_read_b128 v[88:91], v166 offset:16384
	ds_read_b128 v[152:155], v166 offset:20480
	v_exp_f32_e32 v66, v66
	v_exp_f32_e32 v67, v67
	v_exp_f32_e32 v68, v68
	v_exp_f32_e32 v69, v69
	v_cvt_pk_bf16_f32 v87, v87, v92
	s_waitcnt lgkmcnt(4)
	v_mfma_f32_32x32x16_bf16 v[32:47], v[32:35], v[96:99], 0
	ds_read_b128 v[156:159], v167 offset:16384
	ds_read_b128 v[92:95], v167 offset:20480
	v_add_f32_e32 v161, v66, v161
	v_add_f32_e32 v162, v67, v162
	v_add_f32_e32 v78, v68, v78
	v_add_f32_e32 v79, v69, v79
	s_waitcnt lgkmcnt(5)
	v_mfma_f32_32x32x16_bf16 v[48:63], v[124:127], v[100:103], v[48:63]
	v_exp_f32_e32 v70, v70
	v_exp_f32_e32 v71, v71
	s_add_i32 s9, s3, 2
	s_add_i32 s3, s3, -2
	v_lshl_add_u64 v[136:137], v[136:137], 0, s[22:23]
	s_waitcnt lgkmcnt(4)
	v_mfma_f32_32x32x16_bf16 v[32:47], v[120:123], v[100:103], v[32:47]
	v_add_f32_e32 v120, v70, v161
	v_add_f32_e32 v121, v71, v162
	s_cmp_lt_u32 s3, s2
	s_mov_b32 s3, s9
	s_waitcnt lgkmcnt(3)
	v_mfma_f32_32x32x16_bf16 v[48:63], v[88:91], v[104:107], v[48:63]
	v_cvt_pk_bf16_f32 v91, v68, v69
	v_exp_f32_e32 v68, v72
	v_exp_f32_e32 v69, v73
	v_exp_f32_e32 v72, v74
	v_exp_f32_e32 v73, v75
	v_exp_f32_e32 v74, v76
	v_exp_f32_e32 v75, v77
	s_waitcnt lgkmcnt(2)
	v_mfma_f32_32x32x16_bf16 v[32:47], v[152:155], v[104:107], v[32:47]
	v_cvt_pk_bf16_f32 v88, v151, v160
	v_cvt_pk_bf16_f32 v89, v64, v65
	v_cvt_pk_bf16_f32 v90, v66, v67
	v_add_f32_e32 v65, v68, v78
	v_add_f32_e32 v67, v69, v79
	s_waitcnt lgkmcnt(1)
	v_mfma_f32_32x32x16_bf16 v[48:63], v[156:159], v[108:111], v[48:63]
	v_add_f32_e32 v64, v72, v120
	v_add_f32_e32 v66, v73, v121
	v_add_f32_e32 v65, v74, v65
	v_add_f32_e32 v67, v75, v67
	s_waitcnt lgkmcnt(0)
	v_mfma_f32_32x32x16_bf16 v[32:47], v[92:95], v[108:111], v[32:47]
	v_cvt_pk_bf16_f32 v92, v70, v71
	v_cvt_pk_bf16_f32 v93, v68, v69
	v_cvt_pk_bf16_f32 v94, v72, v73
	v_cvt_pk_bf16_f32 v95, v74, v75
	v_add_f32_e64 v64, v64, v66
	v_add_f32_e64 v65, v65, v67
	s_waitcnt lgkmcnt(0)
	s_barrier
	v_add_f32_e32 v64, v64, v65
	v_add_f32_e32 v150, v150, v64
.Lpeel_11:
	s_add_i32 s9, s3, -1
	s_min_u32 s9, s9, s2
	s_lshl_b32 s9, s9, 6
	s_waitcnt vmcnt(1)
	ds_write_b128 v142, v[112:115] offset:16384
	s_waitcnt vmcnt(0)
	ds_write_b128 v142, v[116:119] offset:24576
	s_mul_i32 s18, s9, 0x1200
	s_mov_b32 s19, 0
	v_lshl_add_u64 v[64:65], v[132:133], 0, s[18:19]
	global_load_dwordx4 v[120:123], v[64:65], off offset:2048
	global_load_dwordx4 v[124:127], v[136:137], off offset:-128
	ds_read_b128 v[64:67], v144 offset:8192
	ds_read_b128 v[68:71], v144 offset:12288
	ds_read_b128 v[72:75], v141 offset:8192
	ds_read_b128 v[76:79], v141 offset:12288
	v_exp_f32_e32 v151, v48
	v_exp_f32_e32 v152, v49
	s_waitcnt lgkmcnt(3)
	v_mfma_f32_32x32x16_bf16 v[16:31], v[64:67], v[80:83], v[16:31]
	v_exp_f32_e32 v153, v50
	v_exp_f32_e32 v154, v51
	ds_read_b128 v[48:51], v140 offset:8192
	ds_read_b128 v[64:67], v140 offset:12288
	v_exp_f32_e32 v155, v52
	s_waitcnt lgkmcnt(4)
	v_mfma_f32_32x32x16_bf16 v[0:15], v[68:71], v[80:83], v[0:15]
	v_exp_f32_e32 v156, v53
	v_exp_f32_e32 v159, v54
	v_exp_f32_e32 v160, v55
	v_exp_f32_e32 v162, v57
	s_waitcnt lgkmcnt(3)
	v_mfma_f32_32x32x16_bf16 v[16:31], v[72:75], v[84:87], v[16:31]
	ds_read_b128 v[68:71], v139 offset:8192
	ds_read_b128 v[80:83], v139 offset:12288
	v_add_f32_e32 v157, v155, v151
	v_add_f32_e32 v158, v156, v152
	ds_read_b128 v[52:55], v164
	ds_read_b128 v[72:75], v164 offset:4096
	v_add_f32_e32 v161, v159, v153
	s_waitcnt lgkmcnt(6)
	v_mfma_f32_32x32x16_bf16 v[0:15], v[76:79], v[84:87], v[0:15]
	v_exp_f32_e32 v77, v56
	v_add_f32_e32 v76, v160, v154
	v_exp_f32_e32 v62, v62
	ds_read_b128 v[112:115], v165
	ds_read_b128 v[116:119], v165 offset:4096
	v_cvt_pk_bf16_f32 v56, v151, v152
	s_waitcnt lgkmcnt(7)
	v_mfma_f32_32x32x16_bf16 v[16:31], v[48:51], v[88:91], v[16:31]
	v_exp_f32_e32 v49, v58
	v_exp_f32_e32 v50, v59
	v_add_f32_e32 v48, v77, v157
	v_add_f32_e32 v51, v162, v158
	v_add_f32_e32 v78, v49, v161
	v_add_f32_e32 v76, v50, v76
	s_waitcnt lgkmcnt(6)
	v_mfma_f32_32x32x16_bf16 v[0:15], v[64:67], v[88:91], v[0:15]
	v_exp_f32_e32 v60, v60
	v_add_f32_e32 v151, v62, v78
	v_exp_f32_e32 v61, v61
	v_exp_f32_e32 v63, v63
	v_cvt_pk_bf16_f32 v59, v159, v160
	v_exp_f32_e32 v160, v33
	s_waitcnt lgkmcnt(5)
	v_mfma_f32_32x32x16_bf16 v[16:31], v[68:71], v[92:95], v[16:31]
	v_cvt_pk_bf16_f32 v57, v153, v154
	v_cvt_pk_bf16_f32 v58, v155, v156
	v_add_f32_e32 v48, v60, v48
	v_add_f32_e32 v51, v61, v51
	v_cvt_pk_bf16_f32 v49, v49, v50
	s_waitcnt lgkmcnt(4)
	v_mfma_f32_32x32x16_bf16 v[0:15], v[80:83], v[92:95], v[0:15]
	v_readfirstlane_b32 s18, v171
	s_add_u32 m0, s18, 0x1e000
	s_nop 0
	global_load_lds_dwordx4 v169, s[10:11]
	v_exp_f32_e32 v95, v32
	v_add_f32_e32 v32, v63, v76
	v_add_f32_e32 v163, v160, v51
	v_add_f32_e32 v161, v95, v48
	v_cvt_pk_bf16_f32 v48, v77, v162
	v_cvt_pk_bf16_f32 v51, v62, v63
	s_waitcnt lgkmcnt(3)
	v_mfma_f32_32x32x16_bf16 v[78:93], v[52:55], v[96:99], 0
	v_cvt_pk_bf16_f32 v50, v60, v61
	v_exp_f32_e32 v60, v34
	v_exp_f32_e32 v61, v35
	v_exp_f32_e32 v36, v36
	v_exp_f32_e32 v37, v37
	v_exp_f32_e32 v38, v38
	v_exp_f32_e32 v39, v39
	s_waitcnt lgkmcnt(2)
	v_mfma_f32_32x32x16_bf16 v[62:77], v[72:75], v[96:99], 0
	ds_read_b128 v[52:55], v166
	ds_read_b128 v[152:155], v166 offset:4096
	v_add_f32_e32 v151, v60, v151
	v_add_f32_e32 v162, v61, v32
	s_waitcnt lgkmcnt(3)
	v_mfma_f32_32x32x16_bf16 v[78:93], v[112:115], v[100:103], v[78:93]
	v_add_f32_e32 v112, v36, v161
	v_add_f32_e32 v113, v37, v163
	v_add_f32_e32 v114, v38, v151
	v_exp_f32_e32 v115, v40
	v_add_f32_e32 v40, v39, v162
	ds_read_b128 v[32:35], v167
	ds_read_b128 v[156:159], v167 offset:4096
	s_waitcnt lgkmcnt(4)
	v_mfma_f32_32x32x16_bf16 v[62:77], v[116:119], v[100:103], v[62:77]
	v_exp_f32_e32 v116, v41
	v_add_f32_e32 v41, v115, v112
	s_min_u32 s9, s3, s2
	s_lshl_b32 s9, s9, 6
	v_add_f32_e32 v112, v116, v113
	s_waitcnt lgkmcnt(3)
	v_mfma_f32_32x32x16_bf16 v[78:93], v[52:55], v[104:107], v[78:93]
	v_cvt_pk_bf16_f32 v54, v36, v37
	v_exp_f32_e32 v37, v42
	v_cvt_pk_bf16_f32 v55, v38, v39
	v_exp_f32_e32 v38, v43
	v_exp_f32_e32 v39, v44
	v_exp_f32_e32 v44, v45
	v_exp_f32_e32 v45, v46
	v_exp_f32_e32 v46, v47
	v_cvt_pk_bf16_f32 v52, v95, v160
	v_cvt_pk_bf16_f32 v53, v60, v61
	v_add_f32_e32 v36, v37, v114
	v_add_f32_e32 v43, v38, v40
	v_add_f32_e32 v40, v39, v41
	v_add_f32_e32 v42, v44, v112
	v_add_f32_e32 v41, v45, v36
	v_add_f32_e32 v43, v46, v43
	v_cvt_pk_bf16_f32 v36, v115, v116
	v_cvt_pk_bf16_f32 v37, v37, v38
	v_cvt_pk_bf16_f32 v38, v39, v44
	v_cvt_pk_bf16_f32 v39, v45, v46
	s_waitcnt lgkmcnt(1)
	v_mfma_f32_32x32x16_bf16 v[78:93], v[32:35], v[108:111], v[78:93]
	s_waitcnt lgkmcnt(0)
	s_barrier
	s_mul_i32 s18, s9, 0x1200
	s_mov_b32 s19, 0
	v_lshl_add_u64 v[32:33], v[132:133], 0, s[18:19]
	global_load_dwordx4 v[112:115], v[32:33], off offset:2048
	global_load_dwordx4 v[116:119], v[136:137], off
	v_add_f32_e64 v32, v40, v42
	v_add_f32_e64 v33, v41, v43
	s_waitcnt vmcnt(4)
	ds_write_b128 v142, v[120:123]
	s_waitcnt vmcnt(3)
	ds_write_b128 v142, v[124:127] offset:8192
	v_mfma_f32_32x32x16_bf16 v[62:77], v[152:155], v[104:107], v[62:77]
	v_add_f32_e32 v32, v32, v33
	v_add_f32_e32 v150, v150, v32
	s_waitcnt lgkmcnt(2)
	v_mfma_f32_32x32x16_bf16 v[62:77], v[156:159], v[108:111], v[62:77]
	ds_read_b128 v[32:35], v144 offset:24576
	ds_read_b128 v[40:43], v144 offset:28672
	ds_read_b128 v[44:47], v141 offset:24576
	ds_read_b128 v[120:123], v141 offset:28672
	v_exp_f32_e32 v60, v78
	s_waitcnt lgkmcnt(3)
	v_mfma_f32_32x32x16_bf16 v[16:31], v[32:35], v[56:59], v[16:31]
	v_exp_f32_e32 v61, v79
	v_exp_f32_e32 v95, v80
	v_exp_f32_e32 v81, v81
	ds_read_b128 v[152:155], v140 offset:24576
	ds_read_b128 v[156:159], v140 offset:28672
	s_waitcnt lgkmcnt(4)
	v_mfma_f32_32x32x16_bf16 v[0:15], v[40:43], v[56:59], v[0:15]
	v_exp_f32_e32 v82, v82
	v_exp_f32_e32 v83, v83
	v_add_f32_e32 v78, v82, v60
	v_add_f32_e32 v79, v83, v61
	s_waitcnt lgkmcnt(2)
	v_mfma_f32_32x32x16_bf16 v[0:15], v[120:123], v[48:51], v[0:15]
	ds_read_b128 v[56:59], v139 offset:24576
	ds_read_b128 v[160:163], v139 offset:28672
	ds_read_b128 v[40:43], v164 offset:16384
	ds_read_b128 v[32:35], v164 offset:20480
	v_cvt_pk_bf16_f32 v82, v82, v83
	v_exp_f32_e32 v151, v62
	v_exp_f32_e32 v64, v64
	v_exp_f32_e32 v65, v65
	v_mfma_f32_32x32x16_bf16 v[16:31], v[44:47], v[48:51], v[16:31]
	v_exp_f32_e32 v44, v84
	v_exp_f32_e32 v45, v85
	v_exp_f32_e32 v84, v86
	v_exp_f32_e32 v85, v87
	v_add_f32_e32 v46, v44, v95
	v_add_f32_e32 v47, v45, v81
	v_add_f32_e32 v48, v84, v78
	s_waitcnt lgkmcnt(4)
	v_mfma_f32_32x32x16_bf16 v[0:15], v[156:159], v[52:55], v[0:15]
	v_add_f32_e32 v49, v85, v79
	v_exp_f32_e32 v78, v88
	v_exp_f32_e32 v79, v89
	v_exp_f32_e32 v87, v92
	v_cvt_pk_bf16_f32 v83, v44, v45
	v_exp_f32_e32 v44, v90
	v_mfma_f32_32x32x16_bf16 v[16:31], v[152:155], v[52:55], v[16:31]
	v_exp_f32_e32 v45, v91
	v_exp_f32_e32 v92, v93
	v_add_f32_e32 v46, v78, v46
	v_add_f32_e32 v47, v79, v47
	ds_read_b128 v[124:127], v165 offset:16384
	ds_read_b128 v[120:123], v165 offset:20480
	s_waitcnt lgkmcnt(4)
	v_mfma_f32_32x32x16_bf16 v[0:15], v[160:163], v[36:39], v[0:15]
	v_exp_f32_e32 v160, v63
	v_cvt_pk_bf16_f32 v80, v60, v61
	v_cvt_pk_bf16_f32 v81, v95, v81
	v_add_f32_e32 v48, v44, v48
	v_add_f32_e32 v49, v45, v49
	v_add_f32_e32 v46, v87, v46
	v_add_f32_e32 v47, v92, v47
	v_mfma_f32_32x32x16_bf16 v[16:31], v[56:59], v[36:39], v[16:31]
	v_add_f32_e32 v161, v151, v48
	v_add_f32_e32 v162, v160, v49
	v_cvt_pk_bf16_f32 v84, v84, v85
	v_cvt_pk_bf16_f32 v85, v78, v79
	v_cvt_pk_bf16_f32 v86, v44, v45
	v_add_f32_e32 v78, v64, v46
	v_add_f32_e32 v79, v65, v47
	s_waitcnt lgkmcnt(3)
	v_mfma_f32_32x32x16_bf16 v[48:63], v[40:43], v[96:99], 0
	ds_read_b128 v[88:91], v166 offset:16384
	ds_read_b128 v[152:155], v166 offset:20480
	v_exp_f32_e32 v66, v66
	v_exp_f32_e32 v67, v67
	v_exp_f32_e32 v68, v68
	v_exp_f32_e32 v69, v69
	v_cvt_pk_bf16_f32 v87, v87, v92
	s_waitcnt lgkmcnt(4)
	v_mfma_f32_32x32x16_bf16 v[32:47], v[32:35], v[96:99], 0
	ds_read_b128 v[156:159], v167 offset:16384
	ds_read_b128 v[92:95], v167 offset:20480
	v_add_f32_e32 v161, v66, v161
	v_add_f32_e32 v162, v67, v162
	v_add_f32_e32 v78, v68, v78
	v_add_f32_e32 v79, v69, v79
	s_waitcnt lgkmcnt(5)
	v_mfma_f32_32x32x16_bf16 v[48:63], v[124:127], v[100:103], v[48:63]
	v_exp_f32_e32 v70, v70
	v_exp_f32_e32 v71, v71
	s_add_i32 s9, s3, 2
	s_add_i32 s3, s3, -2
	v_lshl_add_u64 v[136:137], v[136:137], 0, s[22:23]
	s_waitcnt lgkmcnt(4)
	v_mfma_f32_32x32x16_bf16 v[32:47], v[120:123], v[100:103], v[32:47]
	v_add_f32_e32 v120, v70, v161
	v_add_f32_e32 v121, v71, v162
	s_cmp_lt_u32 s3, s2
	s_mov_b32 s3, s9
	s_waitcnt lgkmcnt(3)
	v_mfma_f32_32x32x16_bf16 v[48:63], v[88:91], v[104:107], v[48:63]
	v_cvt_pk_bf16_f32 v91, v68, v69
	v_exp_f32_e32 v68, v72
	v_exp_f32_e32 v69, v73
	v_exp_f32_e32 v72, v74
	v_exp_f32_e32 v73, v75
	v_exp_f32_e32 v74, v76
	v_exp_f32_e32 v75, v77
	s_waitcnt lgkmcnt(2)
	v_mfma_f32_32x32x16_bf16 v[32:47], v[152:155], v[104:107], v[32:47]
	v_cvt_pk_bf16_f32 v88, v151, v160
	v_cvt_pk_bf16_f32 v89, v64, v65
	v_cvt_pk_bf16_f32 v90, v66, v67
	v_add_f32_e32 v65, v68, v78
	v_add_f32_e32 v67, v69, v79
	s_waitcnt lgkmcnt(1)
	v_mfma_f32_32x32x16_bf16 v[48:63], v[156:159], v[108:111], v[48:63]
	v_add_f32_e32 v64, v72, v120
	v_add_f32_e32 v66, v73, v121
	v_add_f32_e32 v65, v74, v65
	v_add_f32_e32 v67, v75, v67
	s_waitcnt lgkmcnt(0)
	v_mfma_f32_32x32x16_bf16 v[32:47], v[92:95], v[108:111], v[32:47]
	v_cvt_pk_bf16_f32 v92, v70, v71
	v_cvt_pk_bf16_f32 v93, v68, v69
	v_cvt_pk_bf16_f32 v94, v72, v73
	v_cvt_pk_bf16_f32 v95, v74, v75
	v_add_f32_e64 v64, v64, v66
	v_add_f32_e64 v65, v65, v67
	s_waitcnt lgkmcnt(0)
	s_barrier
	v_add_f32_e32 v64, v64, v65
	v_add_f32_e32 v150, v150, v64
.LBB0_898:
	s_add_i32 s9, s3, -1
	s_min_u32 s9, s9, s2
	s_lshl_b32 s9, s9, 6
	s_waitcnt vmcnt(1)
	ds_write_b128 v142, v[112:115] offset:16384
	s_waitcnt vmcnt(0)
	ds_write_b128 v142, v[116:119] offset:24576
	s_mul_i32 s18, s9, 0x1200
	s_mov_b32 s19, 0
	v_lshl_add_u64 v[64:65], v[132:133], 0, s[18:19]
	global_load_dwordx4 v[120:123], v[64:65], off offset:2048
	global_load_dwordx4 v[124:127], v[136:137], off offset:-128
	ds_read_b128 v[64:67], v144 offset:8192
	ds_read_b128 v[68:71], v144 offset:12288
	ds_read_b128 v[72:75], v141 offset:8192
	ds_read_b128 v[76:79], v141 offset:12288
	v_exp_f32_e32 v151, v48
	v_exp_f32_e32 v152, v49
	s_waitcnt lgkmcnt(3)
	v_mfma_f32_32x32x16_bf16 v[16:31], v[64:67], v[80:83], v[16:31]
	v_exp_f32_e32 v153, v50
	v_exp_f32_e32 v154, v51
	ds_read_b128 v[48:51], v140 offset:8192
	ds_read_b128 v[64:67], v140 offset:12288
	v_exp_f32_e32 v155, v52
	s_waitcnt lgkmcnt(4)
	v_mfma_f32_32x32x16_bf16 v[0:15], v[68:71], v[80:83], v[0:15]
	v_exp_f32_e32 v156, v53
	v_exp_f32_e32 v159, v54
	v_exp_f32_e32 v160, v55
	v_exp_f32_e32 v162, v57
	s_waitcnt lgkmcnt(3)
	v_mfma_f32_32x32x16_bf16 v[16:31], v[72:75], v[84:87], v[16:31]
	ds_read_b128 v[68:71], v139 offset:8192
	ds_read_b128 v[80:83], v139 offset:12288
	v_add_f32_e32 v157, v155, v151
	v_add_f32_e32 v158, v156, v152
	ds_read_b128 v[52:55], v164
	ds_read_b128 v[72:75], v164 offset:4096
	v_add_f32_e32 v161, v159, v153
	s_waitcnt lgkmcnt(6)
	v_mfma_f32_32x32x16_bf16 v[0:15], v[76:79], v[84:87], v[0:15]
	v_exp_f32_e32 v77, v56
	v_add_f32_e32 v76, v160, v154
	v_exp_f32_e32 v62, v62
	ds_read_b128 v[112:115], v165
	ds_read_b128 v[116:119], v165 offset:4096
	v_cvt_pk_bf16_f32 v56, v151, v152
	s_waitcnt lgkmcnt(7)
	v_mfma_f32_32x32x16_bf16 v[16:31], v[48:51], v[88:91], v[16:31]
	v_exp_f32_e32 v49, v58
	v_exp_f32_e32 v50, v59
	v_add_f32_e32 v48, v77, v157
	v_add_f32_e32 v51, v162, v158
	v_add_f32_e32 v78, v49, v161
	v_add_f32_e32 v76, v50, v76
	s_waitcnt lgkmcnt(6)
	v_mfma_f32_32x32x16_bf16 v[0:15], v[64:67], v[88:91], v[0:15]
	v_exp_f32_e32 v60, v60
	v_add_f32_e32 v151, v62, v78
	v_exp_f32_e32 v61, v61
	v_exp_f32_e32 v63, v63
	v_cvt_pk_bf16_f32 v59, v159, v160
	v_exp_f32_e32 v160, v33
	s_waitcnt lgkmcnt(5)
	v_mfma_f32_32x32x16_bf16 v[16:31], v[68:71], v[92:95], v[16:31]
	v_cvt_pk_bf16_f32 v57, v153, v154
	v_cvt_pk_bf16_f32 v58, v155, v156
	v_add_f32_e32 v48, v60, v48
	v_add_f32_e32 v51, v61, v51
	v_cvt_pk_bf16_f32 v49, v49, v50
	s_waitcnt lgkmcnt(4)
	v_mfma_f32_32x32x16_bf16 v[0:15], v[80:83], v[92:95], v[0:15]
	v_exp_f32_e32 v95, v32
	v_add_f32_e32 v32, v63, v76
	v_add_f32_e32 v163, v160, v51
	v_add_f32_e32 v161, v95, v48
	v_cvt_pk_bf16_f32 v48, v77, v162
	v_cvt_pk_bf16_f32 v51, v62, v63
	s_waitcnt lgkmcnt(3)
	v_mfma_f32_32x32x16_bf16 v[78:93], v[52:55], v[96:99], 0
	v_cvt_pk_bf16_f32 v50, v60, v61
	v_exp_f32_e32 v60, v34
	v_exp_f32_e32 v61, v35
	v_exp_f32_e32 v36, v36
	v_exp_f32_e32 v37, v37
	v_exp_f32_e32 v38, v38
	v_exp_f32_e32 v39, v39
	s_waitcnt lgkmcnt(2)
	v_mfma_f32_32x32x16_bf16 v[62:77], v[72:75], v[96:99], 0
	ds_read_b128 v[52:55], v166
	ds_read_b128 v[152:155], v166 offset:4096
	v_add_f32_e32 v151, v60, v151
	v_add_f32_e32 v162, v61, v32
	s_waitcnt lgkmcnt(3)
	v_mfma_f32_32x32x16_bf16 v[78:93], v[112:115], v[100:103], v[78:93]
	v_add_f32_e32 v112, v36, v161
	v_add_f32_e32 v113, v37, v163
	v_add_f32_e32 v114, v38, v151
	v_exp_f32_e32 v115, v40
	v_add_f32_e32 v40, v39, v162
	ds_read_b128 v[32:35], v167
	ds_read_b128 v[156:159], v167 offset:4096
	s_waitcnt lgkmcnt(4)
	v_mfma_f32_32x32x16_bf16 v[62:77], v[116:119], v[100:103], v[62:77]
	v_exp_f32_e32 v116, v41
	v_add_f32_e32 v41, v115, v112
	s_min_u32 s9, s3, s2
	s_lshl_b32 s9, s9, 6
	v_add_f32_e32 v112, v116, v113
	s_waitcnt lgkmcnt(3)
	v_mfma_f32_32x32x16_bf16 v[78:93], v[52:55], v[104:107], v[78:93]
	v_cvt_pk_bf16_f32 v54, v36, v37
	v_exp_f32_e32 v37, v42
	v_cvt_pk_bf16_f32 v55, v38, v39
	v_exp_f32_e32 v38, v43
	v_exp_f32_e32 v39, v44
	v_exp_f32_e32 v44, v45
	v_exp_f32_e32 v45, v46
	v_exp_f32_e32 v46, v47
	v_cvt_pk_bf16_f32 v52, v95, v160
	v_cvt_pk_bf16_f32 v53, v60, v61
	v_add_f32_e32 v36, v37, v114
	v_add_f32_e32 v43, v38, v40
	v_add_f32_e32 v40, v39, v41
	v_add_f32_e32 v42, v44, v112
	v_add_f32_e32 v41, v45, v36
	v_add_f32_e32 v43, v46, v43
	v_cvt_pk_bf16_f32 v36, v115, v116
	v_cvt_pk_bf16_f32 v37, v37, v38
	v_cvt_pk_bf16_f32 v38, v39, v44
	v_cvt_pk_bf16_f32 v39, v45, v46
	s_waitcnt lgkmcnt(1)
	v_mfma_f32_32x32x16_bf16 v[78:93], v[32:35], v[108:111], v[78:93]
	s_waitcnt lgkmcnt(0)
	s_barrier
	s_mul_i32 s18, s9, 0x1200
	s_mov_b32 s19, 0
	v_lshl_add_u64 v[32:33], v[132:133], 0, s[18:19]
	global_load_dwordx4 v[112:115], v[32:33], off offset:2048
	global_load_dwordx4 v[116:119], v[136:137], off
	v_add_f32_e64 v32, v40, v42
	v_add_f32_e64 v33, v41, v43
	s_waitcnt vmcnt(3)
	ds_write_b128 v142, v[120:123]
	s_waitcnt vmcnt(2)
	ds_write_b128 v142, v[124:127] offset:8192
	v_mfma_f32_32x32x16_bf16 v[62:77], v[152:155], v[104:107], v[62:77]
	v_add_f32_e32 v32, v32, v33
	v_add_f32_e32 v150, v150, v32
	s_waitcnt lgkmcnt(2)
	v_mfma_f32_32x32x16_bf16 v[62:77], v[156:159], v[108:111], v[62:77]
	ds_read_b128 v[32:35], v144 offset:24576
	ds_read_b128 v[40:43], v144 offset:28672
	ds_read_b128 v[44:47], v141 offset:24576
	ds_read_b128 v[120:123], v141 offset:28672
	v_exp_f32_e32 v60, v78
	s_waitcnt lgkmcnt(3)
	v_mfma_f32_32x32x16_bf16 v[16:31], v[32:35], v[56:59], v[16:31]
	v_exp_f32_e32 v61, v79
	v_exp_f32_e32 v95, v80
	v_exp_f32_e32 v81, v81
	ds_read_b128 v[152:155], v140 offset:24576
	ds_read_b128 v[156:159], v140 offset:28672
	s_waitcnt lgkmcnt(4)
	v_mfma_f32_32x32x16_bf16 v[0:15], v[40:43], v[56:59], v[0:15]
	v_exp_f32_e32 v82, v82
	v_exp_f32_e32 v83, v83
	v_add_f32_e32 v78, v82, v60
	v_add_f32_e32 v79, v83, v61
	s_waitcnt lgkmcnt(2)
	v_mfma_f32_32x32x16_bf16 v[0:15], v[120:123], v[48:51], v[0:15]
	ds_read_b128 v[56:59], v139 offset:24576
	ds_read_b128 v[160:163], v139 offset:28672
	ds_read_b128 v[40:43], v164 offset:16384
	ds_read_b128 v[32:35], v164 offset:20480
	v_cvt_pk_bf16_f32 v82, v82, v83
	v_exp_f32_e32 v151, v62
	v_exp_f32_e32 v64, v64
	v_exp_f32_e32 v65, v65
	v_mfma_f32_32x32x16_bf16 v[16:31], v[44:47], v[48:51], v[16:31]
	v_exp_f32_e32 v44, v84
	v_exp_f32_e32 v45, v85
	v_exp_f32_e32 v84, v86
	v_exp_f32_e32 v85, v87
	v_add_f32_e32 v46, v44, v95
	v_add_f32_e32 v47, v45, v81
	v_add_f32_e32 v48, v84, v78
	s_waitcnt lgkmcnt(4)
	v_mfma_f32_32x32x16_bf16 v[0:15], v[156:159], v[52:55], v[0:15]
	v_add_f32_e32 v49, v85, v79
	v_exp_f32_e32 v78, v88
	v_exp_f32_e32 v79, v89
	v_exp_f32_e32 v87, v92
	v_cvt_pk_bf16_f32 v83, v44, v45
	v_exp_f32_e32 v44, v90
	v_mfma_f32_32x32x16_bf16 v[16:31], v[152:155], v[52:55], v[16:31]
	v_exp_f32_e32 v45, v91
	v_exp_f32_e32 v92, v93
	v_add_f32_e32 v46, v78, v46
	v_add_f32_e32 v47, v79, v47
	ds_read_b128 v[124:127], v165 offset:16384
	ds_read_b128 v[120:123], v165 offset:20480
	s_waitcnt lgkmcnt(4)
	v_mfma_f32_32x32x16_bf16 v[0:15], v[160:163], v[36:39], v[0:15]
	v_exp_f32_e32 v160, v63
	v_cvt_pk_bf16_f32 v80, v60, v61
	v_cvt_pk_bf16_f32 v81, v95, v81
	v_add_f32_e32 v48, v44, v48
	v_add_f32_e32 v49, v45, v49
	v_add_f32_e32 v46, v87, v46
	v_add_f32_e32 v47, v92, v47
	v_mfma_f32_32x32x16_bf16 v[16:31], v[56:59], v[36:39], v[16:31]
	v_add_f32_e32 v161, v151, v48
	v_add_f32_e32 v162, v160, v49
	v_cvt_pk_bf16_f32 v84, v84, v85
	v_cvt_pk_bf16_f32 v85, v78, v79
	v_cvt_pk_bf16_f32 v86, v44, v45
	v_add_f32_e32 v78, v64, v46
	v_add_f32_e32 v79, v65, v47
	s_waitcnt lgkmcnt(3)
	v_mfma_f32_32x32x16_bf16 v[48:63], v[40:43], v[96:99], 0
	ds_read_b128 v[88:91], v166 offset:16384
	ds_read_b128 v[152:155], v166 offset:20480
	v_exp_f32_e32 v66, v66
	v_exp_f32_e32 v67, v67
	v_exp_f32_e32 v68, v68
	v_exp_f32_e32 v69, v69
	v_cvt_pk_bf16_f32 v87, v87, v92
	s_waitcnt lgkmcnt(4)
	v_mfma_f32_32x32x16_bf16 v[32:47], v[32:35], v[96:99], 0
	ds_read_b128 v[156:159], v167 offset:16384
	ds_read_b128 v[92:95], v167 offset:20480
	v_add_f32_e32 v161, v66, v161
	v_add_f32_e32 v162, v67, v162
	v_add_f32_e32 v78, v68, v78
	v_add_f32_e32 v79, v69, v79
	s_waitcnt lgkmcnt(5)
	v_mfma_f32_32x32x16_bf16 v[48:63], v[124:127], v[100:103], v[48:63]
	v_exp_f32_e32 v70, v70
	v_exp_f32_e32 v71, v71
	s_add_i32 s9, s3, 2
	s_add_i32 s3, s3, -2
	v_lshl_add_u64 v[136:137], v[136:137], 0, s[22:23]
	s_waitcnt lgkmcnt(4)
	v_mfma_f32_32x32x16_bf16 v[32:47], v[120:123], v[100:103], v[32:47]
	v_add_f32_e32 v120, v70, v161
	v_add_f32_e32 v121, v71, v162
	s_cmp_lt_u32 s3, s2
	s_mov_b32 s3, s9
	s_waitcnt lgkmcnt(3)
	v_mfma_f32_32x32x16_bf16 v[48:63], v[88:91], v[104:107], v[48:63]
	v_cvt_pk_bf16_f32 v91, v68, v69
	v_exp_f32_e32 v68, v72
	v_exp_f32_e32 v69, v73
	v_exp_f32_e32 v72, v74
	v_exp_f32_e32 v73, v75
	v_exp_f32_e32 v74, v76
	v_exp_f32_e32 v75, v77
	s_waitcnt lgkmcnt(2)
	v_mfma_f32_32x32x16_bf16 v[32:47], v[152:155], v[104:107], v[32:47]
	v_cvt_pk_bf16_f32 v88, v151, v160
	v_cvt_pk_bf16_f32 v89, v64, v65
	v_cvt_pk_bf16_f32 v90, v66, v67
	v_add_f32_e32 v65, v68, v78
	v_add_f32_e32 v67, v69, v79
	s_waitcnt lgkmcnt(1)
	v_mfma_f32_32x32x16_bf16 v[48:63], v[156:159], v[108:111], v[48:63]
	v_add_f32_e32 v64, v72, v120
	v_add_f32_e32 v66, v73, v121
	v_add_f32_e32 v65, v74, v65
	v_add_f32_e32 v67, v75, v67
	s_waitcnt lgkmcnt(0)
	v_mfma_f32_32x32x16_bf16 v[32:47], v[92:95], v[108:111], v[32:47]
	v_cvt_pk_bf16_f32 v92, v70, v71
	v_cvt_pk_bf16_f32 v93, v68, v69
	v_cvt_pk_bf16_f32 v94, v72, v73
	v_cvt_pk_bf16_f32 v95, v74, v75
	v_add_f32_e64 v64, v64, v66
	v_add_f32_e64 v65, v65, v67
	s_waitcnt lgkmcnt(0)
	s_barrier
	v_add_f32_e32 v64, v64, v65
	v_add_f32_e32 v150, v150, v64
	s_cbranch_scc1 .LBB0_898
	v_ashrrev_i32_e32 v64, 1, v129
	v_and_or_b32 v132, v64, s88, v148
	v_lshlrev_b32_e32 v176, 4, v138
	s_waitcnt vmcnt(1)
	ds_write_b128 v142, v[112:115] offset:16384
	s_waitcnt vmcnt(0)
	ds_write_b128 v142, v[116:119] offset:24576
	ds_read_b128 v[124:127], v172 offset:32768
	ds_read_b128 v[120:123], v172 offset:40960
	ds_read_b128 v[116:119], v172 offset:49152
	ds_read_b128 v[112:115], v172 offset:57344
	v_ashrrev_i32_e32 v133, 31, v132
	ds_read_b128 v[128:131], v144 offset:8192
	ds_read_b128 v[134:137], v144 offset:12288
	ds_read_b128 v[146:149], v141 offset:8192
	ds_read_b128 v[152:155], v141 offset:12288
	v_exp_f32_e32 v138, v48
	v_exp_f32_e32 v142, v49
	s_waitcnt lgkmcnt(3)
	v_mfma_f32_32x32x16_bf16 v[16:31], v[128:131], v[80:83], v[16:31]
	v_exp_f32_e32 v151, v50
	v_add_f32_e32 v143, 0, v138
	v_add_f32_e32 v145, 0, v142
	v_exp_f32_e32 v156, v51
	ds_read_b128 v[48:51], v140 offset:8192
	ds_read_b128 v[128:131], v140 offset:12288
	v_exp_f32_e32 v52, v52
	s_waitcnt lgkmcnt(4)
	v_mfma_f32_32x32x16_bf16 v[0:15], v[134:137], v[80:83], v[0:15]
	v_exp_f32_e32 v53, v53
	v_exp_f32_e32 v54, v54
	v_exp_f32_e32 v55, v55
	v_add_f32_e32 v157, 0, v151
	v_add_f32_e32 v158, 0, v156
	v_add_f32_e32 v143, v52, v143
	s_waitcnt lgkmcnt(3)
	v_mfma_f32_32x32x16_bf16 v[16:31], v[146:149], v[84:87], v[16:31]
	v_add_f32_e32 v145, v53, v145
	v_add_f32_e32 v146, v54, v157
	ds_read_b128 v[80:83], v139 offset:8192
	ds_read_b128 v[134:137], v139 offset:12288
	v_exp_f32_e32 v56, v56
	v_exp_f32_e32 v57, v57
	v_exp_f32_e32 v58, v58
	s_waitcnt lgkmcnt(4)
	v_mfma_f32_32x32x16_bf16 v[0:15], v[152:155], v[84:87], v[0:15]
	v_add_f32_e32 v84, v55, v158
	v_exp_f32_e32 v59, v59
	v_exp_f32_e32 v60, v60
	v_exp_f32_e32 v32, v32
	v_exp_f32_e32 v33, v33
	v_exp_f32_e32 v34, v34
	s_waitcnt lgkmcnt(3)
	v_mfma_f32_32x32x16_bf16 v[16:31], v[48:51], v[88:91], v[16:31]
	v_cvt_pk_bf16_f32 v51, v54, v55
	v_exp_f32_e32 v54, v61
	v_exp_f32_e32 v55, v62
	v_exp_f32_e32 v61, v63
	v_exp_f32_e32 v35, v35
	v_add_f32_e32 v85, v56, v143
	v_add_f32_e32 v86, v57, v145
	v_add_f32_e32 v87, v58, v146
	v_add_f32_e32 v84, v59, v84
	v_cvt_pk_bf16_f32 v48, v138, v142
	v_cvt_pk_bf16_f32 v49, v151, v156
	v_cvt_pk_bf16_f32 v50, v52, v53
	v_add_f32_e32 v52, v60, v85
	v_add_f32_e32 v53, v54, v86
	v_add_f32_e32 v62, v55, v87
	v_add_f32_e32 v63, v61, v84
	v_exp_f32_e32 v36, v36
	v_exp_f32_e32 v37, v37
	v_exp_f32_e32 v38, v38
	v_exp_f32_e32 v39, v39
	s_waitcnt lgkmcnt(1)
	v_mfma_f32_32x32x16_bf16 v[16:31], v[80:83], v[92:95], v[16:31]
	v_add_f32_e32 v80, v32, v52
	v_add_f32_e32 v81, v33, v53
	v_cvt_pk_bf16_f32 v52, v56, v57
	v_cvt_pk_bf16_f32 v53, v58, v59
	v_cvt_pk_bf16_f32 v54, v60, v54
	v_cvt_pk_bf16_f32 v55, v55, v61
	v_add_f32_e32 v56, v34, v62
	v_add_f32_e32 v57, v35, v63
	v_exp_f32_e32 v40, v40
	v_add_f32_e32 v58, v36, v80
	v_add_f32_e32 v59, v37, v81
	v_add_f32_e32 v56, v38, v56
	v_exp_f32_e32 v41, v41
	v_add_f32_e32 v57, v39, v57
	v_mfma_f32_32x32x16_bf16 v[0:15], v[128:131], v[88:91], v[0:15]
	v_cvt_pk_bf16_f32 v32, v32, v33
	v_cvt_pk_bf16_f32 v33, v34, v35
	v_cvt_pk_bf16_f32 v34, v36, v37
	v_exp_f32_e32 v37, v42
	v_cvt_pk_bf16_f32 v35, v38, v39
	v_exp_f32_e32 v38, v43
	v_exp_f32_e32 v39, v44
	v_exp_f32_e32 v43, v45
	v_exp_f32_e32 v44, v46
	v_exp_f32_e32 v45, v47
	v_add_f32_e32 v58, v40, v58
	v_add_f32_e32 v59, v41, v59
	v_add_f32_e32 v36, v37, v56
	v_add_f32_e32 v42, v38, v57
	v_add_f32_e32 v56, v39, v58
	v_add_f32_e32 v58, v43, v59
	s_waitcnt lgkmcnt(0)
	v_mfma_f32_32x32x16_bf16 v[0:15], v[134:137], v[92:95], v[0:15]
	v_add_f32_e32 v57, v44, v36
	v_add_f32_e32 v59, v45, v42
	v_cvt_pk_bf16_f32 v36, v40, v41
	v_cvt_pk_bf16_f32 v37, v37, v38
	v_cvt_pk_bf16_f32 v38, v39, v43
	v_cvt_pk_bf16_f32 v39, v44, v45
	s_waitcnt lgkmcnt(0)
	s_barrier
	ds_read_b128 v[178:181], v144 offset:24576
	ds_read_b128 v[182:185], v144 offset:28672
	ds_read_b128 v[186:189], v141 offset:24576
	ds_read_b128 v[190:193], v141 offset:28672
	ds_read_b128 v[194:197], v140 offset:24576
	ds_read_b128 v[198:201], v140 offset:28672
	ds_read_b128 v[202:205], v139 offset:24576
	ds_read_b128 v[206:209], v139 offset:28672
	s_waitcnt lgkmcnt(7)
	v_mfma_f32_32x32x16_bf16 v[16:31], v[178:181], v[48:51], v[16:31]
	s_waitcnt lgkmcnt(6)
	v_mfma_f32_32x32x16_bf16 v[0:15], v[182:185], v[48:51], v[0:15]
	s_waitcnt lgkmcnt(5)
	v_mfma_f32_32x32x16_bf16 v[16:31], v[186:189], v[52:55], v[16:31]
	s_waitcnt lgkmcnt(4)
	v_mfma_f32_32x32x16_bf16 v[0:15], v[190:193], v[52:55], v[0:15]
	s_waitcnt lgkmcnt(3)
	v_mfma_f32_32x32x16_bf16 v[16:31], v[194:197], v[32:35], v[16:31]
	s_waitcnt lgkmcnt(2)
	v_mfma_f32_32x32x16_bf16 v[0:15], v[198:201], v[32:35], v[0:15]
	s_waitcnt lgkmcnt(1)
	v_mfma_f32_32x32x16_bf16 v[16:31], v[202:205], v[36:39], v[16:31]
	v_add_f32_e64 v32, v56, v58
	v_add_f32_e64 v33, v57, v59
	v_add_f32_e32 v32, v32, v33
	v_add_f32_e32 v32, v150, v32
	v_mov_b32_e32 v33, v32
	s_nop 1
	v_permlane32_swap_b32_e32 v32, v33
	v_add_f32_e32 v32, v32, v33
	v_div_scale_f32 v33, s[2:3], v32, v32, 1.0
	v_rcp_f32_e32 v34, v33
	s_waitcnt lgkmcnt(0)
	v_mfma_f32_32x32x16_bf16 v[0:15], v[206:209], v[36:39], v[0:15]
	s_waitcnt vmcnt(11)
	v_mov_b32_e32 v40, v127
	s_nop 1
	v_permlane32_swap_b32_e32 v125, v40
	v_fma_f32 v35, -v33, v34, 1.0
	v_fmac_f32_e32 v34, v35, v34
	v_div_scale_f32 v35, vcc, 1.0, v32, 1.0
	v_mul_f32_e32 v36, v35, v34
	v_fma_f32 v37, -v33, v36, v35
	v_fmac_f32_e32 v36, v37, v34
	v_fma_f32 v33, -v33, v36, v35
	v_div_fmas_f32 v33, v33, v34, v36
	v_mov_b32_e32 v35, v126
	v_div_fixup_f32 v34, v33, v32, 1.0
	s_nop 0
	v_permlane32_swap_b32_e32 v124, v35
	v_lshlrev_b32_e32 v38, 16, v124
	v_and_b32_e32 v39, 0xffff0000, v124
	v_mul_f32_e32 v16, v16, v34
	v_mul_f32_e32 v17, v17, v34
	v_mul_f32_e32 v18, v18, v34
	v_mul_f32_e32 v19, v19, v34
	v_mul_f32_e32 v16, v16, v38
	v_mul_f32_e32 v17, v17, v39
	v_lshlrev_b32_e32 v38, 16, v125
	v_and_b32_e32 v39, 0xffff0000, v125
	v_mul_f32_e32 v18, v18, v38
	v_mul_f32_e32 v19, v19, v39
	v_cvt_pk_bf16_f32 v16, v16, v17
	v_cvt_pk_bf16_f32 v17, v18, v19
	v_lshlrev_b32_e32 v18, 16, v35
	v_and_b32_e32 v19, 0xffff0000, v35
	v_mul_f32_e32 v20, v20, v34
	v_mul_f32_e32 v21, v21, v34
	v_mul_f32_e32 v22, v22, v34
	v_mul_f32_e32 v23, v23, v34
	v_mul_f32_e32 v18, v20, v18
	v_mul_f32_e32 v19, v21, v19
	v_lshlrev_b32_e32 v20, 16, v40
	v_and_b32_e32 v21, 0xffff0000, v40
	v_lshlrev_b64 v[32:33], 11, v[132:133]
	v_mul_f32_e32 v20, v22, v20
	v_mul_f32_e32 v21, v23, v21
	v_lshl_add_u64 v[32:33], s[6:7], 0, v[32:33]
	v_cvt_pk_bf16_f32 v18, v18, v19
	v_cvt_pk_bf16_f32 v19, v20, v21
	s_waitcnt vmcnt(10)
	v_mov_b32_e32 v22, v122
	v_lshl_add_u64 v[36:37], v[32:33], 0, v[176:177]
	v_permlane32_swap_b32_e32 v16, v18
	v_permlane32_swap_b32_e32 v17, v19
	v_permlane32_swap_b32_e32 v120, v22
	v_mov_b32_e32 v23, v123
	global_store_dwordx4 v[36:37], v[16:19], off offset:512
	s_nop 0
	v_permlane32_swap_b32_e32 v121, v23
	v_lshlrev_b32_e32 v16, 16, v120
	v_and_b32_e32 v17, 0xffff0000, v120
	v_mul_f32_e32 v18, v24, v34
	v_mul_f32_e32 v19, v25, v34
	v_mul_f32_e32 v20, v26, v34
	v_mul_f32_e32 v21, v27, v34
	v_mul_f32_e32 v16, v18, v16
	v_mul_f32_e32 v17, v19, v17
	v_lshlrev_b32_e32 v18, 16, v121
	v_and_b32_e32 v19, 0xffff0000, v121
	v_mul_f32_e32 v18, v20, v18
	v_mul_f32_e32 v19, v21, v19
	v_cvt_pk_bf16_f32 v16, v16, v17
	v_cvt_pk_bf16_f32 v17, v18, v19
	v_lshlrev_b32_e32 v18, 16, v22
	v_and_b32_e32 v19, 0xffff0000, v22
	v_mul_f32_e32 v20, v28, v34
	v_mul_f32_e32 v21, v29, v34
	v_mul_f32_e32 v0, v0, v34
	v_mul_f32_e32 v1, v1, v34
	v_mul_f32_e32 v18, v20, v18
	v_mul_f32_e32 v19, v21, v19
	v_lshlrev_b32_e32 v20, 16, v23
	v_and_b32_e32 v21, 0xffff0000, v23
	v_mul_f32_e32 v22, v30, v34
	v_mul_f32_e32 v23, v31, v34
	v_cvt_pk_bf16_f32 v18, v18, v19
	v_mul_f32_e32 v20, v22, v20
	v_mul_f32_e32 v21, v23, v21
	s_nop 0
	v_permlane32_swap_b32_e32 v16, v18
	v_cvt_pk_bf16_f32 v19, v20, v21
	s_nop 1
	v_permlane32_swap_b32_e32 v17, v19
	global_store_dwordx4 v[36:37], v[16:19], off offset:544
	v_mul_f32_e32 v2, v2, v34
	v_mul_f32_e32 v3, v3, v34
	v_mul_f32_e32 v4, v4, v34
	v_mul_f32_e32 v5, v5, v34
	s_waitcnt vmcnt(11)
	v_mov_b32_e32 v18, v118
	s_nop 1
	v_permlane32_swap_b32_e32 v116, v18
	v_mov_b32_e32 v19, v119
	s_nop 1
	v_permlane32_swap_b32_e32 v117, v19
	v_lshlrev_b32_e32 v16, 16, v116
	v_and_b32_e32 v17, 0xffff0000, v116
	v_mul_f32_e32 v0, v0, v16
	v_mul_f32_e32 v1, v1, v17
	v_lshlrev_b32_e32 v16, 16, v117
	v_and_b32_e32 v17, 0xffff0000, v117
	v_mul_f32_e32 v2, v2, v16
	v_mul_f32_e32 v3, v3, v17
	v_cvt_pk_bf16_f32 v0, v0, v1
	v_cvt_pk_bf16_f32 v1, v2, v3
	v_lshlrev_b32_e32 v2, 16, v18
	v_and_b32_e32 v3, 0xffff0000, v18
	v_mul_f32_e32 v2, v4, v2
	v_mul_f32_e32 v3, v5, v3
	v_lshlrev_b32_e32 v4, 16, v19
	v_and_b32_e32 v5, 0xffff0000, v19
	v_mul_f32_e32 v6, v6, v34
	v_mul_f32_e32 v7, v7, v34
	v_cvt_pk_bf16_f32 v2, v2, v3
	v_mul_f32_e32 v4, v6, v4
	v_mul_f32_e32 v5, v7, v5
	s_waitcnt vmcnt(10)
	v_mov_b32_e32 v6, v114
	v_cvt_pk_bf16_f32 v3, v4, v5
	v_permlane32_swap_b32_e32 v0, v2
	s_nop 0
	v_permlane32_swap_b32_e32 v1, v3
	v_permlane32_swap_b32_e32 v112, v6
	v_mov_b32_e32 v7, v115
	global_store_dwordx4 v[36:37], v[0:3], off offset:576
	s_nop 0
	v_permlane32_swap_b32_e32 v113, v7
	v_lshlrev_b32_e32 v0, 16, v112
	v_and_b32_e32 v1, 0xffff0000, v112
	v_mul_f32_e32 v2, v8, v34
	v_mul_f32_e32 v3, v9, v34
	v_mul_f32_e32 v4, v10, v34
	v_mul_f32_e32 v5, v11, v34
	v_mul_f32_e32 v0, v2, v0
	v_mul_f32_e32 v1, v3, v1
	v_lshlrev_b32_e32 v2, 16, v113
	v_and_b32_e32 v3, 0xffff0000, v113
	v_mul_f32_e32 v2, v4, v2
	v_mul_f32_e32 v3, v5, v3
	v_cvt_pk_bf16_f32 v0, v0, v1
	v_cvt_pk_bf16_f32 v1, v2, v3
	v_lshlrev_b32_e32 v2, 16, v6
	v_and_b32_e32 v3, 0xffff0000, v6
	v_mul_f32_e32 v4, v12, v34
	v_mul_f32_e32 v5, v13, v34
	s_mov_b64 s[2:3], 0x200
	v_mul_f32_e32 v2, v4, v2
	v_mul_f32_e32 v3, v5, v3
	v_lshlrev_b32_e32 v4, 16, v7
	v_and_b32_e32 v5, 0xffff0000, v7
	v_mul_f32_e32 v6, v14, v34
	v_mul_f32_e32 v7, v15, v34
	v_cvt_pk_bf16_f32 v2, v2, v3
	v_mul_f32_e32 v4, v6, v4
	v_mul_f32_e32 v5, v7, v5
	v_lshl_add_u64 v[32:33], v[36:37], 0, s[2:3]
	v_cvt_pk_bf16_f32 v3, v4, v5
	v_permlane32_swap_b32_e32 v0, v2
	s_nop 0
	v_permlane32_swap_b32_e32 v1, v3
	s_branch .LBB0_876
